# GEMM k-loops: first k-iteration waits vmcnt(N) of the tile prologue (epilogue stores get one more k-tile to drain)
# speedup vs baseline: 1.0020x; 1.0020x over previous
; DEV int tid_l() { int t = threadIdx.x; asm volatile("" : "+v"(t)); return t; }
; DEV int stage_next(int s) { return (s == 2 * GS_STAGE) ? 0 : s + GS_STAGE; }
; DEV void gk_issue2(const GTile& t, int s0) {
;   const int tid = tid_l(), lane = tid & 63, wid = __builtin_amdgcn_readfirstlane(tid >> 6);
;   GK_SRC(t)
;   asm volatile("" ::: "memory");
;   GK_DMA(s0, 0);
;   GK_DMA(stage_next(s0), 1);
;   asm volatile("" ::: "memory");
; }
; template <int WAIT0>
; DEV void gk_main(f32x16 (&acc)[2][2], const GTile& t, int s0) {
;   const int tid = tid_l(), lane = tid & 63, wid = __builtin_amdgcn_readfirstlane(tid >> 6), wm = wid & 1, wn = wid >> 1, l32 = lane & 31, hi = lane >> 5;
;   GK_SRC(t)
;   const int sw = (l32 >> 1) & 7;
;   int xk[4], wk[4];
; #pragma unroll
;   for (int ks = 0; ks < 4; ++ks) { const int ko = ((2 * ks + hi) ^ sw) << 4; xk[ks] = GS_A + (64 * wm + l32) * 128 + ko; wk[ks] = GS_B + (64 * wn + l32) * 128 + ko; }
;   const int nk = t.K >> 6;
;     ...
;   vm_wait_bar<WAIT0>();
;   int stc = s0, std_ = stage_next(stage_next(s0));
; #pragma nounroll
;   for (int kt = 0; kt < nk - 2; ++kt) {
;     GK_DMA(std_, kt + 2);
;     GK_COMPUTE(stc);
;     vm_wait_bar<6>();
;     stc = stage_next(stc); std_ = stage_next(std_);
;   }
.LBB0_72:
	s_cmp_lg_u32 s17, 0
	s_cbranch_scc0 .LBB0_85
	s_bitcmp0_b32 s17, 0
	s_mov_b64 s[6:7], -1
	s_cbranch_scc1 .LBB0_77
	v_mov_b32_e32 v1, v176
	s_waitcnt vmcnt(14) lgkmcnt(0)
	s_barrier
	v_readfirstlane_b32 s6, v1
	s_ashr_i32 s7, s6, 6
	v_and_b32_e32 v2, 31, v1
	v_bfe_u32 v0, v1, 3, 3
	v_lshl_or_b32 v0, s7, 3, v0
	v_and_or_b32 v5, s6, 64, v2
	s_lshr_b32 s6, s6, 1
	v_lshrrev_b32_e32 v3, 1, v0
	s_and_b32 s6, s6, 0x1ffffc0
	v_xor_b32_e32 v3, v3, v1
	v_or_b32_e32 v2, s6, v2
	s_lshl_b32 s6, s7, 10
	v_lshlrev_b32_e32 v3, 4, v3
	s_add_i32 s19, s6, 0
	s_add_i32 s6, s16, 0xc000
	v_and_b32_e32 v6, 0x70, v3
	v_bfe_u32 v3, v1, 5, 1
	v_lshrrev_b32_e32 v4, 1, v1
	v_bfe_u32 v1, v1, 1, 3
	s_cmp_lg_u32 s16, 0x18000
	v_bitop3_b32 v7, v3, v1, 2 bitop3:0x36
	v_bitop3_b32 v8, v3, v1, 4 bitop3:0x36
	v_bitop3_b32 v1, v3, v1, 6 bitop3:0x36
	s_cselect_b32 s9, s6, 0
	v_lshlrev_b32_e32 v5, 7, v5
	v_lshlrev_b32_e32 v2, 7, v2
	v_bitop3_b32 v4, v3, v4, 7 bitop3:0x78
	v_lshlrev_b32_e32 v1, 4, v1
	s_add_i32 s6, s9, 0xc000
	v_lshlrev_b32_e32 v4, 4, v4
	v_lshlrev_b32_e32 v7, 4, v7
	v_lshlrev_b32_e32 v8, 4, v8
	v_or_b32_e32 v76, v1, v5
	s_cmp_lg_u32 s9, 0x18000
	v_or_b32_e32 v77, v2, v1
	v_ashrrev_i32_e32 v1, 31, v0
	s_cselect_b32 s20, s6, 0
	v_or_b32_e32 v83, v2, v4
	v_or_b32_e32 v81, v2, v7
	v_or_b32_e32 v79, v2, v8
	v_lshlrev_b64 v[2:3], 11, v[0:1]
	s_add_u32 s6, s14, 0x100
	v_or_b32_e32 v2, v2, v6
	s_addc_u32 s7, s15, 0
	v_or_b32_e32 v82, v4, v5
	v_lshl_add_u64 v[64:65], s[12:13], 0, v[2:3]
	v_add_u32_e32 v4, 64, v0
	v_lshl_add_u64 v[68:69], s[6:7], 0, v[2:3]
	v_add_u32_e32 v2, 0x80, v0
	v_add_u32_e32 v0, 0xc0, v0
	v_ashrrev_i32_e32 v1, 31, v0
	v_or_b32_e32 v80, v7, v5
	v_or_b32_e32 v78, v8, v5
	v_ashrrev_i32_e32 v5, 31, v4
	v_ashrrev_i32_e32 v3, 31, v2
	v_lshlrev_b64 v[0:1], 11, v[0:1]
	v_lshlrev_b64 v[4:5], 11, v[4:5]
	v_lshlrev_b64 v[2:3], 11, v[2:3]
	v_or_b32_e32 v0, v0, v6
	v_or_b32_e32 v4, v4, v6
	v_or_b32_e32 v2, v2, v6
	v_lshl_add_u64 v[74:75], s[6:7], 0, v[0:1]
	v_mov_b32_e32 v0, 0
	v_lshl_add_u64 v[66:67], s[12:13], 0, v[4:5]
	v_lshl_add_u64 v[70:71], s[6:7], 0, v[4:5]
	v_lshl_add_u64 v[72:73], s[6:7], 0, v[2:3]
	s_mov_b64 s[6:7], 0
	s_mov_b32 s18, s16
	v_mov_b32_e32 v1, v0
	v_mov_b32_e32 v2, v0
	v_mov_b32_e32 v3, v0
	v_mov_b32_e32 v4, v0
	v_mov_b32_e32 v5, v0
	v_mov_b32_e32 v6, v0
	v_mov_b32_e32 v7, v0
	v_mov_b32_e32 v8, v0
	v_mov_b32_e32 v9, v0
	v_mov_b32_e32 v10, v0
	v_mov_b32_e32 v11, v0
	v_mov_b32_e32 v12, v0
	v_mov_b32_e32 v13, v0
	v_mov_b32_e32 v14, v0
	v_mov_b32_e32 v15, v0
	v_mov_b32_e32 v32, v0
	v_mov_b32_e32 v33, v0
	v_mov_b32_e32 v34, v0
	v_mov_b32_e32 v35, v0
	v_mov_b32_e32 v36, v0
	v_mov_b32_e32 v37, v0
	v_mov_b32_e32 v38, v0
	v_mov_b32_e32 v39, v0
	v_mov_b32_e32 v40, v0
	v_mov_b32_e32 v41, v0
	v_mov_b32_e32 v42, v0
	v_mov_b32_e32 v43, v0
	v_mov_b32_e32 v44, v0
	v_mov_b32_e32 v45, v0
	v_mov_b32_e32 v46, v0
	v_mov_b32_e32 v47, v0
	v_mov_b32_e32 v16, v0
	v_mov_b32_e32 v17, v0
	v_mov_b32_e32 v18, v0
	v_mov_b32_e32 v19, v0
	v_mov_b32_e32 v20, v0
	v_mov_b32_e32 v21, v0
	v_mov_b32_e32 v22, v0
	v_mov_b32_e32 v23, v0
	v_mov_b32_e32 v24, v0
	v_mov_b32_e32 v25, v0
	v_mov_b32_e32 v26, v0
	v_mov_b32_e32 v27, v0
	v_mov_b32_e32 v28, v0
	v_mov_b32_e32 v29, v0
	v_mov_b32_e32 v30, v0
	v_mov_b32_e32 v31, v0
	v_mov_b32_e32 v48, v0
	v_mov_b32_e32 v49, v0
	v_mov_b32_e32 v50, v0
	v_mov_b32_e32 v51, v0
	v_mov_b32_e32 v52, v0
	v_mov_b32_e32 v53, v0
	v_mov_b32_e32 v54, v0
	v_mov_b32_e32 v55, v0
	v_mov_b32_e32 v56, v0
	v_mov_b32_e32 v57, v0
	v_mov_b32_e32 v58, v0
	v_mov_b32_e32 v59, v0
	v_mov_b32_e32 v60, v0
	v_mov_b32_e32 v61, v0
	v_mov_b32_e32 v62, v0
	v_mov_b32_e32 v63, v0
	s_add_i32 s99, s18, 0
	v_add_u32_e32 v100, s99, v82
	v_add_u32_e32 v101, s99, v83
	ds_read_b128 v[84:87], v101 offset:16384
	ds_read_b128 v[88:91], v100
	ds_read_b128 v[92:95], v100 offset:4096
	s_mov_b64 vcc, -1
	s_branch .Lfws_75
.Lfw_75:
	s_waitcnt vmcnt(14) lgkmcnt(0)
	s_barrier
	s_mov_b64 vcc, 0
	s_branch .Lfwb_75
.Lfws_75:
.LBB0_75:
	s_add_i32 s21, s19, s20
	s_mov_b32 s98, s21
	s_mov_b64 s[100:101], s[6:7]
	s_waitcnt lgkmcnt(0)
	v_add_u32_e32 v100, s99, v80
	s_add_i32 s21, s18, 0xc000
	s_cmp_lg_u32 s18, 0x18000
	s_cselect_b32 s18, s21, 0
	s_add_i32 s21, s20, 0xc000
	s_cmp_lg_u32 s20, 0x18000
	s_cselect_b32 s20, s21, 0
	ds_read_b128 v[236:239], v101 offset:20480
	v_mfma_f32_32x32x16_bf16 v[48:63], v[84:87], v[88:91], v[48:63]
	v_mfma_f32_32x32x16_bf16 v[16:31], v[84:87], v[92:95], v[16:31]
	s_mov_b32 m0, s98
	v_lshl_add_u64 v[254:255], v[64:65], 0, s[100:101]
	global_load_lds_dwordx4 v[254:255], off
	v_add_u32_e32 v101, s99, v81
	s_add_u32 s6, s6, 0x80
	s_addc_u32 s7, s7, 0
	s_waitcnt lgkmcnt(0)
	ds_read_b128 v[84:87], v101 offset:16384
	ds_read_b128 v[240:243], v100
	ds_read_b128 v[244:247], v100 offset:4096
	v_mfma_f32_32x32x16_bf16 v[32:47], v[236:239], v[88:91], v[32:47]
	v_mfma_f32_32x32x16_bf16 v[0:15], v[236:239], v[92:95], v[0:15]
	s_add_i32 m0, s98, 0x2000
	v_lshl_add_u64 v[254:255], v[66:67], 0, s[100:101]
	global_load_lds_dwordx4 v[254:255], off
	v_add_u32_e32 v100, s99, v78
	s_waitcnt lgkmcnt(0)
	ds_read_b128 v[236:239], v101 offset:20480
	v_mfma_f32_32x32x16_bf16 v[48:63], v[84:87], v[240:243], v[48:63]
	v_mfma_f32_32x32x16_bf16 v[16:31], v[84:87], v[244:247], v[16:31]
	s_add_i32 m0, s98, 0x4000
	v_lshl_add_u64 v[254:255], v[68:69], 0, s[100:101]
	global_load_lds_dwordx4 v[254:255], off
	v_add_u32_e32 v101, s99, v79
	s_waitcnt lgkmcnt(0)
	ds_read_b128 v[84:87], v101 offset:16384
	ds_read_b128 v[88:91], v100
	ds_read_b128 v[92:95], v100 offset:4096
	v_mfma_f32_32x32x16_bf16 v[32:47], v[236:239], v[240:243], v[32:47]
	v_mfma_f32_32x32x16_bf16 v[0:15], v[236:239], v[244:247], v[0:15]
	s_add_i32 m0, s98, 0x6000
	v_lshl_add_u64 v[254:255], v[70:71], 0, s[100:101]
	global_load_lds_dwordx4 v[254:255], off
	v_add_u32_e32 v100, s99, v76
	s_waitcnt lgkmcnt(0)
	ds_read_b128 v[236:239], v101 offset:20480
	v_mfma_f32_32x32x16_bf16 v[48:63], v[84:87], v[88:91], v[48:63]
	v_mfma_f32_32x32x16_bf16 v[16:31], v[84:87], v[92:95], v[16:31]
	s_add_i32 m0, s98, 0x8000
	v_lshl_add_u64 v[254:255], v[72:73], 0, s[100:101]
	global_load_lds_dwordx4 v[254:255], off
	v_add_u32_e32 v101, s99, v77
	s_waitcnt lgkmcnt(0)
	ds_read_b128 v[84:87], v101 offset:16384
	ds_read_b128 v[240:243], v100
	ds_read_b128 v[244:247], v100 offset:4096
	v_mfma_f32_32x32x16_bf16 v[32:47], v[236:239], v[88:91], v[32:47]
	v_mfma_f32_32x32x16_bf16 v[0:15], v[236:239], v[92:95], v[0:15]
	s_add_i32 m0, s98, 0xa000
	v_lshl_add_u64 v[254:255], v[74:75], 0, s[100:101]
	global_load_lds_dwordx4 v[254:255], off
	s_waitcnt lgkmcnt(0)
	ds_read_b128 v[236:239], v101 offset:20480
	v_mfma_f32_32x32x16_bf16 v[48:63], v[84:87], v[240:243], v[48:63]
	v_mfma_f32_32x32x16_bf16 v[16:31], v[84:87], v[244:247], v[16:31]
	s_cbranch_vccnz .Lfw_75
	s_waitcnt vmcnt(6) lgkmcnt(0)
	s_barrier
; DEV int stage_next(int s) { return (s == 2 * GS_STAGE) ? 0 : s + GS_STAGE; }
; template <int WAIT0>
; DEV void gk_main(f32x16 (&acc)[2][2], const GTile& t, int s0) {
;     ...
;   for (int kt = 0; kt < nk - 2; ++kt) {
;     GK_DMA(std_, kt + 2);
;     GK_COMPUTE(stc);
;     vm_wait_bar<6>();
;     stc = stage_next(stc); std_ = stage_next(std_);
;   }
;   GK_COMPUTE(stc);
;   vm_wait_bar<0>();
;   stc = stage_next(stc);
;   GK_COMPUTE(stc);
;   vm_wait_bar<0>();
.Lfwb_75:
	s_waitcnt lgkmcnt(0)
	s_add_i32 s99, s18, 0
	v_add_u32_e32 v100, s99, v82
	v_add_u32_e32 v101, s99, v83
	ds_read_b128 v[84:87], v101 offset:16384
	ds_read_b128 v[88:91], v100
	ds_read_b128 v[92:95], v100 offset:4096
	v_mfma_f32_32x32x16_bf16 v[32:47], v[236:239], v[240:243], v[32:47]
	v_mfma_f32_32x32x16_bf16 v[0:15], v[236:239], v[244:247], v[0:15]
	s_cmpk_lg_i32 s6, 0x700
	s_cbranch_scc1 .LBB0_75
	s_waitcnt lgkmcnt(0)
	s_add_i32 s6, s18, 0
	v_add_u32_e32 v84, s6, v83
	ds_read_b128 v[64:67], v84 offset:16384
	v_add_u32_e32 v72, s6, v82
	ds_read_b128 v[68:71], v72
	ds_read_b128 v[72:75], v72 offset:4096
	s_waitcnt lgkmcnt(0)
	v_mfma_f32_32x32x16_bf16 v[48:63], v[64:67], v[68:71], v[48:63]
	v_mfma_f32_32x32x16_bf16 v[16:31], v[64:67], v[72:75], v[16:31]
	ds_read_b128 v[64:67], v84 offset:20480
	v_add_u32_e32 v84, s6, v81
	s_waitcnt lgkmcnt(0)
	v_mfma_f32_32x32x16_bf16 v[32:47], v[64:67], v[68:71], v[32:47]
	v_mfma_f32_32x32x16_bf16 v[0:15], v[64:67], v[72:75], v[0:15]
	ds_read_b128 v[64:67], v84 offset:16384
	v_add_u32_e32 v72, s6, v80
	ds_read_b128 v[68:71], v72
	ds_read_b128 v[72:75], v72 offset:4096
	s_waitcnt lgkmcnt(0)
	v_mfma_f32_32x32x16_bf16 v[48:63], v[64:67], v[68:71], v[48:63]
	v_mfma_f32_32x32x16_bf16 v[16:31], v[64:67], v[72:75], v[16:31]
	ds_read_b128 v[64:67], v84 offset:20480
	v_add_u32_e32 v84, s6, v79
	s_waitcnt lgkmcnt(0)
	v_mfma_f32_32x32x16_bf16 v[32:47], v[64:67], v[68:71], v[32:47]
	v_mfma_f32_32x32x16_bf16 v[0:15], v[64:67], v[72:75], v[0:15]
	ds_read_b128 v[64:67], v84 offset:16384
	v_add_u32_e32 v72, s6, v78
	ds_read_b128 v[68:71], v72
	ds_read_b128 v[72:75], v72 offset:4096
	s_waitcnt lgkmcnt(0)
	v_mfma_f32_32x32x16_bf16 v[48:63], v[64:67], v[68:71], v[48:63]
	v_mfma_f32_32x32x16_bf16 v[16:31], v[64:67], v[72:75], v[16:31]
	ds_read_b128 v[64:67], v84 offset:20480
	v_add_u32_e32 v84, s6, v77
	s_waitcnt lgkmcnt(0)
	v_mfma_f32_32x32x16_bf16 v[32:47], v[64:67], v[68:71], v[32:47]
	v_mfma_f32_32x32x16_bf16 v[0:15], v[64:67], v[72:75], v[0:15]
	ds_read_b128 v[64:67], v84 offset:16384
	v_add_u32_e32 v72, s6, v76
	ds_read_b128 v[68:71], v72
	ds_read_b128 v[72:75], v72 offset:4096
	s_add_i32 s6, s18, 0xc000
	s_cmp_lg_u32 s18, 0x18000
	s_cselect_b32 s6, s6, 0
	s_waitcnt lgkmcnt(0)
	v_mfma_f32_32x32x16_bf16 v[48:63], v[64:67], v[68:71], v[48:63]
	s_add_i32 s6, s6, 0
	v_add_u32_e32 v83, s6, v83
	v_add_u32_e32 v81, s6, v81
	v_add_u32_e32 v79, s6, v79
	v_add_u32_e32 v77, s6, v77
	v_mfma_f32_32x32x16_bf16 v[16:31], v[64:67], v[72:75], v[16:31]
	ds_read_b128 v[64:67], v84 offset:20480
	s_waitcnt vmcnt(0) lgkmcnt(0)
	s_barrier
	s_waitcnt lgkmcnt(0)
	v_mfma_f32_32x32x16_bf16 v[32:47], v[64:67], v[68:71], v[32:47]
	v_mfma_f32_32x32x16_bf16 v[0:15], v[64:67], v[72:75], v[0:15]
	ds_read_b128 v[64:67], v83 offset:16384
	v_add_u32_e32 v72, s6, v82
	ds_read_b128 v[68:71], v72
	ds_read_b128 v[72:75], v72 offset:4096
	s_waitcnt lgkmcnt(0)
	v_mfma_f32_32x32x16_bf16 v[48:63], v[64:67], v[68:71], v[48:63]
	v_mfma_f32_32x32x16_bf16 v[16:31], v[64:67], v[72:75], v[16:31]
	ds_read_b128 v[64:67], v83 offset:20480
	s_waitcnt lgkmcnt(0)
	v_mfma_f32_32x32x16_bf16 v[32:47], v[64:67], v[68:71], v[32:47]
	v_mfma_f32_32x32x16_bf16 v[0:15], v[64:67], v[72:75], v[0:15]
	ds_read_b128 v[64:67], v81 offset:16384
	v_add_u32_e32 v72, s6, v80
	ds_read_b128 v[68:71], v72
	ds_read_b128 v[72:75], v72 offset:4096
	s_waitcnt lgkmcnt(0)
	v_mfma_f32_32x32x16_bf16 v[48:63], v[64:67], v[68:71], v[48:63]
	v_mfma_f32_32x32x16_bf16 v[16:31], v[64:67], v[72:75], v[16:31]
	ds_read_b128 v[64:67], v81 offset:20480
	s_waitcnt lgkmcnt(0)
	v_mfma_f32_32x32x16_bf16 v[32:47], v[64:67], v[68:71], v[32:47]
	v_mfma_f32_32x32x16_bf16 v[0:15], v[64:67], v[72:75], v[0:15]
	ds_read_b128 v[64:67], v79 offset:16384
	v_add_u32_e32 v72, s6, v78
	ds_read_b128 v[68:71], v72
	ds_read_b128 v[72:75], v72 offset:4096
	s_waitcnt lgkmcnt(0)
	v_mfma_f32_32x32x16_bf16 v[48:63], v[64:67], v[68:71], v[48:63]
	v_mfma_f32_32x32x16_bf16 v[16:31], v[64:67], v[72:75], v[16:31]
	ds_read_b128 v[64:67], v79 offset:20480
	s_waitcnt lgkmcnt(0)
	v_mfma_f32_32x32x16_bf16 v[32:47], v[64:67], v[68:71], v[32:47]
	v_mfma_f32_32x32x16_bf16 v[0:15], v[64:67], v[72:75], v[0:15]
	ds_read_b128 v[64:67], v77 offset:16384
	v_add_u32_e32 v72, s6, v76
	ds_read_b128 v[68:71], v72
	ds_read_b128 v[72:75], v72 offset:4096
	s_mov_b64 s[6:7], 0
	s_waitcnt lgkmcnt(0)
	v_mfma_f32_32x32x16_bf16 v[48:63], v[64:67], v[68:71], v[48:63]
	v_mfma_f32_32x32x16_bf16 v[16:31], v[64:67], v[72:75], v[16:31]
	ds_read_b128 v[64:67], v77 offset:20480
	s_waitcnt vmcnt(0) lgkmcnt(0)
	s_barrier
	s_waitcnt lgkmcnt(0)
	v_mfma_f32_32x32x16_bf16 v[32:47], v[64:67], v[68:71], v[32:47]
	v_mfma_f32_32x32x16_bf16 v[0:15], v[64:67], v[72:75], v[0:15]
; DEV int tid_l() { int t = threadIdx.x; asm volatile("" : "+v"(t)); return t; }
; DEV int stage_next(int s) { return (s == 2 * GS_STAGE) ? 0 : s + GS_STAGE; }
; DEV void gk_issue2(const GTile& t, int s0) {
;   const int tid = tid_l(), lane = tid & 63, wid = __builtin_amdgcn_readfirstlane(tid >> 6);
;   GK_SRC(t)
;   asm volatile("" ::: "memory");
;   GK_DMA(s0, 0);
;   GK_DMA(stage_next(s0), 1);
;   asm volatile("" ::: "memory");
; }
; template <int WAIT0>
; DEV void gk_main(f32x16 (&acc)[2][2], const GTile& t, int s0) {
;   const int tid = tid_l(), lane = tid & 63, wid = __builtin_amdgcn_readfirstlane(tid >> 6), wm = wid & 1, wn = wid >> 1, l32 = lane & 31, hi = lane >> 5;
;   GK_SRC(t)
;   const int sw = (l32 >> 1) & 7;
;   int xk[4], wk[4];
; #pragma unroll
;   for (int ks = 0; ks < 4; ++ks) { const int ko = ((2 * ks + hi) ^ sw) << 4; xk[ks] = GS_A + (64 * wm + l32) * 128 + ko; wk[ks] = GS_B + (64 * wn + l32) * 128 + ko; }
;   const int nk = t.K >> 6;
;     ...
;   vm_wait_bar<WAIT0>();
;   int stc = s0, std_ = stage_next(stage_next(s0));
.LBB0_77:
	s_and_b64 vcc, exec, s[6:7]
	s_cbranch_vccz .LBB0_81
	s_nop 9
	v_mov_b32_e32 v1, v176
	s_waitcnt vmcnt(14) lgkmcnt(0)
	s_barrier
	v_readfirstlane_b32 s6, v1
	s_ashr_i32 s7, s6, 6
	v_and_b32_e32 v2, 31, v1
	v_bfe_u32 v0, v1, 3, 3
	v_lshl_or_b32 v0, s7, 3, v0
	v_and_or_b32 v5, s6, 64, v2
	s_lshr_b32 s6, s6, 1
	v_lshrrev_b32_e32 v3, 1, v0
	s_and_b32 s6, s6, 0x1ffffc0
	v_xor_b32_e32 v3, v3, v1
	v_or_b32_e32 v2, s6, v2
	s_lshl_b32 s6, s7, 10
	v_lshlrev_b32_e32 v3, 4, v3
	s_add_i32 s19, s6, 0
	s_add_i32 s6, s16, 0xc000
	v_and_b32_e32 v6, 0x70, v3
	v_bfe_u32 v3, v1, 5, 1
	v_lshrrev_b32_e32 v4, 1, v1
	v_bfe_u32 v1, v1, 1, 3
	s_cmp_lg_u32 s16, 0x18000
	v_bitop3_b32 v7, v3, v1, 2 bitop3:0x36
	v_bitop3_b32 v8, v3, v1, 4 bitop3:0x36
	v_bitop3_b32 v1, v3, v1, 6 bitop3:0x36
	s_cselect_b32 s9, s6, 0
	v_lshlrev_b32_e32 v5, 7, v5
	v_lshlrev_b32_e32 v2, 7, v2
	v_bitop3_b32 v4, v3, v4, 7 bitop3:0x78
	v_lshlrev_b32_e32 v1, 4, v1
	s_add_i32 s6, s9, 0xc000
	v_lshlrev_b32_e32 v4, 4, v4
	v_lshlrev_b32_e32 v7, 4, v7
	v_lshlrev_b32_e32 v8, 4, v8
	v_or_b32_e32 v76, v1, v5
	s_cmp_lg_u32 s9, 0x18000
	v_or_b32_e32 v77, v2, v1
	v_ashrrev_i32_e32 v1, 31, v0
	s_cselect_b32 s20, s6, 0
	v_or_b32_e32 v83, v2, v4
	v_or_b32_e32 v81, v2, v7
	v_or_b32_e32 v79, v2, v8
	v_lshlrev_b64 v[2:3], 11, v[0:1]
	s_add_u32 s6, s14, 0x100
	v_or_b32_e32 v2, v2, v6
	s_addc_u32 s7, s15, 0
	v_or_b32_e32 v82, v4, v5
	v_lshl_add_u64 v[64:65], s[12:13], 0, v[2:3]
	v_add_u32_e32 v4, 64, v0
	v_lshl_add_u64 v[68:69], s[6:7], 0, v[2:3]
	v_add_u32_e32 v2, 0x80, v0
	v_add_u32_e32 v0, 0xc0, v0
	v_ashrrev_i32_e32 v1, 31, v0
	v_or_b32_e32 v80, v7, v5
	v_or_b32_e32 v78, v8, v5
	v_ashrrev_i32_e32 v5, 31, v4
	v_ashrrev_i32_e32 v3, 31, v2
	v_lshlrev_b64 v[0:1], 11, v[0:1]
	v_lshlrev_b64 v[4:5], 11, v[4:5]
	v_lshlrev_b64 v[2:3], 11, v[2:3]
	v_or_b32_e32 v0, v0, v6
	v_or_b32_e32 v4, v4, v6
	v_or_b32_e32 v2, v2, v6
	v_lshl_add_u64 v[74:75], s[6:7], 0, v[0:1]
	v_mov_b32_e32 v0, 0
	v_lshl_add_u64 v[66:67], s[12:13], 0, v[4:5]
	v_lshl_add_u64 v[70:71], s[6:7], 0, v[4:5]
	v_lshl_add_u64 v[72:73], s[6:7], 0, v[2:3]
	s_mov_b64 s[6:7], 0
	s_mov_b32 s18, s16
	v_mov_b32_e32 v1, v0
	v_mov_b32_e32 v2, v0
	v_mov_b32_e32 v3, v0
	v_mov_b32_e32 v4, v0
	v_mov_b32_e32 v5, v0
	v_mov_b32_e32 v6, v0
	v_mov_b32_e32 v7, v0
	v_mov_b32_e32 v8, v0
	v_mov_b32_e32 v9, v0
	v_mov_b32_e32 v10, v0
	v_mov_b32_e32 v11, v0
	v_mov_b32_e32 v12, v0
	v_mov_b32_e32 v13, v0
	v_mov_b32_e32 v14, v0
	v_mov_b32_e32 v15, v0
	v_mov_b32_e32 v32, v0
	v_mov_b32_e32 v33, v0
	v_mov_b32_e32 v34, v0
	v_mov_b32_e32 v35, v0
	v_mov_b32_e32 v36, v0
	v_mov_b32_e32 v37, v0
	v_mov_b32_e32 v38, v0
	v_mov_b32_e32 v39, v0
	v_mov_b32_e32 v40, v0
	v_mov_b32_e32 v41, v0
	v_mov_b32_e32 v42, v0
	v_mov_b32_e32 v43, v0
	v_mov_b32_e32 v44, v0
	v_mov_b32_e32 v45, v0
	v_mov_b32_e32 v46, v0
	v_mov_b32_e32 v47, v0
	v_mov_b32_e32 v16, v0
	v_mov_b32_e32 v17, v0
	v_mov_b32_e32 v18, v0
	v_mov_b32_e32 v19, v0
	v_mov_b32_e32 v20, v0
	v_mov_b32_e32 v21, v0
	v_mov_b32_e32 v22, v0
	v_mov_b32_e32 v23, v0
	v_mov_b32_e32 v24, v0
	v_mov_b32_e32 v25, v0
	v_mov_b32_e32 v26, v0
	v_mov_b32_e32 v27, v0
	v_mov_b32_e32 v28, v0
	v_mov_b32_e32 v29, v0
	v_mov_b32_e32 v30, v0
	v_mov_b32_e32 v31, v0
	v_mov_b32_e32 v48, v0
	v_mov_b32_e32 v49, v0
	v_mov_b32_e32 v50, v0
	v_mov_b32_e32 v51, v0
	v_mov_b32_e32 v52, v0
	v_mov_b32_e32 v53, v0
	v_mov_b32_e32 v54, v0
	v_mov_b32_e32 v55, v0
	v_mov_b32_e32 v56, v0
	v_mov_b32_e32 v57, v0
	v_mov_b32_e32 v58, v0
	v_mov_b32_e32 v59, v0
	v_mov_b32_e32 v60, v0
	v_mov_b32_e32 v61, v0
	v_mov_b32_e32 v62, v0
	v_mov_b32_e32 v63, v0
	s_add_i32 s99, s18, 0
	v_add_u32_e32 v100, s99, v82
	v_add_u32_e32 v101, s99, v83
	ds_read_b128 v[84:87], v101 offset:16384
	ds_read_b128 v[88:91], v100
	ds_read_b128 v[92:95], v100 offset:4096
	s_mov_b64 vcc, -1
	s_branch .Lfws_79

; DEV int stage_next(int s) { return (s == 2 * GS_STAGE) ? 0 : s + GS_STAGE; }
; template <int WAIT0>
; DEV void gk_main(f32x16 (&acc)[2][2], const GTile& t, int s0) {
;     ...
;   for (int kt = 0; kt < nk - 2; ++kt) {
;     GK_DMA(std_, kt + 2);
;     GK_COMPUTE(stc);
;     vm_wait_bar<6>();
;     stc = stage_next(stc); std_ = stage_next(std_);
;   }
;   GK_COMPUTE(stc);
;   vm_wait_bar<0>();
;   stc = stage_next(stc);
;   GK_COMPUTE(stc);
;   vm_wait_bar<0>();
.Lfwb_79:
	s_waitcnt lgkmcnt(0)
	s_add_i32 s99, s18, 0
	v_add_u32_e32 v100, s99, v82
	v_add_u32_e32 v101, s99, v83
	ds_read_b128 v[84:87], v101 offset:16384
	ds_read_b128 v[88:91], v100
	ds_read_b128 v[92:95], v100 offset:4096
	v_mfma_f32_32x32x16_bf16 v[32:47], v[236:239], v[240:243], v[32:47]
	v_mfma_f32_32x32x16_bf16 v[0:15], v[236:239], v[244:247], v[0:15]
	s_cmpk_lg_i32 s6, 0x700
	s_cbranch_scc1 .LBB0_79
	s_waitcnt lgkmcnt(0)
	s_add_i32 s6, s18, 0
	v_add_u32_e32 v84, s6, v83
	ds_read_b128 v[64:67], v84 offset:16384
	v_add_u32_e32 v72, s6, v82
	ds_read_b128 v[68:71], v72
	ds_read_b128 v[72:75], v72 offset:4096
	s_waitcnt lgkmcnt(0)
	v_mfma_f32_32x32x16_bf16 v[48:63], v[64:67], v[68:71], v[48:63]
	v_mfma_f32_32x32x16_bf16 v[16:31], v[64:67], v[72:75], v[16:31]
	ds_read_b128 v[64:67], v84 offset:20480
	v_add_u32_e32 v84, s6, v81
	s_waitcnt lgkmcnt(0)
	v_mfma_f32_32x32x16_bf16 v[32:47], v[64:67], v[68:71], v[32:47]
	v_mfma_f32_32x32x16_bf16 v[0:15], v[64:67], v[72:75], v[0:15]
	ds_read_b128 v[64:67], v84 offset:16384
	v_add_u32_e32 v72, s6, v80
	ds_read_b128 v[68:71], v72
	ds_read_b128 v[72:75], v72 offset:4096
	s_waitcnt lgkmcnt(0)
	v_mfma_f32_32x32x16_bf16 v[48:63], v[64:67], v[68:71], v[48:63]
	v_mfma_f32_32x32x16_bf16 v[16:31], v[64:67], v[72:75], v[16:31]
	ds_read_b128 v[64:67], v84 offset:20480
	v_add_u32_e32 v84, s6, v79
	s_waitcnt lgkmcnt(0)
	v_mfma_f32_32x32x16_bf16 v[32:47], v[64:67], v[68:71], v[32:47]
	v_mfma_f32_32x32x16_bf16 v[0:15], v[64:67], v[72:75], v[0:15]
	ds_read_b128 v[64:67], v84 offset:16384
	v_add_u32_e32 v72, s6, v78
	ds_read_b128 v[68:71], v72
	ds_read_b128 v[72:75], v72 offset:4096
	s_waitcnt lgkmcnt(0)
	v_mfma_f32_32x32x16_bf16 v[48:63], v[64:67], v[68:71], v[48:63]
	v_mfma_f32_32x32x16_bf16 v[16:31], v[64:67], v[72:75], v[16:31]
	ds_read_b128 v[64:67], v84 offset:20480
	v_add_u32_e32 v84, s6, v77
	s_waitcnt lgkmcnt(0)
	v_mfma_f32_32x32x16_bf16 v[32:47], v[64:67], v[68:71], v[32:47]
	v_mfma_f32_32x32x16_bf16 v[0:15], v[64:67], v[72:75], v[0:15]
	ds_read_b128 v[64:67], v84 offset:16384
	v_add_u32_e32 v72, s6, v76
	ds_read_b128 v[68:71], v72
	ds_read_b128 v[72:75], v72 offset:4096
	s_add_i32 s6, s18, 0xc000
	s_cmp_lg_u32 s18, 0x18000
	s_cselect_b32 s6, s6, 0
	s_waitcnt lgkmcnt(0)
	v_mfma_f32_32x32x16_bf16 v[48:63], v[64:67], v[68:71], v[48:63]
	s_add_i32 s6, s6, 0
	v_add_u32_e32 v83, s6, v83
	v_add_u32_e32 v81, s6, v81
	v_add_u32_e32 v79, s6, v79
	v_add_u32_e32 v77, s6, v77
	v_mfma_f32_32x32x16_bf16 v[16:31], v[64:67], v[72:75], v[16:31]
	ds_read_b128 v[64:67], v84 offset:20480
	s_waitcnt vmcnt(0) lgkmcnt(0)
	s_barrier
	s_waitcnt lgkmcnt(0)
	v_mfma_f32_32x32x16_bf16 v[32:47], v[64:67], v[68:71], v[32:47]
	v_mfma_f32_32x32x16_bf16 v[0:15], v[64:67], v[72:75], v[0:15]
	ds_read_b128 v[64:67], v83 offset:16384
	v_add_u32_e32 v72, s6, v82
	ds_read_b128 v[68:71], v72
	ds_read_b128 v[72:75], v72 offset:4096
	s_waitcnt lgkmcnt(0)
	v_mfma_f32_32x32x16_bf16 v[48:63], v[64:67], v[68:71], v[48:63]
	v_mfma_f32_32x32x16_bf16 v[16:31], v[64:67], v[72:75], v[16:31]
	ds_read_b128 v[64:67], v83 offset:20480
	s_waitcnt lgkmcnt(0)
	v_mfma_f32_32x32x16_bf16 v[32:47], v[64:67], v[68:71], v[32:47]
	v_mfma_f32_32x32x16_bf16 v[0:15], v[64:67], v[72:75], v[0:15]
	ds_read_b128 v[64:67], v81 offset:16384
	v_add_u32_e32 v72, s6, v80
	ds_read_b128 v[68:71], v72
	ds_read_b128 v[72:75], v72 offset:4096
	s_waitcnt lgkmcnt(0)
	v_mfma_f32_32x32x16_bf16 v[48:63], v[64:67], v[68:71], v[48:63]
	v_mfma_f32_32x32x16_bf16 v[16:31], v[64:67], v[72:75], v[16:31]
	ds_read_b128 v[64:67], v81 offset:20480
	s_waitcnt lgkmcnt(0)
	v_mfma_f32_32x32x16_bf16 v[32:47], v[64:67], v[68:71], v[32:47]
	v_mfma_f32_32x32x16_bf16 v[0:15], v[64:67], v[72:75], v[0:15]
	ds_read_b128 v[64:67], v79 offset:16384
	v_add_u32_e32 v72, s6, v78
	ds_read_b128 v[68:71], v72
	ds_read_b128 v[72:75], v72 offset:4096
	s_waitcnt lgkmcnt(0)
	v_mfma_f32_32x32x16_bf16 v[48:63], v[64:67], v[68:71], v[48:63]
	v_mfma_f32_32x32x16_bf16 v[16:31], v[64:67], v[72:75], v[16:31]
	ds_read_b128 v[64:67], v79 offset:20480
	s_waitcnt lgkmcnt(0)
	v_mfma_f32_32x32x16_bf16 v[32:47], v[64:67], v[68:71], v[32:47]
	v_mfma_f32_32x32x16_bf16 v[0:15], v[64:67], v[72:75], v[0:15]
	ds_read_b128 v[64:67], v77 offset:16384
	v_add_u32_e32 v72, s6, v76
	ds_read_b128 v[68:71], v72
	ds_read_b128 v[72:75], v72 offset:4096
	s_waitcnt lgkmcnt(0)
	v_mfma_f32_32x32x16_bf16 v[48:63], v[64:67], v[68:71], v[48:63]
	v_mfma_f32_32x32x16_bf16 v[16:31], v[64:67], v[72:75], v[16:31]
	ds_read_b128 v[64:67], v77 offset:20480
	s_waitcnt vmcnt(0) lgkmcnt(0)
	s_barrier
	s_waitcnt lgkmcnt(0)
	v_mfma_f32_32x32x16_bf16 v[32:47], v[64:67], v[68:71], v[32:47]
	v_mfma_f32_32x32x16_bf16 v[0:15], v[64:67], v[72:75], v[0:15]

; DEV int tid_l() { int t = threadIdx.x; asm volatile("" : "+v"(t)); return t; }
; DEV int stage_next(int s) { return (s == 2 * GS_STAGE) ? 0 : s + GS_STAGE; }
; DEV void gk_issue2(const GTile& t, int s0) {
;   const int tid = tid_l(), lane = tid & 63, wid = __builtin_amdgcn_readfirstlane(tid >> 6);
;   GK_SRC(t)
;   asm volatile("" ::: "memory");
;   GK_DMA(s0, 0);
;   GK_DMA(stage_next(s0), 1);
;   asm volatile("" ::: "memory");
; }
; template <int WAIT0>
; DEV void gk_main(f32x16 (&acc)[2][2], const GTile& t, int s0) {
;   const int tid = tid_l(), lane = tid & 63, wid = __builtin_amdgcn_readfirstlane(tid >> 6), wm = wid & 1, wn = wid >> 1, l32 = lane & 31, hi = lane >> 5;
;   GK_SRC(t)
;   const int sw = (l32 >> 1) & 7;
;   int xk[4], wk[4];
; #pragma unroll
;   for (int ks = 0; ks < 4; ++ks) { const int ko = ((2 * ks + hi) ^ sw) << 4; xk[ks] = GS_A + (64 * wm + l32) * 128 + ko; wk[ks] = GS_B + (64 * wn + l32) * 128 + ko; }
;   const int nk = t.K >> 6;
;     ...
;   vm_wait_bar<WAIT0>();
;   int stc = s0, std_ = stage_next(stage_next(s0));
; #pragma nounroll
;   for (int kt = 0; kt < nk - 2; ++kt) {
;     GK_DMA(std_, kt + 2);
;     GK_COMPUTE(stc);
;     vm_wait_bar<6>();
;     stc = stage_next(stc); std_ = stage_next(std_);
;   }
.LBB0_295:
	s_cmp_lg_u32 s15, 0
	s_cbranch_scc0 .LBB0_306
	s_bitcmp0_b32 s15, 0
	s_mov_b64 s[0:1], -1
	s_cbranch_scc1 .LBB0_300
	v_mov_b32_e32 v1, v176
	s_waitcnt vmcnt(63) lgkmcnt(0)
	s_barrier
	v_readfirstlane_b32 s0, v1
	s_ashr_i32 s1, s0, 6
	v_bfe_u32 v0, v1, 3, 3
	v_and_b32_e32 v2, 31, v1
	v_lshl_or_b32 v0, s1, 3, v0
	v_lshrrev_b32_e32 v3, 1, v0
	v_and_or_b32 v6, s0, 64, v2
	s_lshr_b32 s0, s0, 1
	v_xor_b32_e32 v3, v3, v1
	s_and_b32 s0, s0, 0x1ffffc0
	v_lshlrev_b32_e32 v3, 4, v3
	v_or_b32_e32 v2, s0, v2
	s_lshl_b32 s0, s1, 10
	v_and_b32_e32 v4, 0x70, v3
	v_bfe_u32 v3, v1, 5, 1
	v_lshrrev_b32_e32 v5, 1, v1
	v_bfe_u32 v1, v1, 1, 3
	s_add_i32 s1, s0, 0
	s_add_i32 s0, s14, 0xc000
	v_bitop3_b32 v5, v3, v5, 7 bitop3:0x78
	v_bitop3_b32 v7, v3, v1, 2 bitop3:0x36
	v_bitop3_b32 v8, v3, v1, 4 bitop3:0x36
	v_bitop3_b32 v1, v3, v1, 6 bitop3:0x36
	s_cmp_lg_u32 s14, 0x18000
	v_lshlrev_b32_e32 v2, 7, v2
	v_lshlrev_b32_e32 v5, 4, v5
	v_lshlrev_b32_e32 v7, 4, v7
	v_lshlrev_b32_e32 v8, 4, v8
	v_lshlrev_b32_e32 v1, 4, v1
	s_cselect_b32 s2, s0, 0
	s_add_i32 s0, s2, 0xc000
	v_or_b32_e32 v86, v2, v5
	v_or_b32_e32 v84, v2, v7
	v_or_b32_e32 v82, v2, v8
	v_or_b32_e32 v80, v2, v1
	v_add_u32_e32 v2, 0xc0, v0
	s_cmp_lg_u32 s2, 0x18000
	v_ashrrev_i32_e32 v3, 31, v2
	s_cselect_b32 s3, s0, 0
	s_add_u32 s10, s6, 0x100
	v_lshlrev_b64 v[2:3], 11, v[2:3]
	s_addc_u32 s11, s7, 0
	v_or_b32_e32 v2, v2, v4
	v_lshl_add_u64 v[66:67], s[10:11], 0, v[2:3]
	v_add_u32_e32 v2, 0x80, v0
	v_ashrrev_i32_e32 v3, 31, v2
	v_lshlrev_b64 v[2:3], 11, v[2:3]
	v_or_b32_e32 v2, v2, v4
	v_lshlrev_b32_e32 v6, 7, v6
	v_lshl_add_u64 v[68:69], s[10:11], 0, v[2:3]
	v_add_u32_e32 v2, 64, v0
	v_or_b32_e32 v79, v1, v6
	v_ashrrev_i32_e32 v3, 31, v2
	v_ashrrev_i32_e32 v1, 31, v0
	v_lshlrev_b64 v[2:3], 11, v[2:3]
	v_lshlrev_b64 v[0:1], 11, v[0:1]
	v_or_b32_e32 v2, v2, v4
	v_or_b32_e32 v0, v0, v4
	v_lshl_add_u64 v[70:71], s[10:11], 0, v[2:3]
	v_lshl_add_u64 v[72:73], s[10:11], 0, v[0:1]
	v_readlane_b32 s10, v231, 15
	v_readlane_b32 s11, v231, 16
	v_or_b32_e32 v85, v5, v6
	v_or_b32_e32 v83, v7, v6
	v_lshl_add_u64 v[76:77], s[10:11], 0, v[0:1]
	v_mov_b32_e32 v0, 0
	v_or_b32_e32 v81, v8, v6
	v_lshl_add_u64 v[74:75], s[10:11], 0, v[2:3]
	s_mov_b64 s[10:11], 0
	s_mov_b32 s0, s14
	v_mov_b32_e32 v1, v0
	v_mov_b32_e32 v2, v0
	v_mov_b32_e32 v3, v0
	v_mov_b32_e32 v4, v0
	v_mov_b32_e32 v5, v0
	v_mov_b32_e32 v6, v0
	v_mov_b32_e32 v7, v0
	v_mov_b32_e32 v8, v0
	v_mov_b32_e32 v9, v0
	v_mov_b32_e32 v10, v0
	v_mov_b32_e32 v11, v0
	v_mov_b32_e32 v12, v0
	v_mov_b32_e32 v13, v0
	v_mov_b32_e32 v14, v0
	v_mov_b32_e32 v15, v0
	v_mov_b32_e32 v16, v0
	v_mov_b32_e32 v17, v0
	v_mov_b32_e32 v18, v0
	v_mov_b32_e32 v19, v0
	v_mov_b32_e32 v20, v0
	v_mov_b32_e32 v21, v0
	v_mov_b32_e32 v22, v0
	v_mov_b32_e32 v23, v0
	v_mov_b32_e32 v24, v0
	v_mov_b32_e32 v25, v0
	v_mov_b32_e32 v26, v0
	v_mov_b32_e32 v27, v0
	v_mov_b32_e32 v28, v0
	v_mov_b32_e32 v29, v0
	v_mov_b32_e32 v30, v0
	v_mov_b32_e32 v31, v0
	v_mov_b32_e32 v32, v0
	v_mov_b32_e32 v33, v0
	v_mov_b32_e32 v34, v0
	v_mov_b32_e32 v35, v0
	v_mov_b32_e32 v36, v0
	v_mov_b32_e32 v37, v0
	v_mov_b32_e32 v38, v0
	v_mov_b32_e32 v39, v0
	v_mov_b32_e32 v40, v0
	v_mov_b32_e32 v41, v0
	v_mov_b32_e32 v42, v0
	v_mov_b32_e32 v43, v0
	v_mov_b32_e32 v44, v0
	v_mov_b32_e32 v45, v0
	v_mov_b32_e32 v46, v0
	v_mov_b32_e32 v47, v0
	v_mov_b32_e32 v48, v0
	v_mov_b32_e32 v49, v0
	v_mov_b32_e32 v50, v0
	v_mov_b32_e32 v51, v0
	v_mov_b32_e32 v52, v0
	v_mov_b32_e32 v53, v0
	v_mov_b32_e32 v54, v0
	v_mov_b32_e32 v55, v0
	v_mov_b32_e32 v56, v0
	v_mov_b32_e32 v57, v0
	v_mov_b32_e32 v58, v0
	v_mov_b32_e32 v59, v0
	v_mov_b32_e32 v60, v0
	v_mov_b32_e32 v61, v0
	v_mov_b32_e32 v62, v0
	v_mov_b32_e32 v63, v0
	s_mov_b64 vcc, -1
	s_branch .Lfws_298
.Lfw_298:
	s_waitcnt vmcnt(63) lgkmcnt(0)
	s_barrier
	s_mov_b64 vcc, 0
	s_branch .Lfwb_298
.Lfws_298:
.LBB0_298:
	s_add_i32 s16, s1, s3
	s_mov_b32 s98, s16
	s_mov_b64 s[100:101], s[10:11]
	s_add_i32 s16, s0, 0
	v_add_u32_e32 v87, s16, v85
	ds_read_b128 v[88:91], v87
	ds_read_b128 v[92:95], v87 offset:4096
	v_add_u32_e32 v87, s16, v86
	ds_read_b128 v[96:99], v87 offset:16384
	ds_read_b128 v[100:103], v87 offset:20480
	s_waitcnt lgkmcnt(0)
	v_add_u32_e32 v87, s16, v83
	ds_read_b128 v[236:239], v87
	ds_read_b128 v[240:243], v87 offset:4096
	v_add_u32_e32 v87, s16, v84
	ds_read_b128 v[244:247], v87 offset:16384
	ds_read_b128 v[248:251], v87 offset:20480
	v_mfma_f32_32x32x16_bf16 v[48:63], v[96:99], v[88:91], v[48:63]
	v_mfma_f32_32x32x16_bf16 v[32:47], v[96:99], v[92:95], v[32:47]
	s_mov_b32 m0, s98
	v_lshl_add_u64 v[254:255], v[76:77], 0, s[100:101]
	global_load_lds_dwordx4 v[254:255], off
	v_mfma_f32_32x32x16_bf16 v[16:31], v[100:103], v[88:91], v[16:31]
	v_mfma_f32_32x32x16_bf16 v[0:15], v[100:103], v[92:95], v[0:15]
	s_add_i32 m0, s98, 0x2000
	v_lshl_add_u64 v[254:255], v[74:75], 0, s[100:101]
	global_load_lds_dwordx4 v[254:255], off
	v_add_u32_e32 v87, s16, v81
	s_waitcnt lgkmcnt(0)
	ds_read_b128 v[88:91], v87
	ds_read_b128 v[92:95], v87 offset:4096
	v_add_u32_e32 v87, s16, v82
	ds_read_b128 v[96:99], v87 offset:16384
	ds_read_b128 v[100:103], v87 offset:20480
	v_mfma_f32_32x32x16_bf16 v[48:63], v[244:247], v[236:239], v[48:63]
	v_mfma_f32_32x32x16_bf16 v[32:47], v[244:247], v[240:243], v[32:47]
	s_add_i32 m0, s98, 0x4000
	v_lshl_add_u64 v[254:255], v[72:73], 0, s[100:101]
	global_load_lds_dwordx4 v[254:255], off
	v_mfma_f32_32x32x16_bf16 v[16:31], v[248:251], v[236:239], v[16:31]
	v_mfma_f32_32x32x16_bf16 v[0:15], v[248:251], v[240:243], v[0:15]
	s_add_i32 m0, s98, 0x6000
	v_lshl_add_u64 v[254:255], v[70:71], 0, s[100:101]
	global_load_lds_dwordx4 v[254:255], off
	v_add_u32_e32 v87, s16, v79
	s_waitcnt lgkmcnt(0)
	ds_read_b128 v[236:239], v87
	ds_read_b128 v[240:243], v87 offset:4096
	v_add_u32_e32 v87, s16, v80
	ds_read_b128 v[244:247], v87 offset:16384
	ds_read_b128 v[248:251], v87 offset:20480
	v_mfma_f32_32x32x16_bf16 v[48:63], v[96:99], v[88:91], v[48:63]
	v_mfma_f32_32x32x16_bf16 v[32:47], v[96:99], v[92:95], v[32:47]
	s_add_i32 m0, s98, 0x8000
	v_lshl_add_u64 v[254:255], v[68:69], 0, s[100:101]
	global_load_lds_dwordx4 v[254:255], off
	v_mfma_f32_32x32x16_bf16 v[16:31], v[100:103], v[88:91], v[16:31]
	v_mfma_f32_32x32x16_bf16 v[0:15], v[100:103], v[92:95], v[0:15]
	s_add_i32 m0, s98, 0xa000
	v_lshl_add_u64 v[254:255], v[66:67], 0, s[100:101]
	global_load_lds_dwordx4 v[254:255], off
	s_add_i32 s16, s0, 0xc000
	s_cmp_lg_u32 s0, 0x18000
	s_cselect_b32 s0, s16, 0
	s_add_i32 s16, s3, 0xc000
	s_waitcnt lgkmcnt(0)
	v_mfma_f32_32x32x16_bf16 v[48:63], v[244:247], v[236:239], v[48:63]
	s_cmp_lg_u32 s3, 0x18000
	s_cbranch_vccnz .Lfw_298
	s_waitcnt vmcnt(6) lgkmcnt(0)
	s_barrier
; DEV int stage_next(int s) { return (s == 2 * GS_STAGE) ? 0 : s + GS_STAGE; }
; template <int WAIT0>
; DEV void gk_main(f32x16 (&acc)[2][2], const GTile& t, int s0) {
;     ...
;   for (int kt = 0; kt < nk - 2; ++kt) {
;     GK_DMA(std_, kt + 2);
;     GK_COMPUTE(stc);
;     vm_wait_bar<6>();
;     stc = stage_next(stc); std_ = stage_next(std_);
;   }
;   GK_COMPUTE(stc);
;   vm_wait_bar<0>();
;   stc = stage_next(stc);
;   GK_COMPUTE(stc);
;   vm_wait_bar<0>();
.Lfwb_298:
	s_cselect_b32 s3, s16, 0
	s_add_u32 s10, s10, 0x80
	s_addc_u32 s11, s11, 0
	v_mfma_f32_32x32x16_bf16 v[32:47], v[244:247], v[240:243], v[32:47]
	s_cmpk_lg_i32 s10, 0x700
	v_mfma_f32_32x32x16_bf16 v[16:31], v[248:251], v[236:239], v[16:31]
	v_mfma_f32_32x32x16_bf16 v[0:15], v[248:251], v[240:243], v[0:15]
	s_cbranch_scc1 .LBB0_298
	s_add_i32 s1, s0, 0
	v_add_u32_e32 v87, s1, v86
	ds_read_b128 v[66:69], v87 offset:16384
	v_add_u32_e32 v74, s1, v85
	ds_read_b128 v[70:73], v74
	ds_read_b128 v[74:77], v74 offset:4096
	s_waitcnt lgkmcnt(0)
	v_mfma_f32_32x32x16_bf16 v[48:63], v[66:69], v[70:73], v[48:63]
	v_mfma_f32_32x32x16_bf16 v[32:47], v[66:69], v[74:77], v[32:47]
	ds_read_b128 v[66:69], v87 offset:20480
	v_add_u32_e32 v87, s1, v84
	s_waitcnt lgkmcnt(0)
	v_mfma_f32_32x32x16_bf16 v[16:31], v[66:69], v[70:73], v[16:31]
	v_mfma_f32_32x32x16_bf16 v[0:15], v[66:69], v[74:77], v[0:15]
	ds_read_b128 v[66:69], v87 offset:16384
	v_add_u32_e32 v74, s1, v83
	ds_read_b128 v[70:73], v74
	ds_read_b128 v[74:77], v74 offset:4096
	s_waitcnt lgkmcnt(0)
	v_mfma_f32_32x32x16_bf16 v[48:63], v[66:69], v[70:73], v[48:63]
	v_mfma_f32_32x32x16_bf16 v[32:47], v[66:69], v[74:77], v[32:47]
	ds_read_b128 v[66:69], v87 offset:20480
	v_add_u32_e32 v87, s1, v82
	s_waitcnt lgkmcnt(0)
	v_mfma_f32_32x32x16_bf16 v[16:31], v[66:69], v[70:73], v[16:31]
	v_mfma_f32_32x32x16_bf16 v[0:15], v[66:69], v[74:77], v[0:15]
	ds_read_b128 v[66:69], v87 offset:16384
	v_add_u32_e32 v74, s1, v81
	ds_read_b128 v[70:73], v74
	ds_read_b128 v[74:77], v74 offset:4096
	s_waitcnt lgkmcnt(0)
	v_mfma_f32_32x32x16_bf16 v[48:63], v[66:69], v[70:73], v[48:63]
	v_mfma_f32_32x32x16_bf16 v[32:47], v[66:69], v[74:77], v[32:47]
	ds_read_b128 v[66:69], v87 offset:20480
	v_add_u32_e32 v87, s1, v80
	s_waitcnt lgkmcnt(0)
	v_mfma_f32_32x32x16_bf16 v[16:31], v[66:69], v[70:73], v[16:31]
	v_mfma_f32_32x32x16_bf16 v[0:15], v[66:69], v[74:77], v[0:15]
	ds_read_b128 v[66:69], v87 offset:16384
	v_add_u32_e32 v74, s1, v79
	ds_read_b128 v[70:73], v74
	ds_read_b128 v[74:77], v74 offset:4096
	s_add_i32 s1, s0, 0xc000
	s_cmp_lg_u32 s0, 0x18000
	s_cselect_b32 s0, s1, 0
	s_waitcnt lgkmcnt(0)
	v_mfma_f32_32x32x16_bf16 v[48:63], v[66:69], v[70:73], v[48:63]
	s_add_i32 s0, s0, 0
	v_add_u32_e32 v86, s0, v86
	v_add_u32_e32 v84, s0, v84
	v_add_u32_e32 v82, s0, v82
	v_add_u32_e32 v80, s0, v80
	v_mfma_f32_32x32x16_bf16 v[32:47], v[66:69], v[74:77], v[32:47]
	ds_read_b128 v[66:69], v87 offset:20480
	s_waitcnt vmcnt(0) lgkmcnt(0)
	s_barrier
	s_waitcnt lgkmcnt(0)
	v_mfma_f32_32x32x16_bf16 v[16:31], v[66:69], v[70:73], v[16:31]
	v_mfma_f32_32x32x16_bf16 v[0:15], v[66:69], v[74:77], v[0:15]
	ds_read_b128 v[66:69], v86 offset:16384
	v_add_u32_e32 v74, s0, v85
	ds_read_b128 v[70:73], v74
	ds_read_b128 v[74:77], v74 offset:4096
	s_waitcnt lgkmcnt(0)
	v_mfma_f32_32x32x16_bf16 v[48:63], v[66:69], v[70:73], v[48:63]
	v_mfma_f32_32x32x16_bf16 v[32:47], v[66:69], v[74:77], v[32:47]
	ds_read_b128 v[66:69], v86 offset:20480
	s_waitcnt lgkmcnt(0)
	v_mfma_f32_32x32x16_bf16 v[16:31], v[66:69], v[70:73], v[16:31]
	v_mfma_f32_32x32x16_bf16 v[0:15], v[66:69], v[74:77], v[0:15]
	ds_read_b128 v[66:69], v84 offset:16384
	v_add_u32_e32 v74, s0, v83
	ds_read_b128 v[70:73], v74
	ds_read_b128 v[74:77], v74 offset:4096
	s_waitcnt lgkmcnt(0)
	v_mfma_f32_32x32x16_bf16 v[48:63], v[66:69], v[70:73], v[48:63]
	v_mfma_f32_32x32x16_bf16 v[32:47], v[66:69], v[74:77], v[32:47]
	ds_read_b128 v[66:69], v84 offset:20480
	s_waitcnt lgkmcnt(0)
	v_mfma_f32_32x32x16_bf16 v[16:31], v[66:69], v[70:73], v[16:31]
	v_mfma_f32_32x32x16_bf16 v[0:15], v[66:69], v[74:77], v[0:15]
	ds_read_b128 v[66:69], v82 offset:16384
	v_add_u32_e32 v74, s0, v81
	ds_read_b128 v[70:73], v74
	ds_read_b128 v[74:77], v74 offset:4096
	s_waitcnt lgkmcnt(0)
	v_mfma_f32_32x32x16_bf16 v[48:63], v[66:69], v[70:73], v[48:63]
	v_mfma_f32_32x32x16_bf16 v[32:47], v[66:69], v[74:77], v[32:47]
	ds_read_b128 v[66:69], v82 offset:20480
	s_waitcnt lgkmcnt(0)
	v_mfma_f32_32x32x16_bf16 v[16:31], v[66:69], v[70:73], v[16:31]
	v_mfma_f32_32x32x16_bf16 v[0:15], v[66:69], v[74:77], v[0:15]
	ds_read_b128 v[66:69], v80 offset:16384
	v_add_u32_e32 v74, s0, v79
	ds_read_b128 v[70:73], v74
	ds_read_b128 v[74:77], v74 offset:4096
	s_mov_b64 s[0:1], 0
	s_waitcnt lgkmcnt(0)
	v_mfma_f32_32x32x16_bf16 v[48:63], v[66:69], v[70:73], v[48:63]
	v_mfma_f32_32x32x16_bf16 v[32:47], v[66:69], v[74:77], v[32:47]
	ds_read_b128 v[66:69], v80 offset:20480
	s_waitcnt vmcnt(0) lgkmcnt(0)
	s_barrier
	s_waitcnt lgkmcnt(0)
	v_mfma_f32_32x32x16_bf16 v[16:31], v[66:69], v[70:73], v[16:31]
	v_mfma_f32_32x32x16_bf16 v[0:15], v[66:69], v[74:77], v[0:15]
; DEV int tid_l() { int t = threadIdx.x; asm volatile("" : "+v"(t)); return t; }
; DEV int stage_next(int s) { return (s == 2 * GS_STAGE) ? 0 : s + GS_STAGE; }
; DEV void gk_issue2(const GTile& t, int s0) {
;   const int tid = tid_l(), lane = tid & 63, wid = __builtin_amdgcn_readfirstlane(tid >> 6);
;   GK_SRC(t)
;   asm volatile("" ::: "memory");
;   GK_DMA(s0, 0);
;   GK_DMA(stage_next(s0), 1);
;   asm volatile("" ::: "memory");
; }
; template <int WAIT0>
; DEV void gk_main(f32x16 (&acc)[2][2], const GTile& t, int s0) {
;   const int tid = tid_l(), lane = tid & 63, wid = __builtin_amdgcn_readfirstlane(tid >> 6), wm = wid & 1, wn = wid >> 1, l32 = lane & 31, hi = lane >> 5;
;   GK_SRC(t)
;   const int sw = (l32 >> 1) & 7;
;   int xk[4], wk[4];
; #pragma unroll
;   for (int ks = 0; ks < 4; ++ks) { const int ko = ((2 * ks + hi) ^ sw) << 4; xk[ks] = GS_A + (64 * wm + l32) * 128 + ko; wk[ks] = GS_B + (64 * wn + l32) * 128 + ko; }
;   const int nk = t.K >> 6;
;     ...
;   vm_wait_bar<WAIT0>();
;   int stc = s0, std_ = stage_next(stage_next(s0));
.LBB0_300:
	s_and_b64 vcc, exec, s[0:1]
	s_cbranch_vccz .LBB0_304
	s_nop 9
	v_mov_b32_e32 v1, v176
	s_waitcnt vmcnt(63) lgkmcnt(0)
	s_barrier
	v_readfirstlane_b32 s0, v1
	s_ashr_i32 s1, s0, 6
	v_bfe_u32 v0, v1, 3, 3
	v_and_b32_e32 v2, 31, v1
	v_lshl_or_b32 v0, s1, 3, v0
	v_lshrrev_b32_e32 v3, 1, v0
	v_and_or_b32 v6, s0, 64, v2
	s_lshr_b32 s0, s0, 1
	v_xor_b32_e32 v3, v3, v1
	s_and_b32 s0, s0, 0x1ffffc0
	v_lshlrev_b32_e32 v3, 4, v3
	v_or_b32_e32 v2, s0, v2
	s_lshl_b32 s0, s1, 10
	v_and_b32_e32 v4, 0x70, v3
	v_bfe_u32 v3, v1, 5, 1
	v_lshrrev_b32_e32 v5, 1, v1
	v_bfe_u32 v1, v1, 1, 3
	s_add_i32 s1, s0, 0
	s_add_i32 s0, s14, 0xc000
	v_bitop3_b32 v5, v3, v5, 7 bitop3:0x78
	v_bitop3_b32 v7, v3, v1, 2 bitop3:0x36
	v_bitop3_b32 v8, v3, v1, 4 bitop3:0x36
	v_bitop3_b32 v1, v3, v1, 6 bitop3:0x36
	s_cmp_lg_u32 s14, 0x18000
	v_lshlrev_b32_e32 v2, 7, v2
	v_lshlrev_b32_e32 v5, 4, v5
	v_lshlrev_b32_e32 v7, 4, v7
	v_lshlrev_b32_e32 v8, 4, v8
	v_lshlrev_b32_e32 v1, 4, v1
	s_cselect_b32 s2, s0, 0
	s_add_i32 s0, s2, 0xc000
	v_or_b32_e32 v86, v2, v5
	v_or_b32_e32 v84, v2, v7
	v_or_b32_e32 v82, v2, v8
	v_or_b32_e32 v80, v2, v1
	v_add_u32_e32 v2, 0xc0, v0
	s_cmp_lg_u32 s2, 0x18000
	v_ashrrev_i32_e32 v3, 31, v2
	s_cselect_b32 s3, s0, 0
	s_add_u32 s10, s6, 0x100
	v_lshlrev_b64 v[2:3], 11, v[2:3]
	s_addc_u32 s11, s7, 0
	v_or_b32_e32 v2, v2, v4
	v_lshl_add_u64 v[66:67], s[10:11], 0, v[2:3]
	v_add_u32_e32 v2, 0x80, v0
	v_ashrrev_i32_e32 v3, 31, v2
	v_lshlrev_b64 v[2:3], 11, v[2:3]
	v_or_b32_e32 v2, v2, v4
	v_lshlrev_b32_e32 v6, 7, v6
	v_lshl_add_u64 v[68:69], s[10:11], 0, v[2:3]
	v_add_u32_e32 v2, 64, v0
	v_or_b32_e32 v79, v1, v6
	v_ashrrev_i32_e32 v3, 31, v2
	v_ashrrev_i32_e32 v1, 31, v0
	v_lshlrev_b64 v[2:3], 11, v[2:3]
	v_lshlrev_b64 v[0:1], 11, v[0:1]
	v_or_b32_e32 v2, v2, v4
	v_or_b32_e32 v0, v0, v4
	v_lshl_add_u64 v[70:71], s[10:11], 0, v[2:3]
	v_lshl_add_u64 v[72:73], s[10:11], 0, v[0:1]
	v_readlane_b32 s10, v231, 15
	v_readlane_b32 s11, v231, 16
	v_or_b32_e32 v85, v5, v6
	v_or_b32_e32 v83, v7, v6
	v_lshl_add_u64 v[76:77], s[10:11], 0, v[0:1]
	v_mov_b32_e32 v0, 0
	v_or_b32_e32 v81, v8, v6
	v_lshl_add_u64 v[74:75], s[10:11], 0, v[2:3]
	s_mov_b64 s[10:11], 0
	s_mov_b32 s0, s14
	v_mov_b32_e32 v1, v0
	v_mov_b32_e32 v2, v0
	v_mov_b32_e32 v3, v0
	v_mov_b32_e32 v4, v0
	v_mov_b32_e32 v5, v0
	v_mov_b32_e32 v6, v0
	v_mov_b32_e32 v7, v0
	v_mov_b32_e32 v8, v0
	v_mov_b32_e32 v9, v0
	v_mov_b32_e32 v10, v0
	v_mov_b32_e32 v11, v0
	v_mov_b32_e32 v12, v0
	v_mov_b32_e32 v13, v0
	v_mov_b32_e32 v14, v0
	v_mov_b32_e32 v15, v0
	v_mov_b32_e32 v16, v0
	v_mov_b32_e32 v17, v0
	v_mov_b32_e32 v18, v0
	v_mov_b32_e32 v19, v0
	v_mov_b32_e32 v20, v0
	v_mov_b32_e32 v21, v0
	v_mov_b32_e32 v22, v0
	v_mov_b32_e32 v23, v0
	v_mov_b32_e32 v24, v0
	v_mov_b32_e32 v25, v0
	v_mov_b32_e32 v26, v0
	v_mov_b32_e32 v27, v0
	v_mov_b32_e32 v28, v0
	v_mov_b32_e32 v29, v0
	v_mov_b32_e32 v30, v0
	v_mov_b32_e32 v31, v0
	v_mov_b32_e32 v32, v0
	v_mov_b32_e32 v33, v0
	v_mov_b32_e32 v34, v0
	v_mov_b32_e32 v35, v0
	v_mov_b32_e32 v36, v0
	v_mov_b32_e32 v37, v0
	v_mov_b32_e32 v38, v0
	v_mov_b32_e32 v39, v0
	v_mov_b32_e32 v40, v0
	v_mov_b32_e32 v41, v0
	v_mov_b32_e32 v42, v0
	v_mov_b32_e32 v43, v0
	v_mov_b32_e32 v44, v0
	v_mov_b32_e32 v45, v0
	v_mov_b32_e32 v46, v0
	v_mov_b32_e32 v47, v0
	v_mov_b32_e32 v48, v0
	v_mov_b32_e32 v49, v0
	v_mov_b32_e32 v50, v0
	v_mov_b32_e32 v51, v0
	v_mov_b32_e32 v52, v0
	v_mov_b32_e32 v53, v0
	v_mov_b32_e32 v54, v0
	v_mov_b32_e32 v55, v0
	v_mov_b32_e32 v56, v0
	v_mov_b32_e32 v57, v0
	v_mov_b32_e32 v58, v0
	v_mov_b32_e32 v59, v0
	v_mov_b32_e32 v60, v0
	v_mov_b32_e32 v61, v0
	v_mov_b32_e32 v62, v0
	v_mov_b32_e32 v63, v0
	s_mov_b64 vcc, -1
	s_branch .Lfws_302

; DEV int stage_next(int s) { return (s == 2 * GS_STAGE) ? 0 : s + GS_STAGE; }
; template <int WAIT0>
; DEV void gk_main(f32x16 (&acc)[2][2], const GTile& t, int s0) {
;     ...
;   for (int kt = 0; kt < nk - 2; ++kt) {
;     GK_DMA(std_, kt + 2);
;     GK_COMPUTE(stc);
;     vm_wait_bar<6>();
;     stc = stage_next(stc); std_ = stage_next(std_);
;   }
;   GK_COMPUTE(stc);
;   vm_wait_bar<0>();
;   stc = stage_next(stc);
;   GK_COMPUTE(stc);
;   vm_wait_bar<0>();
.Lfwb_302:
	s_cselect_b32 s3, s16, 0
	s_add_u32 s10, s10, 0x80
	s_addc_u32 s11, s11, 0
	v_mfma_f32_32x32x16_bf16 v[32:47], v[244:247], v[240:243], v[32:47]
	s_cmpk_lg_i32 s10, 0x700
	v_mfma_f32_32x32x16_bf16 v[16:31], v[248:251], v[236:239], v[16:31]
	v_mfma_f32_32x32x16_bf16 v[0:15], v[248:251], v[240:243], v[0:15]
	s_cbranch_scc1 .LBB0_302
	s_add_i32 s1, s0, 0
	v_add_u32_e32 v87, s1, v86
	ds_read_b128 v[66:69], v87 offset:16384
	v_add_u32_e32 v74, s1, v85
	ds_read_b128 v[70:73], v74
	ds_read_b128 v[74:77], v74 offset:4096
	s_waitcnt lgkmcnt(0)
	v_mfma_f32_32x32x16_bf16 v[48:63], v[66:69], v[70:73], v[48:63]
	v_mfma_f32_32x32x16_bf16 v[32:47], v[66:69], v[74:77], v[32:47]
	ds_read_b128 v[66:69], v87 offset:20480
	v_add_u32_e32 v87, s1, v84
	s_waitcnt lgkmcnt(0)
	v_mfma_f32_32x32x16_bf16 v[16:31], v[66:69], v[70:73], v[16:31]
	v_mfma_f32_32x32x16_bf16 v[0:15], v[66:69], v[74:77], v[0:15]
	ds_read_b128 v[66:69], v87 offset:16384
	v_add_u32_e32 v74, s1, v83
	ds_read_b128 v[70:73], v74
	ds_read_b128 v[74:77], v74 offset:4096
	s_waitcnt lgkmcnt(0)
	v_mfma_f32_32x32x16_bf16 v[48:63], v[66:69], v[70:73], v[48:63]
	v_mfma_f32_32x32x16_bf16 v[32:47], v[66:69], v[74:77], v[32:47]
	ds_read_b128 v[66:69], v87 offset:20480
	v_add_u32_e32 v87, s1, v82
	s_waitcnt lgkmcnt(0)
	v_mfma_f32_32x32x16_bf16 v[16:31], v[66:69], v[70:73], v[16:31]
	v_mfma_f32_32x32x16_bf16 v[0:15], v[66:69], v[74:77], v[0:15]
	ds_read_b128 v[66:69], v87 offset:16384
	v_add_u32_e32 v74, s1, v81
	ds_read_b128 v[70:73], v74
	ds_read_b128 v[74:77], v74 offset:4096
	s_waitcnt lgkmcnt(0)
	v_mfma_f32_32x32x16_bf16 v[48:63], v[66:69], v[70:73], v[48:63]
	v_mfma_f32_32x32x16_bf16 v[32:47], v[66:69], v[74:77], v[32:47]
	ds_read_b128 v[66:69], v87 offset:20480
	v_add_u32_e32 v87, s1, v80
	s_waitcnt lgkmcnt(0)
	v_mfma_f32_32x32x16_bf16 v[16:31], v[66:69], v[70:73], v[16:31]
	v_mfma_f32_32x32x16_bf16 v[0:15], v[66:69], v[74:77], v[0:15]
	ds_read_b128 v[66:69], v87 offset:16384
	v_add_u32_e32 v74, s1, v79
	ds_read_b128 v[70:73], v74
	ds_read_b128 v[74:77], v74 offset:4096
	s_add_i32 s1, s0, 0xc000
	s_cmp_lg_u32 s0, 0x18000
	s_cselect_b32 s0, s1, 0
	s_waitcnt lgkmcnt(0)
	v_mfma_f32_32x32x16_bf16 v[48:63], v[66:69], v[70:73], v[48:63]
	s_add_i32 s0, s0, 0
	v_add_u32_e32 v86, s0, v86
	v_add_u32_e32 v84, s0, v84
	v_add_u32_e32 v82, s0, v82
	v_add_u32_e32 v80, s0, v80
	v_mfma_f32_32x32x16_bf16 v[32:47], v[66:69], v[74:77], v[32:47]
	ds_read_b128 v[66:69], v87 offset:20480
	s_waitcnt vmcnt(0) lgkmcnt(0)
	s_barrier
	s_waitcnt lgkmcnt(0)
	v_mfma_f32_32x32x16_bf16 v[16:31], v[66:69], v[70:73], v[16:31]
	v_mfma_f32_32x32x16_bf16 v[0:15], v[66:69], v[74:77], v[0:15]
	ds_read_b128 v[66:69], v86 offset:16384
	v_add_u32_e32 v74, s0, v85
	ds_read_b128 v[70:73], v74
	ds_read_b128 v[74:77], v74 offset:4096
	s_waitcnt lgkmcnt(0)
	v_mfma_f32_32x32x16_bf16 v[48:63], v[66:69], v[70:73], v[48:63]
	v_mfma_f32_32x32x16_bf16 v[32:47], v[66:69], v[74:77], v[32:47]
	ds_read_b128 v[66:69], v86 offset:20480
	s_waitcnt lgkmcnt(0)
	v_mfma_f32_32x32x16_bf16 v[16:31], v[66:69], v[70:73], v[16:31]
	v_mfma_f32_32x32x16_bf16 v[0:15], v[66:69], v[74:77], v[0:15]
	ds_read_b128 v[66:69], v84 offset:16384
	v_add_u32_e32 v74, s0, v83
	ds_read_b128 v[70:73], v74
	ds_read_b128 v[74:77], v74 offset:4096
	s_waitcnt lgkmcnt(0)
	v_mfma_f32_32x32x16_bf16 v[48:63], v[66:69], v[70:73], v[48:63]
	v_mfma_f32_32x32x16_bf16 v[32:47], v[66:69], v[74:77], v[32:47]
	ds_read_b128 v[66:69], v84 offset:20480
	s_waitcnt lgkmcnt(0)
	v_mfma_f32_32x32x16_bf16 v[16:31], v[66:69], v[70:73], v[16:31]
	v_mfma_f32_32x32x16_bf16 v[0:15], v[66:69], v[74:77], v[0:15]
	ds_read_b128 v[66:69], v82 offset:16384
	v_add_u32_e32 v74, s0, v81
	ds_read_b128 v[70:73], v74
	ds_read_b128 v[74:77], v74 offset:4096
	s_waitcnt lgkmcnt(0)
	v_mfma_f32_32x32x16_bf16 v[48:63], v[66:69], v[70:73], v[48:63]
	v_mfma_f32_32x32x16_bf16 v[32:47], v[66:69], v[74:77], v[32:47]
	ds_read_b128 v[66:69], v82 offset:20480
	s_waitcnt lgkmcnt(0)
	v_mfma_f32_32x32x16_bf16 v[16:31], v[66:69], v[70:73], v[16:31]
	v_mfma_f32_32x32x16_bf16 v[0:15], v[66:69], v[74:77], v[0:15]
	ds_read_b128 v[66:69], v80 offset:16384
	v_add_u32_e32 v74, s0, v79
	ds_read_b128 v[70:73], v74
	ds_read_b128 v[74:77], v74 offset:4096
	s_waitcnt lgkmcnt(0)
	v_mfma_f32_32x32x16_bf16 v[48:63], v[66:69], v[70:73], v[48:63]
	v_mfma_f32_32x32x16_bf16 v[32:47], v[66:69], v[74:77], v[32:47]
	ds_read_b128 v[66:69], v80 offset:20480
	s_waitcnt vmcnt(0) lgkmcnt(0)
	s_barrier
	s_waitcnt lgkmcnt(0)
	v_mfma_f32_32x32x16_bf16 v[16:31], v[66:69], v[70:73], v[16:31]
	v_mfma_f32_32x32x16_bf16 v[0:15], v[66:69], v[74:77], v[0:15]

; DEV int tid_l() { int t = threadIdx.x; asm volatile("" : "+v"(t)); return t; }
; DEV int stage_next(int s) { return (s == 2 * GS_STAGE) ? 0 : s + GS_STAGE; }
; DEV void gk_issue2(const GTile& t, int s0) {
;   const int tid = tid_l(), lane = tid & 63, wid = __builtin_amdgcn_readfirstlane(tid >> 6);
;   GK_SRC(t)
;   asm volatile("" ::: "memory");
;   GK_DMA(s0, 0);
;   GK_DMA(stage_next(s0), 1);
;   asm volatile("" ::: "memory");
; }
; template <int WAIT0>
; DEV void gk_main(f32x16 (&acc)[2][2], const GTile& t, int s0) {
;   const int tid = tid_l(), lane = tid & 63, wid = __builtin_amdgcn_readfirstlane(tid >> 6), wm = wid & 1, wn = wid >> 1, l32 = lane & 31, hi = lane >> 5;
;   GK_SRC(t)
;   const int sw = (l32 >> 1) & 7;
;   int xk[4], wk[4];
; #pragma unroll
;   for (int ks = 0; ks < 4; ++ks) { const int ko = ((2 * ks + hi) ^ sw) << 4; xk[ks] = GS_A + (64 * wm + l32) * 128 + ko; wk[ks] = GS_B + (64 * wn + l32) * 128 + ko; }
;   const int nk = t.K >> 6;
;     ...
;   vm_wait_bar<WAIT0>();
;   int stc = s0, std_ = stage_next(stage_next(s0));
.LBB0_405:
	s_and_b64 vcc, exec, s[8:9]
	s_cbranch_vccz .LBB0_409
	s_nop 9
	v_mov_b32_e32 v0, v176
	s_add_i32 s8, s18, 0xc000
	v_readfirstlane_b32 s2, v0
	v_and_b32_e32 v1, 31, v0
	s_ashr_i32 s3, s2, 6
	v_and_or_b32 v7, s2, 64, v1
	s_lshr_b32 s2, s2, 1
	s_and_b32 s2, s2, 0x1ffffc0
	v_bfe_u32 v2, v0, 3, 3
	v_or_b32_e32 v1, s2, v1
	s_lshl_b32 s2, s3, 10
	v_lshl_or_b32 v4, s3, 3, v2
	s_add_i32 s3, s2, 0
	s_lshr_b32 s2, s16, 6
	s_cmp_lg_u32 s18, 0x18000
	s_cselect_b32 s17, s8, 0
	s_add_i32 s8, s17, 0xc000
	v_lshrrev_b32_e32 v2, 1, v4
	v_bfe_u32 v3, v0, 5, 1
	v_lshrrev_b32_e32 v5, 1, v0
	v_bfe_u32 v6, v0, 1, 3
	s_cmp_lg_u32 s17, 0x18000
	v_bitop3_b32 v5, v3, v5, 7 bitop3:0x78
	v_bitop3_b32 v8, v3, v6, 2 bitop3:0x36
	v_bitop3_b32 v9, v3, v6, 4 bitop3:0x36
	v_bitop3_b32 v3, v3, v6, 6 bitop3:0x36
	s_cselect_b32 s8, s8, 0
	s_add_i32 s9, s2, -2
	v_bitop3_b32 v0, v2, 7, v0 bitop3:0x48
	v_lshlrev_b32_e32 v1, 7, v1
	v_lshlrev_b32_e32 v5, 4, v5
	v_lshlrev_b32_e32 v8, 4, v8
	v_lshlrev_b32_e32 v9, 4, v9
	v_lshlrev_b32_e32 v3, 4, v3
	v_lshlrev_b32_e32 v120, 4, v0
	s_add_u32 s10, s6, 0x100
	v_add_u32_e32 v0, 0xc0, v4
	v_lshlrev_b32_e32 v7, 7, v7
	v_or_b32_e32 v83, v1, v5
	v_or_b32_e32 v81, v1, v8
	v_or_b32_e32 v79, v1, v9
	v_or_b32_e32 v77, v1, v3
	s_addc_u32 s11, s7, 0
	v_ashrrev_i32_e32 v1, 31, v0
	v_or_b32_e32 v76, v3, v7
	v_alignbit_b32 v3, v1, v0, 31
	v_lshlrev_b32_e32 v2, 1, v0
	v_mov_b64_e32 v[0:1], s[10:11]
	v_mad_u64_u32 v[64:65], s[10:11], v2, s16, v[0:1]
	v_mov_b32_e32 v2, v65
	v_mad_u64_u32 v[2:3], s[10:11], v3, s16, v[2:3]
	v_mov_b32_e32 v65, v2
	v_add_u32_e32 v2, 0x80, v4
	v_ashrrev_i32_e32 v3, 31, v2
	v_alignbit_b32 v3, v3, v2, 31
	v_lshlrev_b32_e32 v2, 1, v2
	v_mad_u64_u32 v[66:67], s[10:11], v2, s16, v[0:1]
	v_mov_b32_e32 v2, v67
	v_mad_u64_u32 v[2:3], s[10:11], v3, s16, v[2:3]
	v_add_u32_e32 v3, 64, v4
	v_lshlrev_b32_e32 v6, 1, v3
	v_or_b32_e32 v82, v5, v7
	v_ashrrev_i32_e32 v5, 31, v3
	v_mad_u64_u32 v[68:69], s[10:11], v6, s16, v[0:1]
	v_mov_b32_e32 v67, v2
	v_mov_b32_e32 v2, v69
	v_alignbit_b32 v5, v5, v3, 31
	v_or_b32_e32 v80, v8, v7
	v_or_b32_e32 v78, v9, v7
	v_mad_u64_u32 v[2:3], s[10:11], v5, s16, v[2:3]
	v_lshlrev_b32_e32 v7, 1, v4
	v_mov_b32_e32 v69, v2
	v_ashrrev_i32_e32 v2, 31, v4
	v_mad_u64_u32 v[70:71], s[10:11], v7, s16, v[0:1]
	v_mov_b32_e32 v0, v71
	v_alignbit_b32 v4, v2, v4, 31
	v_mad_u64_u32 v[0:1], s[10:11], v4, s16, v[0:1]
	s_add_u32 s10, s4, 0x100
	s_addc_u32 s11, s5, 0
	v_mov_b32_e32 v71, v0
	v_mov_b64_e32 v[0:1], s[10:11]
	v_mad_u64_u32 v[74:75], s[10:11], v7, s16, v[0:1]
	v_mad_u64_u32 v[72:73], s[10:11], v6, s16, v[0:1]
	v_mov_b32_e32 v0, v75
	s_waitcnt vmcnt(22) lgkmcnt(0)
	s_barrier
	v_mov_b32_e32 v2, v73
	v_mad_u64_u32 v[0:1], s[10:11], v4, s16, v[0:1]
	v_mad_u64_u32 v[2:3], s[10:11], v5, s16, v[2:3]
	v_mov_b32_e32 v75, v0
	v_mov_b32_e32 v0, 0
	v_mov_b32_e32 v73, v2
	s_mov_b32 s2, s18
	v_mov_b32_e32 v1, v0
	v_mov_b32_e32 v2, v0
	v_mov_b32_e32 v3, v0
	v_mov_b32_e32 v4, v0
	v_mov_b32_e32 v5, v0
	v_mov_b32_e32 v6, v0
	v_mov_b32_e32 v7, v0
	v_mov_b32_e32 v8, v0
	v_mov_b32_e32 v9, v0
	v_mov_b32_e32 v10, v0
	v_mov_b32_e32 v11, v0
	v_mov_b32_e32 v12, v0
	v_mov_b32_e32 v13, v0
	v_mov_b32_e32 v14, v0
	v_mov_b32_e32 v15, v0
	v_mov_b32_e32 v16, v0
	v_mov_b32_e32 v17, v0
	v_mov_b32_e32 v18, v0
	v_mov_b32_e32 v19, v0
	v_mov_b32_e32 v20, v0
	v_mov_b32_e32 v21, v0
	v_mov_b32_e32 v22, v0
	v_mov_b32_e32 v23, v0
	v_mov_b32_e32 v24, v0
	v_mov_b32_e32 v25, v0
	v_mov_b32_e32 v26, v0
	v_mov_b32_e32 v27, v0
	v_mov_b32_e32 v28, v0
	v_mov_b32_e32 v29, v0
	v_mov_b32_e32 v30, v0
	v_mov_b32_e32 v31, v0
	v_mov_b32_e32 v32, v0
	v_mov_b32_e32 v33, v0
	v_mov_b32_e32 v34, v0
	v_mov_b32_e32 v35, v0
	v_mov_b32_e32 v36, v0
	v_mov_b32_e32 v37, v0
	v_mov_b32_e32 v38, v0
	v_mov_b32_e32 v39, v0
	v_mov_b32_e32 v40, v0
	v_mov_b32_e32 v41, v0
	v_mov_b32_e32 v42, v0
	v_mov_b32_e32 v43, v0
	v_mov_b32_e32 v44, v0
	v_mov_b32_e32 v45, v0
	v_mov_b32_e32 v46, v0
	v_mov_b32_e32 v47, v0
	v_mov_b32_e32 v48, v0
	v_mov_b32_e32 v49, v0
	v_mov_b32_e32 v50, v0
	v_mov_b32_e32 v51, v0
	v_mov_b32_e32 v52, v0
	v_mov_b32_e32 v53, v0
	v_mov_b32_e32 v54, v0
	v_mov_b32_e32 v55, v0
	v_mov_b32_e32 v56, v0
	v_mov_b32_e32 v57, v0
	v_mov_b32_e32 v58, v0
	v_mov_b32_e32 v59, v0
	v_mov_b32_e32 v60, v0
	v_mov_b32_e32 v61, v0
	v_mov_b32_e32 v62, v0
	v_mov_b32_e32 v63, v0
	s_add_i32 s99, s2, 0
	v_add_u32_e32 v252, s99, v82
	v_add_u32_e32 v253, s99, v83
	ds_read_b128 v[84:87], v252
	ds_read_b128 v[88:91], v252 offset:4096
	ds_read_b128 v[92:95], v253 offset:16384
	ds_read_b128 v[96:99], v253 offset:20480
	s_mov_b64 vcc, -1
	s_branch .Lfws_407
.Lfw_407:
	s_waitcnt vmcnt(22) lgkmcnt(0)
	s_barrier
	s_mov_b64 vcc, 0
	s_branch .Lfwb_407
; DEV int stage_next(int s) { return (s == 2 * GS_STAGE) ? 0 : s + GS_STAGE; }
; template <int WAIT0>
; DEV void gk_main(f32x16 (&acc)[2][2], const GTile& t, int s0) {
;     ...
;   vm_wait_bar<WAIT0>();
;   int stc = s0, std_ = stage_next(stage_next(s0));
; #pragma nounroll
;   for (int kt = 0; kt < nk - 2; ++kt) {
;     GK_DMA(std_, kt + 2);
;     GK_COMPUTE(stc);
;     vm_wait_bar<6>();
;     stc = stage_next(stc); std_ = stage_next(std_);
;   }
.Lfws_407:
.LBB0_407:
	s_add_i32 s10, s3, s8
	s_mov_b32 s98, s10
	s_waitcnt lgkmcnt(0)
	v_add_u32_e32 v252, s99, v80
	v_add_u32_e32 v253, s99, v81
	ds_read_b128 v[236:239], v252
	ds_read_b128 v[240:243], v252 offset:4096
	ds_read_b128 v[244:247], v253 offset:16384
	ds_read_b128 v[248:251], v253 offset:20480
	v_mfma_f32_32x32x16_bf16 v[48:63], v[92:95], v[84:87], v[48:63]
	v_mfma_f32_32x32x16_bf16 v[32:47], v[92:95], v[88:91], v[32:47]
	s_mov_b32 m0, s98
	v_lshl_add_u64 v[254:255], v[74:75], 0, v[120:121]
	global_load_lds_dwordx4 v[254:255], off
	v_lshl_add_u64 v[74:75], v[74:75], 0, s[96:97]
	v_mfma_f32_32x32x16_bf16 v[16:31], v[96:99], v[84:87], v[16:31]
	v_mfma_f32_32x32x16_bf16 v[0:15], v[96:99], v[88:91], v[0:15]
	s_add_i32 m0, s98, 0x2000
	v_lshl_add_u64 v[254:255], v[72:73], 0, v[120:121]
	global_load_lds_dwordx4 v[254:255], off
	v_lshl_add_u64 v[72:73], v[72:73], 0, s[96:97]
	s_waitcnt lgkmcnt(0)
	v_add_u32_e32 v252, s99, v78
	v_add_u32_e32 v253, s99, v79
	ds_read_b128 v[84:87], v252
	ds_read_b128 v[88:91], v252 offset:4096
	ds_read_b128 v[92:95], v253 offset:16384
	ds_read_b128 v[96:99], v253 offset:20480
	v_mfma_f32_32x32x16_bf16 v[48:63], v[244:247], v[236:239], v[48:63]
	v_mfma_f32_32x32x16_bf16 v[32:47], v[244:247], v[240:243], v[32:47]
	s_add_i32 m0, s98, 0x4000
	v_lshl_add_u64 v[254:255], v[70:71], 0, v[120:121]
	global_load_lds_dwordx4 v[254:255], off
	v_lshl_add_u64 v[70:71], v[70:71], 0, s[96:97]
	v_mfma_f32_32x32x16_bf16 v[16:31], v[248:251], v[236:239], v[16:31]
	v_mfma_f32_32x32x16_bf16 v[0:15], v[248:251], v[240:243], v[0:15]
	s_add_i32 m0, s98, 0x6000
	v_lshl_add_u64 v[254:255], v[68:69], 0, v[120:121]
	global_load_lds_dwordx4 v[254:255], off
	v_lshl_add_u64 v[68:69], v[68:69], 0, s[96:97]
	s_waitcnt lgkmcnt(0)
	v_add_u32_e32 v252, s99, v76
	v_add_u32_e32 v253, s99, v77
	ds_read_b128 v[236:239], v252
	ds_read_b128 v[240:243], v252 offset:4096
	ds_read_b128 v[244:247], v253 offset:16384
	ds_read_b128 v[248:251], v253 offset:20480
	v_mfma_f32_32x32x16_bf16 v[48:63], v[92:95], v[84:87], v[48:63]
	v_mfma_f32_32x32x16_bf16 v[32:47], v[92:95], v[88:91], v[32:47]
	s_add_i32 m0, s98, 0x8000
	v_lshl_add_u64 v[254:255], v[66:67], 0, v[120:121]
	global_load_lds_dwordx4 v[254:255], off
	v_lshl_add_u64 v[66:67], v[66:67], 0, s[96:97]
	v_mfma_f32_32x32x16_bf16 v[16:31], v[96:99], v[84:87], v[16:31]
	v_mfma_f32_32x32x16_bf16 v[0:15], v[96:99], v[88:91], v[0:15]
	s_add_i32 m0, s98, 0xa000
	v_lshl_add_u64 v[254:255], v[64:65], 0, v[120:121]
	global_load_lds_dwordx4 v[254:255], off
	v_lshl_add_u64 v[64:65], v[64:65], 0, s[96:97]
	s_add_i32 s10, s2, 0xc000
	s_cmp_lg_u32 s2, 0x18000
	s_cselect_b32 s2, s10, 0
	s_waitcnt lgkmcnt(0)
	v_mfma_f32_32x32x16_bf16 v[48:63], v[244:247], v[236:239], v[48:63]
	s_add_i32 s10, s8, 0xc000
	s_cbranch_vccnz .Lfw_407
	s_waitcnt vmcnt(6) lgkmcnt(0)
	s_barrier
; DEV int stage_next(int s) { return (s == 2 * GS_STAGE) ? 0 : s + GS_STAGE; }
; template <int WAIT0>
; DEV void gk_main(f32x16 (&acc)[2][2], const GTile& t, int s0) {
;     ...
;   for (int kt = 0; kt < nk - 2; ++kt) {
;     GK_DMA(std_, kt + 2);
;     GK_COMPUTE(stc);
;     vm_wait_bar<6>();
;     stc = stage_next(stc); std_ = stage_next(std_);
;   }
;   GK_COMPUTE(stc);
;   vm_wait_bar<0>();
;   stc = stage_next(stc);
;   GK_COMPUTE(stc);
;   vm_wait_bar<0>();
.Lfwb_407:
	s_cmp_lg_u32 s8, 0x18000
	s_cselect_b32 s8, s10, 0
	s_add_i32 s9, s9, -1
	s_add_i32 s99, s2, 0
	v_add_u32_e32 v252, s99, v82
	v_add_u32_e32 v253, s99, v83
	ds_read_b128 v[84:87], v252
	ds_read_b128 v[88:91], v252 offset:4096
	ds_read_b128 v[92:95], v253 offset:16384
	ds_read_b128 v[96:99], v253 offset:20480
	v_mfma_f32_32x32x16_bf16 v[32:47], v[244:247], v[240:243], v[32:47]
	s_cmp_lg_u32 s9, 0
	v_mfma_f32_32x32x16_bf16 v[16:31], v[248:251], v[236:239], v[16:31]
	v_mfma_f32_32x32x16_bf16 v[0:15], v[248:251], v[240:243], v[0:15]
	s_cbranch_scc1 .LBB0_407
	s_waitcnt lgkmcnt(0)
	s_add_i32 s3, s2, 0
	v_add_u32_e32 v84, s3, v83
	ds_read_b128 v[64:67], v84 offset:16384
	v_add_u32_e32 v72, s3, v82
	ds_read_b128 v[68:71], v72
	ds_read_b128 v[72:75], v72 offset:4096
	s_waitcnt lgkmcnt(0)
	v_mfma_f32_32x32x16_bf16 v[48:63], v[64:67], v[68:71], v[48:63]
	v_mfma_f32_32x32x16_bf16 v[32:47], v[64:67], v[72:75], v[32:47]
	ds_read_b128 v[64:67], v84 offset:20480
	v_add_u32_e32 v84, s3, v81
	s_waitcnt lgkmcnt(0)
	v_mfma_f32_32x32x16_bf16 v[16:31], v[64:67], v[68:71], v[16:31]
	v_mfma_f32_32x32x16_bf16 v[0:15], v[64:67], v[72:75], v[0:15]
	ds_read_b128 v[64:67], v84 offset:16384
	v_add_u32_e32 v72, s3, v80
	ds_read_b128 v[68:71], v72
	ds_read_b128 v[72:75], v72 offset:4096
	s_waitcnt lgkmcnt(0)
	v_mfma_f32_32x32x16_bf16 v[48:63], v[64:67], v[68:71], v[48:63]
	v_mfma_f32_32x32x16_bf16 v[32:47], v[64:67], v[72:75], v[32:47]
	ds_read_b128 v[64:67], v84 offset:20480
	v_add_u32_e32 v84, s3, v79
	s_waitcnt lgkmcnt(0)
	v_mfma_f32_32x32x16_bf16 v[16:31], v[64:67], v[68:71], v[16:31]
	v_mfma_f32_32x32x16_bf16 v[0:15], v[64:67], v[72:75], v[0:15]
	ds_read_b128 v[64:67], v84 offset:16384
	v_add_u32_e32 v72, s3, v78
	ds_read_b128 v[68:71], v72
	ds_read_b128 v[72:75], v72 offset:4096
	s_waitcnt lgkmcnt(0)
	v_mfma_f32_32x32x16_bf16 v[48:63], v[64:67], v[68:71], v[48:63]
	v_mfma_f32_32x32x16_bf16 v[32:47], v[64:67], v[72:75], v[32:47]
	ds_read_b128 v[64:67], v84 offset:20480
	v_add_u32_e32 v84, s3, v77
	s_waitcnt lgkmcnt(0)
	v_mfma_f32_32x32x16_bf16 v[16:31], v[64:67], v[68:71], v[16:31]
	v_mfma_f32_32x32x16_bf16 v[0:15], v[64:67], v[72:75], v[0:15]
	ds_read_b128 v[64:67], v84 offset:16384
	v_add_u32_e32 v72, s3, v76
	ds_read_b128 v[68:71], v72
	ds_read_b128 v[72:75], v72 offset:4096
	s_add_i32 s3, s2, 0xc000
	s_cmp_lg_u32 s2, 0x18000
	s_cselect_b32 s2, s3, 0
	s_waitcnt lgkmcnt(0)
	v_mfma_f32_32x32x16_bf16 v[48:63], v[64:67], v[68:71], v[48:63]
	s_add_i32 s2, s2, 0
	v_add_u32_e32 v83, s2, v83
	v_add_u32_e32 v81, s2, v81
	v_add_u32_e32 v79, s2, v79
	v_add_u32_e32 v77, s2, v77
	v_mfma_f32_32x32x16_bf16 v[32:47], v[64:67], v[72:75], v[32:47]
	ds_read_b128 v[64:67], v84 offset:20480
	s_waitcnt vmcnt(0) lgkmcnt(0)
	s_barrier
	s_waitcnt lgkmcnt(0)
	v_mfma_f32_32x32x16_bf16 v[16:31], v[64:67], v[68:71], v[16:31]
	v_mfma_f32_32x32x16_bf16 v[0:15], v[64:67], v[72:75], v[0:15]
	ds_read_b128 v[64:67], v83 offset:16384
	v_add_u32_e32 v72, s2, v82
	ds_read_b128 v[68:71], v72
	ds_read_b128 v[72:75], v72 offset:4096
	s_waitcnt lgkmcnt(0)
	v_mfma_f32_32x32x16_bf16 v[48:63], v[64:67], v[68:71], v[48:63]
	v_mfma_f32_32x32x16_bf16 v[32:47], v[64:67], v[72:75], v[32:47]
	ds_read_b128 v[64:67], v83 offset:20480
	s_waitcnt lgkmcnt(0)
	v_mfma_f32_32x32x16_bf16 v[16:31], v[64:67], v[68:71], v[16:31]
	v_mfma_f32_32x32x16_bf16 v[0:15], v[64:67], v[72:75], v[0:15]
	ds_read_b128 v[64:67], v81 offset:16384
	v_add_u32_e32 v72, s2, v80
	ds_read_b128 v[68:71], v72
	ds_read_b128 v[72:75], v72 offset:4096
	s_waitcnt lgkmcnt(0)
	v_mfma_f32_32x32x16_bf16 v[48:63], v[64:67], v[68:71], v[48:63]
	v_mfma_f32_32x32x16_bf16 v[32:47], v[64:67], v[72:75], v[32:47]
	ds_read_b128 v[64:67], v81 offset:20480
	s_waitcnt lgkmcnt(0)
	v_mfma_f32_32x32x16_bf16 v[16:31], v[64:67], v[68:71], v[16:31]
	v_mfma_f32_32x32x16_bf16 v[0:15], v[64:67], v[72:75], v[0:15]
	ds_read_b128 v[64:67], v79 offset:16384
	v_add_u32_e32 v72, s2, v78
	ds_read_b128 v[68:71], v72
	ds_read_b128 v[72:75], v72 offset:4096
	s_waitcnt lgkmcnt(0)
	v_mfma_f32_32x32x16_bf16 v[48:63], v[64:67], v[68:71], v[48:63]
	v_mfma_f32_32x32x16_bf16 v[32:47], v[64:67], v[72:75], v[32:47]
	ds_read_b128 v[64:67], v79 offset:20480
	s_waitcnt lgkmcnt(0)
	v_mfma_f32_32x32x16_bf16 v[16:31], v[64:67], v[68:71], v[16:31]
	v_mfma_f32_32x32x16_bf16 v[0:15], v[64:67], v[72:75], v[0:15]
	ds_read_b128 v[64:67], v77 offset:16384
	v_add_u32_e32 v72, s2, v76
	ds_read_b128 v[68:71], v72
	ds_read_b128 v[72:75], v72 offset:4096
	s_waitcnt lgkmcnt(0)
	v_mfma_f32_32x32x16_bf16 v[48:63], v[64:67], v[68:71], v[48:63]
	v_mfma_f32_32x32x16_bf16 v[32:47], v[64:67], v[72:75], v[32:47]
	ds_read_b128 v[64:67], v77 offset:20480
	s_waitcnt vmcnt(0) lgkmcnt(0)
	s_barrier
	s_waitcnt lgkmcnt(0)
	v_mfma_f32_32x32x16_bf16 v[16:31], v[64:67], v[68:71], v[16:31]
	v_mfma_f32_32x32x16_bf16 v[0:15], v[64:67], v[72:75], v[0:15]

; DEV int tid_l() { int t = threadIdx.x; asm volatile("" : "+v"(t)); return t; }
; DEV int stage_next(int s) { return (s == 2 * GS_STAGE) ? 0 : s + GS_STAGE; }
; template <int WAIT0>
; DEV void gk_main(f32x16 (&acc)[2][2], const GTile& t, int s0) {
;   const int tid = tid_l(), lane = tid & 63, wid = __builtin_amdgcn_readfirstlane(tid >> 6), wm = wid & 1, wn = wid >> 1, l32 = lane & 31, hi = lane >> 5;
;   GK_SRC(t)
;   const int sw = (l32 >> 1) & 7;
;   int xk[4], wk[4];
; #pragma unroll
;   for (int ks = 0; ks < 4; ++ks) { const int ko = ((2 * ks + hi) ^ sw) << 4; xk[ks] = GS_A + (64 * wm + l32) * 128 + ko; wk[ks] = GS_B + (64 * wn + l32) * 128 + ko; }
;   const int nk = t.K >> 6;
;     ...
;   vm_wait_bar<WAIT0>();
;   int stc = s0, std_ = stage_next(stage_next(s0));
.LBB0_424:
	s_cmp_lg_u32 s2, 0
	s_cbranch_scc0 .LBB0_435
	s_bitcmp0_b32 s2, 0
	s_mov_b64 s[6:7], -1
	s_cbranch_scc1 .LBB0_429
	v_mov_b32_e32 v1, v176
	s_waitcnt vmcnt(14) lgkmcnt(0)
	s_barrier
	v_readfirstlane_b32 s3, v1
	s_ashr_i32 s6, s3, 6
	v_bfe_u32 v0, v1, 3, 3
	v_and_b32_e32 v2, 31, v1
	v_lshl_or_b32 v0, s6, 3, v0
	v_lshrrev_b32_e32 v3, 1, v0
	v_and_or_b32 v6, s3, 64, v2
	s_lshr_b32 s3, s3, 1
	v_xor_b32_e32 v3, v3, v1
	s_and_b32 s3, s3, 0x1ffffc0
	v_lshlrev_b32_e32 v3, 4, v3
	v_or_b32_e32 v2, s3, v2
	s_lshl_b32 s3, s6, 10
	v_and_b32_e32 v4, 0x70, v3
	v_bfe_u32 v3, v1, 5, 1
	v_lshrrev_b32_e32 v5, 1, v1
	v_bfe_u32 v1, v1, 1, 3
	s_add_i32 s10, s3, 0
	s_add_i32 s3, s9, 0xc000
	v_bitop3_b32 v5, v3, v5, 7 bitop3:0x78
	v_bitop3_b32 v7, v3, v1, 2 bitop3:0x36
	v_bitop3_b32 v8, v3, v1, 4 bitop3:0x36
	v_bitop3_b32 v1, v3, v1, 6 bitop3:0x36
	s_cmp_lg_u32 s9, 0x18000
	v_lshlrev_b32_e32 v2, 7, v2
	v_lshlrev_b32_e32 v5, 4, v5
	v_lshlrev_b32_e32 v7, 4, v7
	v_lshlrev_b32_e32 v8, 4, v8
	v_lshlrev_b32_e32 v1, 4, v1
	s_cselect_b32 s8, s3, 0
	s_add_i32 s3, s8, 0xc000
	v_or_b32_e32 v83, v2, v5
	v_or_b32_e32 v81, v2, v7
	v_or_b32_e32 v79, v2, v8
	v_or_b32_e32 v77, v2, v1
	v_add_u32_e32 v2, 0xc0, v0
	s_cmp_lg_u32 s8, 0x18000
	v_ashrrev_i32_e32 v3, 31, v2
	s_cselect_b32 s11, s3, 0
	s_add_u32 s6, s4, 0x100
	v_lshlrev_b64 v[2:3], 11, v[2:3]
	s_addc_u32 s7, s5, 0
	v_or_b32_e32 v2, v2, v4
	v_lshl_add_u64 v[64:65], s[6:7], 0, v[2:3]
	v_add_u32_e32 v2, 0x80, v0
	v_ashrrev_i32_e32 v3, 31, v2
	v_lshlrev_b64 v[2:3], 11, v[2:3]
	v_or_b32_e32 v2, v2, v4
	v_lshlrev_b32_e32 v6, 7, v6
	v_lshl_add_u64 v[66:67], s[6:7], 0, v[2:3]
	v_add_u32_e32 v2, 64, v0
	v_or_b32_e32 v76, v1, v6
	v_ashrrev_i32_e32 v3, 31, v2
	v_ashrrev_i32_e32 v1, 31, v0
	v_lshlrev_b64 v[2:3], 11, v[2:3]
	v_lshlrev_b64 v[0:1], 11, v[0:1]
	v_or_b32_e32 v2, v2, v4
	v_or_b32_e32 v0, v0, v4
	v_lshl_add_u64 v[68:69], s[6:7], 0, v[2:3]
	v_lshl_add_u64 v[70:71], s[6:7], 0, v[0:1]
	v_readlane_b32 s6, v231, 15
	v_readlane_b32 s7, v231, 16
	v_or_b32_e32 v82, v5, v6
	v_or_b32_e32 v80, v7, v6
	v_lshl_add_u64 v[74:75], s[6:7], 0, v[0:1]
	v_mov_b32_e32 v0, 0
	v_or_b32_e32 v78, v8, v6
	v_lshl_add_u64 v[72:73], s[6:7], 0, v[2:3]
	s_mov_b64 s[6:7], 0
	s_mov_b32 s3, s9
	v_mov_b32_e32 v1, v0
	v_mov_b32_e32 v2, v0
	v_mov_b32_e32 v3, v0
	v_mov_b32_e32 v4, v0
	v_mov_b32_e32 v5, v0
	v_mov_b32_e32 v6, v0
	v_mov_b32_e32 v7, v0
	v_mov_b32_e32 v8, v0
	v_mov_b32_e32 v9, v0
	v_mov_b32_e32 v10, v0
	v_mov_b32_e32 v11, v0
	v_mov_b32_e32 v12, v0
	v_mov_b32_e32 v13, v0
	v_mov_b32_e32 v14, v0
	v_mov_b32_e32 v15, v0
	v_mov_b32_e32 v32, v0
	v_mov_b32_e32 v33, v0
	v_mov_b32_e32 v34, v0
	v_mov_b32_e32 v35, v0
	v_mov_b32_e32 v36, v0
	v_mov_b32_e32 v37, v0
	v_mov_b32_e32 v38, v0
	v_mov_b32_e32 v39, v0
	v_mov_b32_e32 v40, v0
	v_mov_b32_e32 v41, v0
	v_mov_b32_e32 v42, v0
	v_mov_b32_e32 v43, v0
	v_mov_b32_e32 v44, v0
	v_mov_b32_e32 v45, v0
	v_mov_b32_e32 v46, v0
	v_mov_b32_e32 v47, v0
	v_mov_b32_e32 v16, v0
	v_mov_b32_e32 v17, v0
	v_mov_b32_e32 v18, v0
	v_mov_b32_e32 v19, v0
	v_mov_b32_e32 v20, v0
	v_mov_b32_e32 v21, v0
	v_mov_b32_e32 v22, v0
	v_mov_b32_e32 v23, v0
	v_mov_b32_e32 v24, v0
	v_mov_b32_e32 v25, v0
	v_mov_b32_e32 v26, v0
	v_mov_b32_e32 v27, v0
	v_mov_b32_e32 v28, v0
	v_mov_b32_e32 v29, v0
	v_mov_b32_e32 v30, v0
	v_mov_b32_e32 v31, v0
	v_mov_b32_e32 v48, v0
	v_mov_b32_e32 v49, v0
	v_mov_b32_e32 v50, v0
	v_mov_b32_e32 v51, v0
	v_mov_b32_e32 v52, v0
	v_mov_b32_e32 v53, v0
	v_mov_b32_e32 v54, v0
	v_mov_b32_e32 v55, v0
	v_mov_b32_e32 v56, v0
	v_mov_b32_e32 v57, v0
	v_mov_b32_e32 v58, v0
	v_mov_b32_e32 v59, v0
	v_mov_b32_e32 v60, v0
	v_mov_b32_e32 v61, v0
	v_mov_b32_e32 v62, v0
	v_mov_b32_e32 v63, v0
	s_add_i32 s99, s3, 0
	v_add_u32_e32 v252, s99, v82
	v_add_u32_e32 v253, s99, v83
	ds_read_b128 v[84:87], v252
	ds_read_b128 v[88:91], v252 offset:4096
	ds_read_b128 v[92:95], v253 offset:16384
	ds_read_b128 v[96:99], v253 offset:20480
	s_mov_b64 vcc, -1
	s_branch .Lfws_427

; DEV int stage_next(int s) { return (s == 2 * GS_STAGE) ? 0 : s + GS_STAGE; }
; template <int WAIT0>
; DEV void gk_main(f32x16 (&acc)[2][2], const GTile& t, int s0) {
;     ...
;   for (int kt = 0; kt < nk - 2; ++kt) {
;     GK_DMA(std_, kt + 2);
;     GK_COMPUTE(stc);
;     vm_wait_bar<6>();
;     stc = stage_next(stc); std_ = stage_next(std_);
;   }
;   GK_COMPUTE(stc);
;   vm_wait_bar<0>();
;   stc = stage_next(stc);
;   GK_COMPUTE(stc);
;   vm_wait_bar<0>();
.Lfws_427:
.LBB0_427:
	s_add_i32 s12, s10, s11
	s_mov_b32 s98, s12
	s_mov_b64 s[100:101], s[6:7]
	s_waitcnt lgkmcnt(0)
	v_add_u32_e32 v252, s99, v80
	v_add_u32_e32 v253, s99, v81
	ds_read_b128 v[236:239], v252
	ds_read_b128 v[240:243], v252 offset:4096
	ds_read_b128 v[244:247], v253 offset:16384
	ds_read_b128 v[248:251], v253 offset:20480
	v_mfma_f32_32x32x16_bf16 v[48:63], v[92:95], v[84:87], v[48:63]
	v_mfma_f32_32x32x16_bf16 v[16:31], v[92:95], v[88:91], v[16:31]
	s_mov_b32 m0, s98
	v_lshl_add_u64 v[254:255], v[74:75], 0, s[100:101]
	global_load_lds_dwordx4 v[254:255], off
	v_mfma_f32_32x32x16_bf16 v[32:47], v[96:99], v[84:87], v[32:47]
	v_mfma_f32_32x32x16_bf16 v[0:15], v[96:99], v[88:91], v[0:15]
	s_add_i32 m0, s98, 0x2000
	v_lshl_add_u64 v[254:255], v[72:73], 0, s[100:101]
	global_load_lds_dwordx4 v[254:255], off
	s_waitcnt lgkmcnt(0)
	v_add_u32_e32 v252, s99, v78
	v_add_u32_e32 v253, s99, v79
	ds_read_b128 v[84:87], v252
	ds_read_b128 v[88:91], v252 offset:4096
	ds_read_b128 v[92:95], v253 offset:16384
	ds_read_b128 v[96:99], v253 offset:20480
	v_mfma_f32_32x32x16_bf16 v[48:63], v[244:247], v[236:239], v[48:63]
	v_mfma_f32_32x32x16_bf16 v[16:31], v[244:247], v[240:243], v[16:31]
	s_add_i32 m0, s98, 0x4000
	v_lshl_add_u64 v[254:255], v[70:71], 0, s[100:101]
	global_load_lds_dwordx4 v[254:255], off
	v_mfma_f32_32x32x16_bf16 v[32:47], v[248:251], v[236:239], v[32:47]
	v_mfma_f32_32x32x16_bf16 v[0:15], v[248:251], v[240:243], v[0:15]
	s_add_i32 m0, s98, 0x6000
	v_lshl_add_u64 v[254:255], v[68:69], 0, s[100:101]
	global_load_lds_dwordx4 v[254:255], off
	s_waitcnt lgkmcnt(0)
	v_add_u32_e32 v252, s99, v76
	v_add_u32_e32 v253, s99, v77
	ds_read_b128 v[236:239], v252
	ds_read_b128 v[240:243], v252 offset:4096
	ds_read_b128 v[244:247], v253 offset:16384
	ds_read_b128 v[248:251], v253 offset:20480
	v_mfma_f32_32x32x16_bf16 v[48:63], v[92:95], v[84:87], v[48:63]
	v_mfma_f32_32x32x16_bf16 v[16:31], v[92:95], v[88:91], v[16:31]
	s_add_i32 m0, s98, 0x8000
	v_lshl_add_u64 v[254:255], v[66:67], 0, s[100:101]
	global_load_lds_dwordx4 v[254:255], off
	v_mfma_f32_32x32x16_bf16 v[32:47], v[96:99], v[84:87], v[32:47]
	v_mfma_f32_32x32x16_bf16 v[0:15], v[96:99], v[88:91], v[0:15]
	s_add_i32 m0, s98, 0xa000
	v_lshl_add_u64 v[254:255], v[64:65], 0, s[100:101]
	global_load_lds_dwordx4 v[254:255], off
	s_add_i32 s12, s3, 0xc000
	s_cmp_lg_u32 s3, 0x18000
	s_cselect_b32 s3, s12, 0
	s_waitcnt lgkmcnt(0)
	v_mfma_f32_32x32x16_bf16 v[48:63], v[244:247], v[236:239], v[48:63]
	s_add_i32 s12, s11, 0xc000
	s_cmp_lg_u32 s11, 0x18000
	s_cbranch_vccnz .Lfw_427
	s_waitcnt vmcnt(6) lgkmcnt(0)
	s_barrier
.Lfwb_427:
	s_cselect_b32 s11, s12, 0
	s_add_u32 s6, s6, 0x80
	s_add_i32 s99, s3, 0
	v_add_u32_e32 v252, s99, v82
	v_add_u32_e32 v253, s99, v83
	ds_read_b128 v[84:87], v252
	ds_read_b128 v[88:91], v252 offset:4096
	ds_read_b128 v[92:95], v253 offset:16384
	ds_read_b128 v[96:99], v253 offset:20480
	v_mfma_f32_32x32x16_bf16 v[16:31], v[244:247], v[240:243], v[16:31]
	s_addc_u32 s7, s7, 0
	s_cmpk_lg_i32 s6, 0x700
	v_mfma_f32_32x32x16_bf16 v[32:47], v[248:251], v[236:239], v[32:47]
	v_mfma_f32_32x32x16_bf16 v[0:15], v[248:251], v[240:243], v[0:15]
	s_cbranch_scc1 .LBB0_427
	s_waitcnt lgkmcnt(0)
	s_add_i32 s6, s3, 0
	v_add_u32_e32 v84, s6, v83
	ds_read_b128 v[64:67], v84 offset:16384
	v_add_u32_e32 v72, s6, v82
	ds_read_b128 v[68:71], v72
	ds_read_b128 v[72:75], v72 offset:4096
	s_waitcnt lgkmcnt(0)
	v_mfma_f32_32x32x16_bf16 v[48:63], v[64:67], v[68:71], v[48:63]
	v_mfma_f32_32x32x16_bf16 v[16:31], v[64:67], v[72:75], v[16:31]
	ds_read_b128 v[64:67], v84 offset:20480
	v_add_u32_e32 v84, s6, v81
	s_waitcnt lgkmcnt(0)
	v_mfma_f32_32x32x16_bf16 v[32:47], v[64:67], v[68:71], v[32:47]
	v_mfma_f32_32x32x16_bf16 v[0:15], v[64:67], v[72:75], v[0:15]
	ds_read_b128 v[64:67], v84 offset:16384
	v_add_u32_e32 v72, s6, v80
	ds_read_b128 v[68:71], v72
	ds_read_b128 v[72:75], v72 offset:4096
	s_waitcnt lgkmcnt(0)
	v_mfma_f32_32x32x16_bf16 v[48:63], v[64:67], v[68:71], v[48:63]
	v_mfma_f32_32x32x16_bf16 v[16:31], v[64:67], v[72:75], v[16:31]
	ds_read_b128 v[64:67], v84 offset:20480
	v_add_u32_e32 v84, s6, v79
	s_waitcnt lgkmcnt(0)
	v_mfma_f32_32x32x16_bf16 v[32:47], v[64:67], v[68:71], v[32:47]
	v_mfma_f32_32x32x16_bf16 v[0:15], v[64:67], v[72:75], v[0:15]
	ds_read_b128 v[64:67], v84 offset:16384
	v_add_u32_e32 v72, s6, v78
	ds_read_b128 v[68:71], v72
	ds_read_b128 v[72:75], v72 offset:4096
	s_waitcnt lgkmcnt(0)
	v_mfma_f32_32x32x16_bf16 v[48:63], v[64:67], v[68:71], v[48:63]
	v_mfma_f32_32x32x16_bf16 v[16:31], v[64:67], v[72:75], v[16:31]
	ds_read_b128 v[64:67], v84 offset:20480
	v_add_u32_e32 v84, s6, v77
	s_waitcnt lgkmcnt(0)
	v_mfma_f32_32x32x16_bf16 v[32:47], v[64:67], v[68:71], v[32:47]
	v_mfma_f32_32x32x16_bf16 v[0:15], v[64:67], v[72:75], v[0:15]
	ds_read_b128 v[64:67], v84 offset:16384
	v_add_u32_e32 v72, s6, v76
	ds_read_b128 v[68:71], v72
	ds_read_b128 v[72:75], v72 offset:4096
	s_add_i32 s6, s3, 0xc000
	s_cmp_lg_u32 s3, 0x18000
	s_cselect_b32 s3, s6, 0
	s_waitcnt lgkmcnt(0)
	v_mfma_f32_32x32x16_bf16 v[48:63], v[64:67], v[68:71], v[48:63]
	s_add_i32 s3, s3, 0
	v_add_u32_e32 v83, s3, v83
	v_add_u32_e32 v81, s3, v81
	v_add_u32_e32 v79, s3, v79
	v_add_u32_e32 v77, s3, v77
	s_mov_b64 s[6:7], 0
	v_mfma_f32_32x32x16_bf16 v[16:31], v[64:67], v[72:75], v[16:31]
	ds_read_b128 v[64:67], v84 offset:20480
	s_waitcnt vmcnt(0) lgkmcnt(0)
	s_barrier
; DEV int tid_l() { int t = threadIdx.x; asm volatile("" : "+v"(t)); return t; }
; DEV int stage_next(int s) { return (s == 2 * GS_STAGE) ? 0 : s + GS_STAGE; }
; template <int WAIT0>
; DEV void gk_main(f32x16 (&acc)[2][2], const GTile& t, int s0) {
;   const int tid = tid_l(), lane = tid & 63, wid = __builtin_amdgcn_readfirstlane(tid >> 6), wm = wid & 1, wn = wid >> 1, l32 = lane & 31, hi = lane >> 5;
;   GK_SRC(t)
;   const int sw = (l32 >> 1) & 7;
;   int xk[4], wk[4];
; #pragma unroll
;   for (int ks = 0; ks < 4; ++ks) { const int ko = ((2 * ks + hi) ^ sw) << 4; xk[ks] = GS_A + (64 * wm + l32) * 128 + ko; wk[ks] = GS_B + (64 * wn + l32) * 128 + ko; }
;   const int nk = t.K >> 6;
;     ...
;   vm_wait_bar<WAIT0>();
;   int stc = s0, std_ = stage_next(stage_next(s0));
;     ...
;   GK_COMPUTE(stc);
;   vm_wait_bar<0>();
;   stc = stage_next(stc);
;   GK_COMPUTE(stc);
;   vm_wait_bar<0>();
	s_waitcnt lgkmcnt(0)
	v_mfma_f32_32x32x16_bf16 v[32:47], v[64:67], v[68:71], v[32:47]
	v_mfma_f32_32x32x16_bf16 v[0:15], v[64:67], v[72:75], v[0:15]
	ds_read_b128 v[64:67], v83 offset:16384
	v_add_u32_e32 v72, s3, v82
	ds_read_b128 v[68:71], v72
	ds_read_b128 v[72:75], v72 offset:4096
	s_waitcnt lgkmcnt(0)
	v_mfma_f32_32x32x16_bf16 v[48:63], v[64:67], v[68:71], v[48:63]
	v_mfma_f32_32x32x16_bf16 v[16:31], v[64:67], v[72:75], v[16:31]
	ds_read_b128 v[64:67], v83 offset:20480
	s_waitcnt lgkmcnt(0)
	v_mfma_f32_32x32x16_bf16 v[32:47], v[64:67], v[68:71], v[32:47]
	v_mfma_f32_32x32x16_bf16 v[0:15], v[64:67], v[72:75], v[0:15]
	ds_read_b128 v[64:67], v81 offset:16384
	v_add_u32_e32 v72, s3, v80
	ds_read_b128 v[68:71], v72
	ds_read_b128 v[72:75], v72 offset:4096
	s_waitcnt lgkmcnt(0)
	v_mfma_f32_32x32x16_bf16 v[48:63], v[64:67], v[68:71], v[48:63]
	v_mfma_f32_32x32x16_bf16 v[16:31], v[64:67], v[72:75], v[16:31]
	ds_read_b128 v[64:67], v81 offset:20480
	s_waitcnt lgkmcnt(0)
	v_mfma_f32_32x32x16_bf16 v[32:47], v[64:67], v[68:71], v[32:47]
	v_mfma_f32_32x32x16_bf16 v[0:15], v[64:67], v[72:75], v[0:15]
	ds_read_b128 v[64:67], v79 offset:16384
	v_add_u32_e32 v72, s3, v78
	ds_read_b128 v[68:71], v72
	ds_read_b128 v[72:75], v72 offset:4096
	s_waitcnt lgkmcnt(0)
	v_mfma_f32_32x32x16_bf16 v[48:63], v[64:67], v[68:71], v[48:63]
	v_mfma_f32_32x32x16_bf16 v[16:31], v[64:67], v[72:75], v[16:31]
	ds_read_b128 v[64:67], v79 offset:20480
	s_waitcnt lgkmcnt(0)
	v_mfma_f32_32x32x16_bf16 v[32:47], v[64:67], v[68:71], v[32:47]
	v_mfma_f32_32x32x16_bf16 v[0:15], v[64:67], v[72:75], v[0:15]
	ds_read_b128 v[64:67], v77 offset:16384
	v_add_u32_e32 v72, s3, v76
	ds_read_b128 v[68:71], v72
	ds_read_b128 v[72:75], v72 offset:4096
	s_waitcnt lgkmcnt(0)
	v_mfma_f32_32x32x16_bf16 v[48:63], v[64:67], v[68:71], v[48:63]
	v_mfma_f32_32x32x16_bf16 v[16:31], v[64:67], v[72:75], v[16:31]
	ds_read_b128 v[64:67], v77 offset:20480
	s_waitcnt vmcnt(0) lgkmcnt(0)
	s_barrier
	s_waitcnt lgkmcnt(0)
	v_mfma_f32_32x32x16_bf16 v[32:47], v[64:67], v[68:71], v[32:47]
	v_mfma_f32_32x32x16_bf16 v[0:15], v[64:67], v[72:75], v[0:15]
.LBB0_429:
	s_and_b64 vcc, exec, s[6:7]
	s_cbranch_vccz .LBB0_433
	s_nop 9
	v_mov_b32_e32 v1, v176
	s_waitcnt vmcnt(14) lgkmcnt(0)
	s_barrier
	v_readfirstlane_b32 s3, v1
	s_ashr_i32 s6, s3, 6
	v_bfe_u32 v0, v1, 3, 3
	v_and_b32_e32 v2, 31, v1
	v_lshl_or_b32 v0, s6, 3, v0
	v_lshrrev_b32_e32 v3, 1, v0
	v_and_or_b32 v6, s3, 64, v2
	s_lshr_b32 s3, s3, 1
	v_xor_b32_e32 v3, v3, v1
	s_and_b32 s3, s3, 0x1ffffc0
	v_lshlrev_b32_e32 v3, 4, v3
	v_or_b32_e32 v2, s3, v2
	s_lshl_b32 s3, s6, 10
	v_and_b32_e32 v4, 0x70, v3
	v_bfe_u32 v3, v1, 5, 1
	v_lshrrev_b32_e32 v5, 1, v1
	v_bfe_u32 v1, v1, 1, 3
	s_add_i32 s10, s3, 0
	s_add_i32 s3, s9, 0xc000
	v_bitop3_b32 v5, v3, v5, 7 bitop3:0x78
	v_bitop3_b32 v7, v3, v1, 2 bitop3:0x36
	v_bitop3_b32 v8, v3, v1, 4 bitop3:0x36
	v_bitop3_b32 v1, v3, v1, 6 bitop3:0x36
	s_cmp_lg_u32 s9, 0x18000
	v_lshlrev_b32_e32 v2, 7, v2
	v_lshlrev_b32_e32 v5, 4, v5
	v_lshlrev_b32_e32 v7, 4, v7
	v_lshlrev_b32_e32 v8, 4, v8
	v_lshlrev_b32_e32 v1, 4, v1
	s_cselect_b32 s8, s3, 0
	s_add_i32 s3, s8, 0xc000
	v_or_b32_e32 v83, v2, v5
	v_or_b32_e32 v81, v2, v7
	v_or_b32_e32 v79, v2, v8
	v_or_b32_e32 v77, v2, v1
	v_add_u32_e32 v2, 0xc0, v0
	s_cmp_lg_u32 s8, 0x18000
	v_ashrrev_i32_e32 v3, 31, v2
	s_cselect_b32 s11, s3, 0
	s_add_u32 s6, s4, 0x100
	v_lshlrev_b64 v[2:3], 11, v[2:3]
	s_addc_u32 s7, s5, 0
	v_or_b32_e32 v2, v2, v4
	v_lshl_add_u64 v[64:65], s[6:7], 0, v[2:3]
	v_add_u32_e32 v2, 0x80, v0
	v_ashrrev_i32_e32 v3, 31, v2
	v_lshlrev_b64 v[2:3], 11, v[2:3]
	v_or_b32_e32 v2, v2, v4
	v_lshlrev_b32_e32 v6, 7, v6
	v_lshl_add_u64 v[66:67], s[6:7], 0, v[2:3]
	v_add_u32_e32 v2, 64, v0
	v_or_b32_e32 v76, v1, v6
	v_ashrrev_i32_e32 v3, 31, v2
	v_ashrrev_i32_e32 v1, 31, v0
	v_lshlrev_b64 v[2:3], 11, v[2:3]
	v_lshlrev_b64 v[0:1], 11, v[0:1]
	v_or_b32_e32 v2, v2, v4
	v_or_b32_e32 v0, v0, v4
	v_lshl_add_u64 v[68:69], s[6:7], 0, v[2:3]
	v_lshl_add_u64 v[70:71], s[6:7], 0, v[0:1]
	v_readlane_b32 s6, v231, 15
	v_readlane_b32 s7, v231, 16
	v_or_b32_e32 v82, v5, v6
	v_or_b32_e32 v80, v7, v6
	v_lshl_add_u64 v[74:75], s[6:7], 0, v[0:1]
	v_mov_b32_e32 v0, 0
	v_or_b32_e32 v78, v8, v6
	v_lshl_add_u64 v[72:73], s[6:7], 0, v[2:3]
	s_mov_b64 s[6:7], 0
	s_mov_b32 s3, s9
	v_mov_b32_e32 v1, v0
	v_mov_b32_e32 v2, v0
	v_mov_b32_e32 v3, v0
	v_mov_b32_e32 v4, v0
	v_mov_b32_e32 v5, v0
	v_mov_b32_e32 v6, v0
	v_mov_b32_e32 v7, v0
	v_mov_b32_e32 v8, v0
	v_mov_b32_e32 v9, v0
	v_mov_b32_e32 v10, v0
	v_mov_b32_e32 v11, v0
	v_mov_b32_e32 v12, v0
	v_mov_b32_e32 v13, v0
	v_mov_b32_e32 v14, v0
	v_mov_b32_e32 v15, v0
	v_mov_b32_e32 v32, v0
	v_mov_b32_e32 v33, v0
	v_mov_b32_e32 v34, v0
	v_mov_b32_e32 v35, v0
	v_mov_b32_e32 v36, v0
	v_mov_b32_e32 v37, v0
	v_mov_b32_e32 v38, v0
	v_mov_b32_e32 v39, v0
	v_mov_b32_e32 v40, v0
	v_mov_b32_e32 v41, v0
	v_mov_b32_e32 v42, v0
	v_mov_b32_e32 v43, v0
	v_mov_b32_e32 v44, v0
	v_mov_b32_e32 v45, v0
	v_mov_b32_e32 v46, v0
	v_mov_b32_e32 v47, v0
	v_mov_b32_e32 v16, v0
	v_mov_b32_e32 v17, v0
	v_mov_b32_e32 v18, v0
	v_mov_b32_e32 v19, v0
	v_mov_b32_e32 v20, v0
	v_mov_b32_e32 v21, v0
	v_mov_b32_e32 v22, v0
	v_mov_b32_e32 v23, v0
	v_mov_b32_e32 v24, v0
	v_mov_b32_e32 v25, v0
	v_mov_b32_e32 v26, v0
	v_mov_b32_e32 v27, v0
	v_mov_b32_e32 v28, v0
	v_mov_b32_e32 v29, v0
	v_mov_b32_e32 v30, v0
	v_mov_b32_e32 v31, v0
	v_mov_b32_e32 v48, v0
	v_mov_b32_e32 v49, v0
	v_mov_b32_e32 v50, v0
	v_mov_b32_e32 v51, v0
	v_mov_b32_e32 v52, v0
	v_mov_b32_e32 v53, v0
	v_mov_b32_e32 v54, v0
	v_mov_b32_e32 v55, v0
	v_mov_b32_e32 v56, v0
	v_mov_b32_e32 v57, v0
	v_mov_b32_e32 v58, v0
	v_mov_b32_e32 v59, v0
	v_mov_b32_e32 v60, v0
	v_mov_b32_e32 v61, v0
	v_mov_b32_e32 v62, v0
	v_mov_b32_e32 v63, v0
	s_add_i32 s99, s3, 0
	v_add_u32_e32 v252, s99, v82
	v_add_u32_e32 v253, s99, v83
	ds_read_b128 v[84:87], v252
	ds_read_b128 v[88:91], v252 offset:4096
	ds_read_b128 v[92:95], v253 offset:16384
	ds_read_b128 v[96:99], v253 offset:20480
	s_mov_b64 vcc, -1
	s_branch .Lfws_431

; DEV int stage_next(int s) { return (s == 2 * GS_STAGE) ? 0 : s + GS_STAGE; }
; template <int WAIT0>
; DEV void gk_main(f32x16 (&acc)[2][2], const GTile& t, int s0) {
;     ...
;   for (int kt = 0; kt < nk - 2; ++kt) {
;     GK_DMA(std_, kt + 2);
;     GK_COMPUTE(stc);
;     vm_wait_bar<6>();
;     stc = stage_next(stc); std_ = stage_next(std_);
;   }
;   GK_COMPUTE(stc);
;   vm_wait_bar<0>();
;   stc = stage_next(stc);
;   GK_COMPUTE(stc);
;   vm_wait_bar<0>();
.Lfwb_431:
	s_cselect_b32 s11, s12, 0
	s_add_u32 s6, s6, 0x80
	s_add_i32 s99, s3, 0
	v_add_u32_e32 v252, s99, v82
	v_add_u32_e32 v253, s99, v83
	ds_read_b128 v[84:87], v252
	ds_read_b128 v[88:91], v252 offset:4096
	ds_read_b128 v[92:95], v253 offset:16384
	ds_read_b128 v[96:99], v253 offset:20480
	v_mfma_f32_32x32x16_bf16 v[16:31], v[244:247], v[240:243], v[16:31]
	s_addc_u32 s7, s7, 0
	s_cmpk_lg_i32 s6, 0x700
	v_mfma_f32_32x32x16_bf16 v[32:47], v[248:251], v[236:239], v[32:47]
	v_mfma_f32_32x32x16_bf16 v[0:15], v[248:251], v[240:243], v[0:15]
	s_cbranch_scc1 .LBB0_431
	s_waitcnt lgkmcnt(0)
	s_add_i32 s6, s3, 0
	v_add_u32_e32 v84, s6, v83
	ds_read_b128 v[64:67], v84 offset:16384
	v_add_u32_e32 v72, s6, v82
	ds_read_b128 v[68:71], v72
	ds_read_b128 v[72:75], v72 offset:4096
	s_waitcnt lgkmcnt(0)
	v_mfma_f32_32x32x16_bf16 v[48:63], v[64:67], v[68:71], v[48:63]
	v_mfma_f32_32x32x16_bf16 v[16:31], v[64:67], v[72:75], v[16:31]
	ds_read_b128 v[64:67], v84 offset:20480
	v_add_u32_e32 v84, s6, v81
	s_waitcnt lgkmcnt(0)
	v_mfma_f32_32x32x16_bf16 v[32:47], v[64:67], v[68:71], v[32:47]
	v_mfma_f32_32x32x16_bf16 v[0:15], v[64:67], v[72:75], v[0:15]
	ds_read_b128 v[64:67], v84 offset:16384
	v_add_u32_e32 v72, s6, v80
	ds_read_b128 v[68:71], v72
	ds_read_b128 v[72:75], v72 offset:4096
	s_waitcnt lgkmcnt(0)
	v_mfma_f32_32x32x16_bf16 v[48:63], v[64:67], v[68:71], v[48:63]
	v_mfma_f32_32x32x16_bf16 v[16:31], v[64:67], v[72:75], v[16:31]
	ds_read_b128 v[64:67], v84 offset:20480
	v_add_u32_e32 v84, s6, v79
	s_waitcnt lgkmcnt(0)
	v_mfma_f32_32x32x16_bf16 v[32:47], v[64:67], v[68:71], v[32:47]
	v_mfma_f32_32x32x16_bf16 v[0:15], v[64:67], v[72:75], v[0:15]
	ds_read_b128 v[64:67], v84 offset:16384
	v_add_u32_e32 v72, s6, v78
	ds_read_b128 v[68:71], v72
	ds_read_b128 v[72:75], v72 offset:4096
	s_waitcnt lgkmcnt(0)
	v_mfma_f32_32x32x16_bf16 v[48:63], v[64:67], v[68:71], v[48:63]
	v_mfma_f32_32x32x16_bf16 v[16:31], v[64:67], v[72:75], v[16:31]
	ds_read_b128 v[64:67], v84 offset:20480
	v_add_u32_e32 v84, s6, v77
	s_waitcnt lgkmcnt(0)
	v_mfma_f32_32x32x16_bf16 v[32:47], v[64:67], v[68:71], v[32:47]
	v_mfma_f32_32x32x16_bf16 v[0:15], v[64:67], v[72:75], v[0:15]
	ds_read_b128 v[64:67], v84 offset:16384
	v_add_u32_e32 v72, s6, v76
	ds_read_b128 v[68:71], v72
	ds_read_b128 v[72:75], v72 offset:4096
	s_add_i32 s6, s3, 0xc000
	s_cmp_lg_u32 s3, 0x18000
	s_cselect_b32 s3, s6, 0
	s_waitcnt lgkmcnt(0)
	v_mfma_f32_32x32x16_bf16 v[48:63], v[64:67], v[68:71], v[48:63]
	s_add_i32 s3, s3, 0
	v_add_u32_e32 v83, s3, v83
	v_add_u32_e32 v81, s3, v81
	v_add_u32_e32 v79, s3, v79
	v_add_u32_e32 v77, s3, v77
	v_mfma_f32_32x32x16_bf16 v[16:31], v[64:67], v[72:75], v[16:31]
	ds_read_b128 v[64:67], v84 offset:20480
	s_waitcnt vmcnt(0) lgkmcnt(0)
	s_barrier
	s_waitcnt lgkmcnt(0)
	v_mfma_f32_32x32x16_bf16 v[32:47], v[64:67], v[68:71], v[32:47]
	v_mfma_f32_32x32x16_bf16 v[0:15], v[64:67], v[72:75], v[0:15]
	ds_read_b128 v[64:67], v83 offset:16384
	v_add_u32_e32 v72, s3, v82
	ds_read_b128 v[68:71], v72
	ds_read_b128 v[72:75], v72 offset:4096
	s_waitcnt lgkmcnt(0)
	v_mfma_f32_32x32x16_bf16 v[48:63], v[64:67], v[68:71], v[48:63]
	v_mfma_f32_32x32x16_bf16 v[16:31], v[64:67], v[72:75], v[16:31]
	ds_read_b128 v[64:67], v83 offset:20480
	s_waitcnt lgkmcnt(0)
	v_mfma_f32_32x32x16_bf16 v[32:47], v[64:67], v[68:71], v[32:47]
	v_mfma_f32_32x32x16_bf16 v[0:15], v[64:67], v[72:75], v[0:15]
	ds_read_b128 v[64:67], v81 offset:16384
	v_add_u32_e32 v72, s3, v80
	ds_read_b128 v[68:71], v72
	ds_read_b128 v[72:75], v72 offset:4096
	s_waitcnt lgkmcnt(0)
	v_mfma_f32_32x32x16_bf16 v[48:63], v[64:67], v[68:71], v[48:63]
	v_mfma_f32_32x32x16_bf16 v[16:31], v[64:67], v[72:75], v[16:31]
	ds_read_b128 v[64:67], v81 offset:20480
	s_waitcnt lgkmcnt(0)
	v_mfma_f32_32x32x16_bf16 v[32:47], v[64:67], v[68:71], v[32:47]
	v_mfma_f32_32x32x16_bf16 v[0:15], v[64:67], v[72:75], v[0:15]
	ds_read_b128 v[64:67], v79 offset:16384
	v_add_u32_e32 v72, s3, v78
	ds_read_b128 v[68:71], v72
	ds_read_b128 v[72:75], v72 offset:4096
	s_waitcnt lgkmcnt(0)
	v_mfma_f32_32x32x16_bf16 v[48:63], v[64:67], v[68:71], v[48:63]
	v_mfma_f32_32x32x16_bf16 v[16:31], v[64:67], v[72:75], v[16:31]
	ds_read_b128 v[64:67], v79 offset:20480
	s_waitcnt lgkmcnt(0)
	v_mfma_f32_32x32x16_bf16 v[32:47], v[64:67], v[68:71], v[32:47]
	v_mfma_f32_32x32x16_bf16 v[0:15], v[64:67], v[72:75], v[0:15]
	ds_read_b128 v[64:67], v77 offset:16384
	v_add_u32_e32 v72, s3, v76
	ds_read_b128 v[68:71], v72
	ds_read_b128 v[72:75], v72 offset:4096
	s_waitcnt lgkmcnt(0)
	v_mfma_f32_32x32x16_bf16 v[48:63], v[64:67], v[68:71], v[48:63]
	v_mfma_f32_32x32x16_bf16 v[16:31], v[64:67], v[72:75], v[16:31]
	ds_read_b128 v[64:67], v77 offset:20480
	s_waitcnt vmcnt(0) lgkmcnt(0)
	s_barrier
	s_waitcnt lgkmcnt(0)
	v_mfma_f32_32x32x16_bf16 v[32:47], v[64:67], v[68:71], v[32:47]
	v_mfma_f32_32x32x16_bf16 v[0:15], v[64:67], v[72:75], v[0:15]

; DEV int tid_l() { int t = threadIdx.x; asm volatile("" : "+v"(t)); return t; }
; DEV int stage_next(int s) { return (s == 2 * GS_STAGE) ? 0 : s + GS_STAGE; }
; template <int WAIT0>
; DEV void gk_main(f32x16 (&acc)[2][2], const GTile& t, int s0) {
;   const int tid = tid_l(), lane = tid & 63, wid = __builtin_amdgcn_readfirstlane(tid >> 6), wm = wid & 1, wn = wid >> 1, l32 = lane & 31, hi = lane >> 5;
;   GK_SRC(t)
;   const int sw = (l32 >> 1) & 7;
;   int xk[4], wk[4];
; #pragma unroll
;   for (int ks = 0; ks < 4; ++ks) { const int ko = ((2 * ks + hi) ^ sw) << 4; xk[ks] = GS_A + (64 * wm + l32) * 128 + ko; wk[ks] = GS_B + (64 * wn + l32) * 128 + ko; }
;   const int nk = t.K >> 6;
;     ...
;   vm_wait_bar<WAIT0>();
;   int stc = s0, std_ = stage_next(stage_next(s0));
.LBB0_712:
	s_cmp_lg_u32 s12, 0
	s_cbranch_scc0 .LBB0_723
	s_bitcmp0_b32 s12, 0
	s_mov_b64 s[6:7], -1
	s_cbranch_scc1 .LBB0_717
	v_mov_b32_e32 v1, v176
	s_waitcnt vmcnt(22) lgkmcnt(0)
	s_barrier
	v_readfirstlane_b32 s2, v1
	s_ashr_i32 s3, s2, 6
	v_bfe_u32 v0, v1, 3, 3
	v_and_b32_e32 v2, 31, v1
	v_lshl_or_b32 v0, s3, 3, v0
	v_lshrrev_b32_e32 v3, 1, v0
	v_and_or_b32 v6, s2, 64, v2
	s_lshr_b32 s2, s2, 1
	v_xor_b32_e32 v3, v3, v1
	s_and_b32 s2, s2, 0x1ffffc0
	v_lshlrev_b32_e32 v3, 4, v3
	v_or_b32_e32 v2, s2, v2
	s_lshl_b32 s2, s3, 10
	v_and_b32_e32 v4, 0x70, v3
	v_bfe_u32 v3, v1, 5, 1
	v_lshrrev_b32_e32 v5, 1, v1
	v_bfe_u32 v1, v1, 1, 3
	s_add_i32 s3, s2, 0
	s_add_i32 s2, s11, 0xc000
	v_bitop3_b32 v5, v3, v5, 7 bitop3:0x78
	v_bitop3_b32 v7, v3, v1, 2 bitop3:0x36
	v_bitop3_b32 v8, v3, v1, 4 bitop3:0x36
	v_bitop3_b32 v1, v3, v1, 6 bitop3:0x36
	s_cmp_lg_u32 s11, 0x18000
	v_lshlrev_b32_e32 v2, 7, v2
	v_lshlrev_b32_e32 v5, 4, v5
	v_lshlrev_b32_e32 v7, 4, v7
	v_lshlrev_b32_e32 v8, 4, v8
	v_lshlrev_b32_e32 v1, 4, v1
	s_cselect_b32 s10, s2, 0
	s_add_i32 s2, s10, 0xc000
	v_or_b32_e32 v83, v2, v5
	v_or_b32_e32 v82, v2, v7
	v_or_b32_e32 v80, v2, v8
	v_or_b32_e32 v78, v2, v1
	v_add_u32_e32 v2, 0xc0, v0
	s_cmp_lg_u32 s10, 0x18000
	v_ashrrev_i32_e32 v3, 31, v2
	s_cselect_b32 s13, s2, 0
	s_add_u32 s6, s4, 0x100
	v_lshlrev_b64 v[2:3], 11, v[2:3]
	s_addc_u32 s7, s5, 0
	v_or_b32_e32 v2, v2, v4
	v_lshl_add_u64 v[64:65], s[6:7], 0, v[2:3]
	v_add_u32_e32 v2, 0x80, v0
	v_ashrrev_i32_e32 v3, 31, v2
	v_lshlrev_b64 v[2:3], 11, v[2:3]
	v_lshlrev_b32_e32 v6, 7, v6
	v_or_b32_e32 v2, v2, v4
	v_or_b32_e32 v76, v1, v6
	v_lshl_add_u64 v[66:67], s[6:7], 0, v[2:3]
	v_add_u32_e32 v2, 64, v0
	v_ashrrev_i32_e32 v1, 31, v0
	v_ashrrev_i32_e32 v3, 31, v2
	v_lshlrev_b64 v[0:1], 11, v[0:1]
	v_lshlrev_b64 v[2:3], 11, v[2:3]
	v_or_b32_e32 v0, v0, v4
	v_or_b32_e32 v2, v2, v4
	v_lshl_add_u64 v[70:71], s[6:7], 0, v[0:1]
	v_lshl_add_u64 v[74:75], s[8:9], 0, v[0:1]
	v_mov_b32_e32 v0, 0
	v_or_b32_e32 v81, v5, v6
	v_or_b32_e32 v79, v7, v6
	v_or_b32_e32 v77, v8, v6
	v_lshl_add_u64 v[68:69], s[6:7], 0, v[2:3]
	v_lshl_add_u64 v[72:73], s[8:9], 0, v[2:3]
	s_mov_b64 s[6:7], 0
	s_mov_b32 s2, s11
	v_mov_b32_e32 v1, v0
	v_mov_b32_e32 v2, v0
	v_mov_b32_e32 v3, v0
	v_mov_b32_e32 v4, v0
	v_mov_b32_e32 v5, v0
	v_mov_b32_e32 v6, v0
	v_mov_b32_e32 v7, v0
	v_mov_b32_e32 v8, v0
	v_mov_b32_e32 v9, v0
	v_mov_b32_e32 v10, v0
	v_mov_b32_e32 v11, v0
	v_mov_b32_e32 v12, v0
	v_mov_b32_e32 v13, v0
	v_mov_b32_e32 v14, v0
	v_mov_b32_e32 v15, v0
	v_mov_b32_e32 v32, v0
	v_mov_b32_e32 v33, v0
	v_mov_b32_e32 v34, v0
	v_mov_b32_e32 v35, v0
	v_mov_b32_e32 v36, v0
	v_mov_b32_e32 v37, v0
	v_mov_b32_e32 v38, v0
	v_mov_b32_e32 v39, v0
	v_mov_b32_e32 v40, v0
	v_mov_b32_e32 v41, v0
	v_mov_b32_e32 v42, v0
	v_mov_b32_e32 v43, v0
	v_mov_b32_e32 v44, v0
	v_mov_b32_e32 v45, v0
	v_mov_b32_e32 v46, v0
	v_mov_b32_e32 v47, v0
	v_mov_b32_e32 v16, v0
	v_mov_b32_e32 v17, v0
	v_mov_b32_e32 v18, v0
	v_mov_b32_e32 v19, v0
	v_mov_b32_e32 v20, v0
	v_mov_b32_e32 v21, v0
	v_mov_b32_e32 v22, v0
	v_mov_b32_e32 v23, v0
	v_mov_b32_e32 v24, v0
	v_mov_b32_e32 v25, v0
	v_mov_b32_e32 v26, v0
	v_mov_b32_e32 v27, v0
	v_mov_b32_e32 v28, v0
	v_mov_b32_e32 v29, v0
	v_mov_b32_e32 v30, v0
	v_mov_b32_e32 v31, v0
	v_mov_b32_e32 v48, v0
	v_mov_b32_e32 v49, v0
	v_mov_b32_e32 v50, v0
	v_mov_b32_e32 v51, v0
	v_mov_b32_e32 v52, v0
	v_mov_b32_e32 v53, v0
	v_mov_b32_e32 v54, v0
	v_mov_b32_e32 v55, v0
	v_mov_b32_e32 v56, v0
	v_mov_b32_e32 v57, v0
	v_mov_b32_e32 v58, v0
	v_mov_b32_e32 v59, v0
	v_mov_b32_e32 v60, v0
	v_mov_b32_e32 v61, v0
	v_mov_b32_e32 v62, v0
	v_mov_b32_e32 v63, v0
	s_add_i32 s99, s2, 0
	v_add_u32_e32 v253, s99, v81
	v_add_u32_e32 v252, s99, v83
	ds_read_b128 v[84:87], v252 offset:16384
	ds_read_b128 v[88:91], v253
	ds_read_b128 v[92:95], v253 offset:4096
	ds_read_b128 v[96:99], v252 offset:20480
	s_mov_b64 vcc, -1
	s_branch .Lfws_715

; DEV int stage_next(int s) { return (s == 2 * GS_STAGE) ? 0 : s + GS_STAGE; }
; template <int WAIT0>
; DEV void gk_main(f32x16 (&acc)[2][2], const GTile& t, int s0) {
;     ...
;   for (int kt = 0; kt < nk - 2; ++kt) {
;     GK_DMA(std_, kt + 2);
;     GK_COMPUTE(stc);
;     vm_wait_bar<6>();
;     stc = stage_next(stc); std_ = stage_next(std_);
;   }
;   GK_COMPUTE(stc);
;   vm_wait_bar<0>();
;   stc = stage_next(stc);
;   GK_COMPUTE(stc);
;   vm_wait_bar<0>();
.Lfws_715:
.LBB0_715:
	s_add_i32 s14, s3, s13
	s_mov_b32 s98, s14
	s_mov_b64 s[100:101], s[6:7]
	s_waitcnt lgkmcnt(0)
	v_add_u32_e32 v101, s99, v82
	v_add_u32_e32 v100, s99, v79
	s_add_i32 s14, s2, 0xc000
	s_cmp_lg_u32 s2, 0x18000
	s_cselect_b32 s2, s14, 0
	s_add_i32 s14, s13, 0xc000
	s_cmp_lg_u32 s13, 0x18000
	s_cselect_b32 s13, s14, 0
	s_add_u32 s6, s6, 0x80
	s_addc_u32 s7, s7, 0
	ds_read_b128 v[236:239], v101 offset:16384
	ds_read_b128 v[240:243], v100
	ds_read_b128 v[244:247], v100 offset:4096
	ds_read_b128 v[248:251], v101 offset:20480
	v_mfma_f32_32x32x16_bf16 v[48:63], v[84:87], v[88:91], v[48:63]
	v_mfma_f32_32x32x16_bf16 v[16:31], v[84:87], v[92:95], v[16:31]
	s_mov_b32 m0, s98
	v_lshl_add_u64 v[254:255], v[74:75], 0, s[100:101]
	global_load_lds_dwordx4 v[254:255], off
	v_mfma_f32_32x32x16_bf16 v[32:47], v[96:99], v[88:91], v[32:47]
	v_mfma_f32_32x32x16_bf16 v[0:15], v[96:99], v[92:95], v[0:15]
	s_add_i32 m0, s98, 0x2000
	v_lshl_add_u64 v[254:255], v[72:73], 0, s[100:101]
	global_load_lds_dwordx4 v[254:255], off
	v_add_u32_e32 v101, s99, v80
	v_add_u32_e32 v100, s99, v77
	s_waitcnt lgkmcnt(0)
	ds_read_b128 v[84:87], v101 offset:16384
	ds_read_b128 v[88:91], v100
	ds_read_b128 v[92:95], v100 offset:4096
	ds_read_b128 v[96:99], v101 offset:20480
	v_mfma_f32_32x32x16_bf16 v[48:63], v[236:239], v[240:243], v[48:63]
	v_mfma_f32_32x32x16_bf16 v[16:31], v[236:239], v[244:247], v[16:31]
	s_add_i32 m0, s98, 0x4000
	v_lshl_add_u64 v[254:255], v[70:71], 0, s[100:101]
	global_load_lds_dwordx4 v[254:255], off
	v_mfma_f32_32x32x16_bf16 v[32:47], v[248:251], v[240:243], v[32:47]
	v_mfma_f32_32x32x16_bf16 v[0:15], v[248:251], v[244:247], v[0:15]
	s_add_i32 m0, s98, 0x6000
	v_lshl_add_u64 v[254:255], v[68:69], 0, s[100:101]
	global_load_lds_dwordx4 v[254:255], off
	v_add_u32_e32 v101, s99, v78
	v_add_u32_e32 v100, s99, v76
	s_waitcnt lgkmcnt(0)
	ds_read_b128 v[236:239], v101 offset:16384
	ds_read_b128 v[240:243], v100
	ds_read_b128 v[244:247], v100 offset:4096
	ds_read_b128 v[248:251], v101 offset:20480
	v_mfma_f32_32x32x16_bf16 v[48:63], v[84:87], v[88:91], v[48:63]
	v_mfma_f32_32x32x16_bf16 v[16:31], v[84:87], v[92:95], v[16:31]
	s_add_i32 m0, s98, 0x8000
	v_lshl_add_u64 v[254:255], v[66:67], 0, s[100:101]
	global_load_lds_dwordx4 v[254:255], off
	v_mfma_f32_32x32x16_bf16 v[32:47], v[96:99], v[88:91], v[32:47]
	v_mfma_f32_32x32x16_bf16 v[0:15], v[96:99], v[92:95], v[0:15]
	s_add_i32 m0, s98, 0xa000
	v_lshl_add_u64 v[254:255], v[64:65], 0, s[100:101]
	global_load_lds_dwordx4 v[254:255], off
	s_cbranch_vccnz .Lfw_715
	s_waitcnt vmcnt(6) lgkmcnt(0)
	s_barrier
.Lfwb_715:
	s_waitcnt lgkmcnt(0)
	s_add_i32 s99, s2, 0
	v_add_u32_e32 v253, s99, v81
	v_add_u32_e32 v252, s99, v83
	ds_read_b128 v[84:87], v252 offset:16384
	ds_read_b128 v[88:91], v253
	ds_read_b128 v[92:95], v253 offset:4096
	ds_read_b128 v[96:99], v252 offset:20480
	v_mfma_f32_32x32x16_bf16 v[48:63], v[236:239], v[240:243], v[48:63]
	v_mfma_f32_32x32x16_bf16 v[16:31], v[236:239], v[244:247], v[16:31]
	v_mfma_f32_32x32x16_bf16 v[32:47], v[248:251], v[240:243], v[32:47]
	v_mfma_f32_32x32x16_bf16 v[0:15], v[248:251], v[244:247], v[0:15]
	s_cmpk_lg_i32 s6, 0x700
	s_cbranch_scc1 .LBB0_715
	s_waitcnt lgkmcnt(0)
	s_add_i32 s3, s2, 0
	v_add_u32_e32 v84, s3, v83
	ds_read_b128 v[64:67], v84 offset:16384
	v_add_u32_e32 v72, s3, v81
	ds_read_b128 v[68:71], v72
	ds_read_b128 v[72:75], v72 offset:4096
	ds_read_b128 v[84:87], v84 offset:20480
	s_mov_b64 s[6:7], 0
	s_waitcnt lgkmcnt(0)
	v_mfma_f32_32x32x16_bf16 v[32:47], v[84:87], v[68:71], v[32:47]
	v_mfma_f32_32x32x16_bf16 v[0:15], v[84:87], v[72:75], v[0:15]
	v_add_u32_e32 v84, s3, v82
	v_mfma_f32_32x32x16_bf16 v[48:63], v[64:67], v[68:71], v[48:63]
	v_mfma_f32_32x32x16_bf16 v[16:31], v[64:67], v[72:75], v[16:31]
	ds_read_b128 v[64:67], v84 offset:16384
	v_add_u32_e32 v72, s3, v79
	ds_read_b128 v[68:71], v72
	ds_read_b128 v[72:75], v72 offset:4096
	ds_read_b128 v[84:87], v84 offset:20480
	s_waitcnt lgkmcnt(0)
	v_mfma_f32_32x32x16_bf16 v[32:47], v[84:87], v[68:71], v[32:47]
	v_mfma_f32_32x32x16_bf16 v[0:15], v[84:87], v[72:75], v[0:15]
	v_add_u32_e32 v84, s3, v80
	v_mfma_f32_32x32x16_bf16 v[48:63], v[64:67], v[68:71], v[48:63]
	v_mfma_f32_32x32x16_bf16 v[16:31], v[64:67], v[72:75], v[16:31]
	ds_read_b128 v[64:67], v84 offset:16384
	v_add_u32_e32 v72, s3, v77
	ds_read_b128 v[68:71], v72
	ds_read_b128 v[72:75], v72 offset:4096
	ds_read_b128 v[84:87], v84 offset:20480
	s_waitcnt lgkmcnt(0)
	v_mfma_f32_32x32x16_bf16 v[32:47], v[84:87], v[68:71], v[32:47]
	v_mfma_f32_32x32x16_bf16 v[0:15], v[84:87], v[72:75], v[0:15]
	v_add_u32_e32 v84, s3, v78
	v_mfma_f32_32x32x16_bf16 v[48:63], v[64:67], v[68:71], v[48:63]
	v_mfma_f32_32x32x16_bf16 v[16:31], v[64:67], v[72:75], v[16:31]
	ds_read_b128 v[64:67], v84 offset:16384
	v_add_u32_e32 v72, s3, v76
	s_add_i32 s3, s2, 0xc000
	ds_read_b128 v[68:71], v72
	ds_read_b128 v[72:75], v72 offset:4096
	ds_read_b128 v[84:87], v84 offset:20480
	s_cmp_lg_u32 s2, 0x18000
	s_cselect_b32 s2, s3, 0
	s_add_i32 s2, s2, 0
	s_waitcnt vmcnt(0) lgkmcnt(0)
	s_barrier
; DEV int tid_l() { int t = threadIdx.x; asm volatile("" : "+v"(t)); return t; }
; DEV int stage_next(int s) { return (s == 2 * GS_STAGE) ? 0 : s + GS_STAGE; }
; template <int WAIT0>
; DEV void gk_main(f32x16 (&acc)[2][2], const GTile& t, int s0) {
;   const int tid = tid_l(), lane = tid & 63, wid = __builtin_amdgcn_readfirstlane(tid >> 6), wm = wid & 1, wn = wid >> 1, l32 = lane & 31, hi = lane >> 5;
;   GK_SRC(t)
;   const int sw = (l32 >> 1) & 7;
;   int xk[4], wk[4];
; #pragma unroll
;   for (int ks = 0; ks < 4; ++ks) { const int ko = ((2 * ks + hi) ^ sw) << 4; xk[ks] = GS_A + (64 * wm + l32) * 128 + ko; wk[ks] = GS_B + (64 * wn + l32) * 128 + ko; }
;   const int nk = t.K >> 6;
;     ...
;   vm_wait_bar<WAIT0>();
;   int stc = s0, std_ = stage_next(stage_next(s0));
;     ...
;   GK_COMPUTE(stc);
;   vm_wait_bar<0>();
;   stc = stage_next(stc);
;   GK_COMPUTE(stc);
;   vm_wait_bar<0>();
	v_add_u32_e32 v83, s2, v83
	s_waitcnt lgkmcnt(0)
	v_mfma_f32_32x32x16_bf16 v[48:63], v[64:67], v[68:71], v[48:63]
	v_mfma_f32_32x32x16_bf16 v[16:31], v[64:67], v[72:75], v[16:31]
	ds_read_b128 v[64:67], v83 offset:16384
	v_mfma_f32_32x32x16_bf16 v[32:47], v[84:87], v[68:71], v[32:47]
	v_mfma_f32_32x32x16_bf16 v[0:15], v[84:87], v[72:75], v[0:15]
	v_add_u32_e32 v72, s2, v81
	ds_read_b128 v[68:71], v72
	ds_read_b128 v[72:75], v72 offset:4096
	ds_read_b128 v[84:87], v83 offset:20480
	v_add_u32_e32 v81, s2, v82
	s_waitcnt lgkmcnt(0)
	v_mfma_f32_32x32x16_bf16 v[48:63], v[64:67], v[68:71], v[48:63]
	v_mfma_f32_32x32x16_bf16 v[16:31], v[64:67], v[72:75], v[16:31]
	ds_read_b128 v[64:67], v81 offset:16384
	v_mfma_f32_32x32x16_bf16 v[32:47], v[84:87], v[68:71], v[32:47]
	v_mfma_f32_32x32x16_bf16 v[0:15], v[84:87], v[72:75], v[0:15]
	v_add_u32_e32 v72, s2, v79
	ds_read_b128 v[68:71], v72
	ds_read_b128 v[72:75], v72 offset:4096
	ds_read_b128 v[82:85], v81 offset:20480
	v_add_u32_e32 v79, s2, v80
	s_waitcnt lgkmcnt(0)
	v_mfma_f32_32x32x16_bf16 v[48:63], v[64:67], v[68:71], v[48:63]
	v_mfma_f32_32x32x16_bf16 v[16:31], v[64:67], v[72:75], v[16:31]
	ds_read_b128 v[64:67], v79 offset:16384
	v_mfma_f32_32x32x16_bf16 v[32:47], v[82:85], v[68:71], v[32:47]
	v_mfma_f32_32x32x16_bf16 v[0:15], v[82:85], v[72:75], v[0:15]
	v_add_u32_e32 v72, s2, v77
	ds_read_b128 v[68:71], v72
	ds_read_b128 v[72:75], v72 offset:4096
	ds_read_b128 v[80:83], v79 offset:20480
	v_add_u32_e32 v77, s2, v78
	s_waitcnt lgkmcnt(0)
	v_mfma_f32_32x32x16_bf16 v[48:63], v[64:67], v[68:71], v[48:63]
	v_mfma_f32_32x32x16_bf16 v[16:31], v[64:67], v[72:75], v[16:31]
	ds_read_b128 v[64:67], v77 offset:16384
	v_mfma_f32_32x32x16_bf16 v[32:47], v[80:83], v[68:71], v[32:47]
	v_mfma_f32_32x32x16_bf16 v[0:15], v[80:83], v[72:75], v[0:15]
	v_add_u32_e32 v72, s2, v76
	ds_read_b128 v[68:71], v72
	ds_read_b128 v[72:75], v72 offset:4096
	ds_read_b128 v[76:79], v77 offset:20480
	s_waitcnt vmcnt(0) lgkmcnt(0)
	s_barrier
	s_waitcnt lgkmcnt(0)
	v_mfma_f32_32x32x16_bf16 v[48:63], v[64:67], v[68:71], v[48:63]
	v_mfma_f32_32x32x16_bf16 v[16:31], v[64:67], v[72:75], v[16:31]
	v_mfma_f32_32x32x16_bf16 v[32:47], v[76:79], v[68:71], v[32:47]
	v_mfma_f32_32x32x16_bf16 v[0:15], v[76:79], v[72:75], v[0:15]
.LBB0_717:
	s_and_b64 vcc, exec, s[6:7]
	s_cbranch_vccz .LBB0_721
	s_nop 9
	v_mov_b32_e32 v1, v176
	s_waitcnt vmcnt(22) lgkmcnt(0)
	s_barrier
	v_readfirstlane_b32 s2, v1
	s_ashr_i32 s3, s2, 6
	v_bfe_u32 v0, v1, 3, 3
	v_and_b32_e32 v2, 31, v1
	v_lshl_or_b32 v0, s3, 3, v0
	v_lshrrev_b32_e32 v3, 1, v0
	v_and_or_b32 v6, s2, 64, v2
	s_lshr_b32 s2, s2, 1
	v_xor_b32_e32 v3, v3, v1
	s_and_b32 s2, s2, 0x1ffffc0
	v_lshlrev_b32_e32 v3, 4, v3
	v_or_b32_e32 v2, s2, v2
	s_lshl_b32 s2, s3, 10
	v_and_b32_e32 v4, 0x70, v3
	v_bfe_u32 v3, v1, 5, 1
	v_lshrrev_b32_e32 v5, 1, v1
	v_bfe_u32 v1, v1, 1, 3
	s_add_i32 s3, s2, 0
	s_add_i32 s2, s11, 0xc000
	v_bitop3_b32 v5, v3, v5, 7 bitop3:0x78
	v_bitop3_b32 v7, v3, v1, 2 bitop3:0x36
	v_bitop3_b32 v8, v3, v1, 4 bitop3:0x36
	v_bitop3_b32 v1, v3, v1, 6 bitop3:0x36
	s_cmp_lg_u32 s11, 0x18000
	v_lshlrev_b32_e32 v2, 7, v2
	v_lshlrev_b32_e32 v5, 4, v5
	v_lshlrev_b32_e32 v7, 4, v7
	v_lshlrev_b32_e32 v8, 4, v8
	v_lshlrev_b32_e32 v1, 4, v1
	s_cselect_b32 s10, s2, 0
	s_add_i32 s2, s10, 0xc000
	v_or_b32_e32 v83, v2, v5
	v_or_b32_e32 v82, v2, v7
	v_or_b32_e32 v80, v2, v8
	v_or_b32_e32 v78, v2, v1
	v_add_u32_e32 v2, 0xc0, v0
	s_cmp_lg_u32 s10, 0x18000
	v_ashrrev_i32_e32 v3, 31, v2
	s_cselect_b32 s13, s2, 0
	s_add_u32 s6, s4, 0x100
	v_lshlrev_b64 v[2:3], 11, v[2:3]
	s_addc_u32 s7, s5, 0
	v_or_b32_e32 v2, v2, v4
	v_lshl_add_u64 v[64:65], s[6:7], 0, v[2:3]
	v_add_u32_e32 v2, 0x80, v0
	v_ashrrev_i32_e32 v3, 31, v2
	v_lshlrev_b64 v[2:3], 11, v[2:3]
	v_lshlrev_b32_e32 v6, 7, v6
	v_or_b32_e32 v2, v2, v4
	v_or_b32_e32 v76, v1, v6
	v_lshl_add_u64 v[66:67], s[6:7], 0, v[2:3]
	v_add_u32_e32 v2, 64, v0
	v_ashrrev_i32_e32 v1, 31, v0
	v_ashrrev_i32_e32 v3, 31, v2
	v_lshlrev_b64 v[0:1], 11, v[0:1]
	v_lshlrev_b64 v[2:3], 11, v[2:3]
	v_or_b32_e32 v0, v0, v4
	v_or_b32_e32 v2, v2, v4
	v_lshl_add_u64 v[70:71], s[6:7], 0, v[0:1]
	v_lshl_add_u64 v[74:75], s[8:9], 0, v[0:1]
	v_mov_b32_e32 v0, 0
	v_or_b32_e32 v81, v5, v6
	v_or_b32_e32 v79, v7, v6
	v_or_b32_e32 v77, v8, v6
	v_lshl_add_u64 v[68:69], s[6:7], 0, v[2:3]
	v_lshl_add_u64 v[72:73], s[8:9], 0, v[2:3]
	s_mov_b64 s[6:7], 0
	s_mov_b32 s2, s11
	v_mov_b32_e32 v1, v0
	v_mov_b32_e32 v2, v0
	v_mov_b32_e32 v3, v0
	v_mov_b32_e32 v4, v0
	v_mov_b32_e32 v5, v0
	v_mov_b32_e32 v6, v0
	v_mov_b32_e32 v7, v0
	v_mov_b32_e32 v8, v0
	v_mov_b32_e32 v9, v0
	v_mov_b32_e32 v10, v0
	v_mov_b32_e32 v11, v0
	v_mov_b32_e32 v12, v0
	v_mov_b32_e32 v13, v0
	v_mov_b32_e32 v14, v0
	v_mov_b32_e32 v15, v0
	v_mov_b32_e32 v32, v0
	v_mov_b32_e32 v33, v0
	v_mov_b32_e32 v34, v0
	v_mov_b32_e32 v35, v0
	v_mov_b32_e32 v36, v0
	v_mov_b32_e32 v37, v0
	v_mov_b32_e32 v38, v0
	v_mov_b32_e32 v39, v0
	v_mov_b32_e32 v40, v0
	v_mov_b32_e32 v41, v0
	v_mov_b32_e32 v42, v0
	v_mov_b32_e32 v43, v0
	v_mov_b32_e32 v44, v0
	v_mov_b32_e32 v45, v0
	v_mov_b32_e32 v46, v0
	v_mov_b32_e32 v47, v0
	v_mov_b32_e32 v16, v0
	v_mov_b32_e32 v17, v0
	v_mov_b32_e32 v18, v0
	v_mov_b32_e32 v19, v0
	v_mov_b32_e32 v20, v0
	v_mov_b32_e32 v21, v0
	v_mov_b32_e32 v22, v0
	v_mov_b32_e32 v23, v0
	v_mov_b32_e32 v24, v0
	v_mov_b32_e32 v25, v0
	v_mov_b32_e32 v26, v0
	v_mov_b32_e32 v27, v0
	v_mov_b32_e32 v28, v0
	v_mov_b32_e32 v29, v0
	v_mov_b32_e32 v30, v0
	v_mov_b32_e32 v31, v0
	v_mov_b32_e32 v48, v0
	v_mov_b32_e32 v49, v0
	v_mov_b32_e32 v50, v0
	v_mov_b32_e32 v51, v0
	v_mov_b32_e32 v52, v0
	v_mov_b32_e32 v53, v0
	v_mov_b32_e32 v54, v0
	v_mov_b32_e32 v55, v0
	v_mov_b32_e32 v56, v0
	v_mov_b32_e32 v57, v0
	v_mov_b32_e32 v58, v0
	v_mov_b32_e32 v59, v0
	v_mov_b32_e32 v60, v0
	v_mov_b32_e32 v61, v0
	v_mov_b32_e32 v62, v0
	v_mov_b32_e32 v63, v0
	s_add_i32 s99, s2, 0
	v_add_u32_e32 v253, s99, v81
	v_add_u32_e32 v252, s99, v83
	ds_read_b128 v[84:87], v252 offset:16384
	ds_read_b128 v[88:91], v253
	ds_read_b128 v[92:95], v253 offset:4096
	ds_read_b128 v[96:99], v252 offset:20480
	s_mov_b64 vcc, -1
	s_branch .Lfws_719

; DEV int stage_next(int s) { return (s == 2 * GS_STAGE) ? 0 : s + GS_STAGE; }
; template <int WAIT0>
; DEV void gk_main(f32x16 (&acc)[2][2], const GTile& t, int s0) {
;     ...
;   for (int kt = 0; kt < nk - 2; ++kt) {
;     GK_DMA(std_, kt + 2);
;     GK_COMPUTE(stc);
;     vm_wait_bar<6>();
;     stc = stage_next(stc); std_ = stage_next(std_);
;   }
;   GK_COMPUTE(stc);
;   vm_wait_bar<0>();
;   stc = stage_next(stc);
;   GK_COMPUTE(stc);
;   vm_wait_bar<0>();
.Lfwb_719:
	s_waitcnt lgkmcnt(0)
	s_add_i32 s99, s2, 0
	v_add_u32_e32 v253, s99, v81
	v_add_u32_e32 v252, s99, v83
	ds_read_b128 v[84:87], v252 offset:16384
	ds_read_b128 v[88:91], v253
	ds_read_b128 v[92:95], v253 offset:4096
	ds_read_b128 v[96:99], v252 offset:20480
	v_mfma_f32_32x32x16_bf16 v[48:63], v[236:239], v[240:243], v[48:63]
	v_mfma_f32_32x32x16_bf16 v[16:31], v[236:239], v[244:247], v[16:31]
	v_mfma_f32_32x32x16_bf16 v[32:47], v[248:251], v[240:243], v[32:47]
	v_mfma_f32_32x32x16_bf16 v[0:15], v[248:251], v[244:247], v[0:15]
	s_cmpk_lg_i32 s6, 0x700
	s_cbranch_scc1 .LBB0_719
	s_waitcnt lgkmcnt(0)
	s_add_i32 s3, s2, 0
	v_add_u32_e32 v84, s3, v83
	ds_read_b128 v[64:67], v84 offset:16384
	v_add_u32_e32 v72, s3, v81
	ds_read_b128 v[68:71], v72
	ds_read_b128 v[72:75], v72 offset:4096
	ds_read_b128 v[84:87], v84 offset:20480
	s_waitcnt lgkmcnt(0)
	v_mfma_f32_32x32x16_bf16 v[32:47], v[84:87], v[68:71], v[32:47]
	v_mfma_f32_32x32x16_bf16 v[0:15], v[84:87], v[72:75], v[0:15]
	v_add_u32_e32 v84, s3, v82
	v_mfma_f32_32x32x16_bf16 v[48:63], v[64:67], v[68:71], v[48:63]
	v_mfma_f32_32x32x16_bf16 v[16:31], v[64:67], v[72:75], v[16:31]
	ds_read_b128 v[64:67], v84 offset:16384
	v_add_u32_e32 v72, s3, v79
	ds_read_b128 v[68:71], v72
	ds_read_b128 v[72:75], v72 offset:4096
	ds_read_b128 v[84:87], v84 offset:20480
	s_waitcnt lgkmcnt(0)
	v_mfma_f32_32x32x16_bf16 v[32:47], v[84:87], v[68:71], v[32:47]
	v_mfma_f32_32x32x16_bf16 v[0:15], v[84:87], v[72:75], v[0:15]
	v_add_u32_e32 v84, s3, v80
	v_mfma_f32_32x32x16_bf16 v[48:63], v[64:67], v[68:71], v[48:63]
	v_mfma_f32_32x32x16_bf16 v[16:31], v[64:67], v[72:75], v[16:31]
	ds_read_b128 v[64:67], v84 offset:16384
	v_add_u32_e32 v72, s3, v77
	ds_read_b128 v[68:71], v72
	ds_read_b128 v[72:75], v72 offset:4096
	ds_read_b128 v[84:87], v84 offset:20480
	s_waitcnt lgkmcnt(0)
	v_mfma_f32_32x32x16_bf16 v[32:47], v[84:87], v[68:71], v[32:47]
	v_mfma_f32_32x32x16_bf16 v[0:15], v[84:87], v[72:75], v[0:15]
	v_add_u32_e32 v84, s3, v78
	v_mfma_f32_32x32x16_bf16 v[48:63], v[64:67], v[68:71], v[48:63]
	v_mfma_f32_32x32x16_bf16 v[16:31], v[64:67], v[72:75], v[16:31]
	ds_read_b128 v[64:67], v84 offset:16384
	v_add_u32_e32 v72, s3, v76
	s_add_i32 s3, s2, 0xc000
	ds_read_b128 v[68:71], v72
	ds_read_b128 v[72:75], v72 offset:4096
	ds_read_b128 v[84:87], v84 offset:20480
	s_cmp_lg_u32 s2, 0x18000
	s_cselect_b32 s2, s3, 0
	s_add_i32 s2, s2, 0
	s_waitcnt vmcnt(0) lgkmcnt(0)
	s_barrier
	v_add_u32_e32 v83, s2, v83
	s_waitcnt lgkmcnt(0)
	v_mfma_f32_32x32x16_bf16 v[48:63], v[64:67], v[68:71], v[48:63]
	v_mfma_f32_32x32x16_bf16 v[16:31], v[64:67], v[72:75], v[16:31]
	ds_read_b128 v[64:67], v83 offset:16384
	v_mfma_f32_32x32x16_bf16 v[32:47], v[84:87], v[68:71], v[32:47]
	v_mfma_f32_32x32x16_bf16 v[0:15], v[84:87], v[72:75], v[0:15]
	v_add_u32_e32 v72, s2, v81
	ds_read_b128 v[68:71], v72
	ds_read_b128 v[72:75], v72 offset:4096
	ds_read_b128 v[84:87], v83 offset:20480
	v_add_u32_e32 v81, s2, v82
	s_waitcnt lgkmcnt(0)
	v_mfma_f32_32x32x16_bf16 v[48:63], v[64:67], v[68:71], v[48:63]
	v_mfma_f32_32x32x16_bf16 v[16:31], v[64:67], v[72:75], v[16:31]
	ds_read_b128 v[64:67], v81 offset:16384
	v_mfma_f32_32x32x16_bf16 v[32:47], v[84:87], v[68:71], v[32:47]
	v_mfma_f32_32x32x16_bf16 v[0:15], v[84:87], v[72:75], v[0:15]
	v_add_u32_e32 v72, s2, v79
	ds_read_b128 v[68:71], v72
	ds_read_b128 v[72:75], v72 offset:4096
	ds_read_b128 v[82:85], v81 offset:20480
	v_add_u32_e32 v79, s2, v80
	s_waitcnt lgkmcnt(0)
	v_mfma_f32_32x32x16_bf16 v[48:63], v[64:67], v[68:71], v[48:63]
	v_mfma_f32_32x32x16_bf16 v[16:31], v[64:67], v[72:75], v[16:31]
	ds_read_b128 v[64:67], v79 offset:16384
	v_mfma_f32_32x32x16_bf16 v[32:47], v[82:85], v[68:71], v[32:47]
	v_mfma_f32_32x32x16_bf16 v[0:15], v[82:85], v[72:75], v[0:15]
	v_add_u32_e32 v72, s2, v77
	ds_read_b128 v[68:71], v72
	ds_read_b128 v[72:75], v72 offset:4096
	ds_read_b128 v[80:83], v79 offset:20480
	v_add_u32_e32 v77, s2, v78
	s_waitcnt lgkmcnt(0)
	v_mfma_f32_32x32x16_bf16 v[48:63], v[64:67], v[68:71], v[48:63]
	v_mfma_f32_32x32x16_bf16 v[16:31], v[64:67], v[72:75], v[16:31]
	ds_read_b128 v[64:67], v77 offset:16384
	v_mfma_f32_32x32x16_bf16 v[32:47], v[80:83], v[68:71], v[32:47]
	v_mfma_f32_32x32x16_bf16 v[0:15], v[80:83], v[72:75], v[0:15]
	v_add_u32_e32 v72, s2, v76
	ds_read_b128 v[68:71], v72
	ds_read_b128 v[72:75], v72 offset:4096
	ds_read_b128 v[76:79], v77 offset:20480
	s_waitcnt vmcnt(0) lgkmcnt(0)
	s_barrier
	s_waitcnt lgkmcnt(0)
	v_mfma_f32_32x32x16_bf16 v[48:63], v[64:67], v[68:71], v[48:63]
	v_mfma_f32_32x32x16_bf16 v[16:31], v[64:67], v[72:75], v[16:31]
	v_mfma_f32_32x32x16_bf16 v[32:47], v[76:79], v[68:71], v[32:47]
	v_mfma_f32_32x32x16_bf16 v[0:15], v[76:79], v[72:75], v[0:15]

; DEV int tid_l() { int t = threadIdx.x; asm volatile("" : "+v"(t)); return t; }
; DEV int stage_next(int s) { return (s == 2 * GS_STAGE) ? 0 : s + GS_STAGE; }
; template <int WAIT0>
; DEV void gk_main(f32x16 (&acc)[2][2], const GTile& t, int s0) {
;   const int tid = tid_l(), lane = tid & 63, wid = __builtin_amdgcn_readfirstlane(tid >> 6), wm = wid & 1, wn = wid >> 1, l32 = lane & 31, hi = lane >> 5;
;   GK_SRC(t)
;   const int sw = (l32 >> 1) & 7;
;   int xk[4], wk[4];
; #pragma unroll
;   for (int ks = 0; ks < 4; ++ks) { const int ko = ((2 * ks + hi) ^ sw) << 4; xk[ks] = GS_A + (64 * wm + l32) * 128 + ko; wk[ks] = GS_B + (64 * wn + l32) * 128 + ko; }
;   const int nk = t.K >> 6;
;     ...
;   vm_wait_bar<WAIT0>();
;   int stc = s0, std_ = stage_next(stage_next(s0));
.LBB0_734:
	s_cmp_lg_u32 s17, 0
	s_cbranch_scc0 .LBB0_745
	s_bitcmp0_b32 s17, 0
	s_mov_b64 s[10:11], -1
	s_cbranch_scc1 .LBB0_739
	v_mov_b32_e32 v1, v176
	s_waitcnt vmcnt(63) lgkmcnt(0)
	s_barrier
	v_readfirstlane_b32 s2, v1
	s_ashr_i32 s3, s2, 6
	v_bfe_u32 v0, v1, 3, 3
	v_and_b32_e32 v2, 31, v1
	v_lshl_or_b32 v0, s3, 3, v0
	v_lshrrev_b32_e32 v3, 1, v0
	v_and_or_b32 v6, s2, 64, v2
	s_lshr_b32 s2, s2, 1
	v_xor_b32_e32 v3, v3, v1
	s_and_b32 s2, s2, 0x1ffffc0
	v_lshlrev_b32_e32 v3, 4, v3
	v_or_b32_e32 v2, s2, v2
	s_lshl_b32 s2, s3, 10
	v_and_b32_e32 v4, 0x70, v3
	v_bfe_u32 v3, v1, 5, 1
	v_lshrrev_b32_e32 v5, 1, v1
	v_bfe_u32 v1, v1, 1, 3
	s_add_i32 s3, s2, 0
	s_add_i32 s2, s16, 0xc000
	v_bitop3_b32 v5, v3, v5, 7 bitop3:0x78
	v_bitop3_b32 v7, v3, v1, 2 bitop3:0x36
	v_bitop3_b32 v8, v3, v1, 4 bitop3:0x36
	v_bitop3_b32 v1, v3, v1, 6 bitop3:0x36
	s_cmp_lg_u32 s16, 0x18000
	v_lshlrev_b32_e32 v2, 7, v2
	v_lshlrev_b32_e32 v5, 4, v5
	v_lshlrev_b32_e32 v7, 4, v7
	v_lshlrev_b32_e32 v8, 4, v8
	v_lshlrev_b32_e32 v1, 4, v1
	s_cselect_b32 s18, s2, 0
	s_add_i32 s2, s18, 0xc000
	v_or_b32_e32 v86, v2, v5
	v_or_b32_e32 v85, v2, v7
	v_or_b32_e32 v83, v2, v8
	v_or_b32_e32 v81, v2, v1
	v_add_u32_e32 v2, 0xc0, v0
	s_cmp_lg_u32 s18, 0x18000
	v_ashrrev_i32_e32 v3, 31, v2
	s_cselect_b32 s19, s2, 0
	s_add_u32 s10, s6, 0x100
	v_lshlrev_b64 v[2:3], 11, v[2:3]
	s_addc_u32 s11, s7, 0
	v_or_b32_e32 v2, v2, v4
	v_lshl_add_u64 v[66:67], s[10:11], 0, v[2:3]
	v_add_u32_e32 v2, 0x80, v0
	v_ashrrev_i32_e32 v3, 31, v2
	v_lshlrev_b64 v[2:3], 11, v[2:3]
	v_lshlrev_b32_e32 v6, 7, v6
	v_or_b32_e32 v2, v2, v4
	v_or_b32_e32 v79, v1, v6
	v_lshl_add_u64 v[68:69], s[10:11], 0, v[2:3]
	v_add_u32_e32 v2, 64, v0
	v_ashrrev_i32_e32 v1, 31, v0
	v_ashrrev_i32_e32 v3, 31, v2
	v_lshlrev_b64 v[0:1], 11, v[0:1]
	v_lshlrev_b64 v[2:3], 11, v[2:3]
	v_or_b32_e32 v0, v0, v4
	v_or_b32_e32 v2, v2, v4
	v_lshl_add_u64 v[72:73], s[10:11], 0, v[0:1]
	v_lshl_add_u64 v[76:77], s[8:9], 0, v[0:1]
	v_mov_b32_e32 v0, 0
	v_or_b32_e32 v84, v5, v6
	v_or_b32_e32 v82, v7, v6
	v_or_b32_e32 v80, v8, v6
	v_lshl_add_u64 v[70:71], s[10:11], 0, v[2:3]
	v_lshl_add_u64 v[74:75], s[8:9], 0, v[2:3]
	s_mov_b64 s[10:11], 0
	s_mov_b32 s2, s16
	v_mov_b32_e32 v1, v0
	v_mov_b32_e32 v2, v0
	v_mov_b32_e32 v3, v0
	v_mov_b32_e32 v4, v0
	v_mov_b32_e32 v5, v0
	v_mov_b32_e32 v6, v0
	v_mov_b32_e32 v7, v0
	v_mov_b32_e32 v8, v0
	v_mov_b32_e32 v9, v0
	v_mov_b32_e32 v10, v0
	v_mov_b32_e32 v11, v0
	v_mov_b32_e32 v12, v0
	v_mov_b32_e32 v13, v0
	v_mov_b32_e32 v14, v0
	v_mov_b32_e32 v15, v0
	v_mov_b32_e32 v16, v0
	v_mov_b32_e32 v17, v0
	v_mov_b32_e32 v18, v0
	v_mov_b32_e32 v19, v0
	v_mov_b32_e32 v20, v0
	v_mov_b32_e32 v21, v0
	v_mov_b32_e32 v22, v0
	v_mov_b32_e32 v23, v0
	v_mov_b32_e32 v24, v0
	v_mov_b32_e32 v25, v0
	v_mov_b32_e32 v26, v0
	v_mov_b32_e32 v27, v0
	v_mov_b32_e32 v28, v0
	v_mov_b32_e32 v29, v0
	v_mov_b32_e32 v30, v0
	v_mov_b32_e32 v31, v0
	v_mov_b32_e32 v32, v0
	v_mov_b32_e32 v33, v0
	v_mov_b32_e32 v34, v0
	v_mov_b32_e32 v35, v0
	v_mov_b32_e32 v36, v0
	v_mov_b32_e32 v37, v0
	v_mov_b32_e32 v38, v0
	v_mov_b32_e32 v39, v0
	v_mov_b32_e32 v40, v0
	v_mov_b32_e32 v41, v0
	v_mov_b32_e32 v42, v0
	v_mov_b32_e32 v43, v0
	v_mov_b32_e32 v44, v0
	v_mov_b32_e32 v45, v0
	v_mov_b32_e32 v46, v0
	v_mov_b32_e32 v47, v0
	v_mov_b32_e32 v48, v0
	v_mov_b32_e32 v49, v0
	v_mov_b32_e32 v50, v0
	v_mov_b32_e32 v51, v0
	v_mov_b32_e32 v52, v0
	v_mov_b32_e32 v53, v0
	v_mov_b32_e32 v54, v0
	v_mov_b32_e32 v55, v0
	v_mov_b32_e32 v56, v0
	v_mov_b32_e32 v57, v0
	v_mov_b32_e32 v58, v0
	v_mov_b32_e32 v59, v0
	v_mov_b32_e32 v60, v0
	v_mov_b32_e32 v61, v0
	v_mov_b32_e32 v62, v0
	v_mov_b32_e32 v63, v0
	s_add_i32 s99, s2, 0
	v_add_u32_e32 v252, s99, v86
	v_add_u32_e32 v87, s99, v84
	ds_read_b128 v[88:91], v252 offset:16384
	ds_read_b128 v[92:95], v87
	ds_read_b128 v[96:99], v87 offset:4096
	ds_read_b128 v[100:103], v252 offset:20480
	s_mov_b64 vcc, -1
	s_branch .Lfws_737

; DEV int stage_next(int s) { return (s == 2 * GS_STAGE) ? 0 : s + GS_STAGE; }
; template <int WAIT0>
; DEV void gk_main(f32x16 (&acc)[2][2], const GTile& t, int s0) {
;     ...
;   for (int kt = 0; kt < nk - 2; ++kt) {
;     GK_DMA(std_, kt + 2);
;     GK_COMPUTE(stc);
;     vm_wait_bar<6>();
;     stc = stage_next(stc); std_ = stage_next(std_);
;   }
;   GK_COMPUTE(stc);
;   vm_wait_bar<0>();
;   stc = stage_next(stc);
;   GK_COMPUTE(stc);
;   vm_wait_bar<0>();
.Lfws_737:
.LBB0_737:
	s_add_i32 s20, s3, s19
	s_mov_b32 s98, s20
	s_mov_b64 s[100:101], s[10:11]
	s_waitcnt lgkmcnt(0)
	v_add_u32_e32 v104, s99, v85
	v_add_u32_e32 v87, s99, v82
	s_add_i32 s20, s2, 0xc000
	s_cmp_lg_u32 s2, 0x18000
	s_cselect_b32 s2, s20, 0
	s_add_i32 s20, s19, 0xc000
	s_cmp_lg_u32 s19, 0x18000
	s_cselect_b32 s19, s20, 0
	s_add_u32 s10, s10, 0x80
	s_addc_u32 s11, s11, 0
	ds_read_b128 v[236:239], v104 offset:16384
	ds_read_b128 v[240:243], v87
	ds_read_b128 v[244:247], v87 offset:4096
	ds_read_b128 v[248:251], v104 offset:20480
	v_mfma_f32_32x32x16_bf16 v[48:63], v[88:91], v[92:95], v[48:63]
	v_mfma_f32_32x32x16_bf16 v[32:47], v[88:91], v[96:99], v[32:47]
	s_mov_b32 m0, s98
	v_lshl_add_u64 v[254:255], v[76:77], 0, s[100:101]
	global_load_lds_dwordx4 v[254:255], off
	v_mfma_f32_32x32x16_bf16 v[16:31], v[100:103], v[92:95], v[16:31]
	v_mfma_f32_32x32x16_bf16 v[0:15], v[100:103], v[96:99], v[0:15]
	s_add_i32 m0, s98, 0x2000
	v_lshl_add_u64 v[254:255], v[74:75], 0, s[100:101]
	global_load_lds_dwordx4 v[254:255], off
	v_add_u32_e32 v104, s99, v83
	v_add_u32_e32 v87, s99, v80
	s_waitcnt lgkmcnt(0)
	ds_read_b128 v[88:91], v104 offset:16384
	ds_read_b128 v[92:95], v87
	ds_read_b128 v[96:99], v87 offset:4096
	ds_read_b128 v[100:103], v104 offset:20480
	v_mfma_f32_32x32x16_bf16 v[48:63], v[236:239], v[240:243], v[48:63]
	v_mfma_f32_32x32x16_bf16 v[32:47], v[236:239], v[244:247], v[32:47]
	s_add_i32 m0, s98, 0x4000
	v_lshl_add_u64 v[254:255], v[72:73], 0, s[100:101]
	global_load_lds_dwordx4 v[254:255], off
	v_mfma_f32_32x32x16_bf16 v[16:31], v[248:251], v[240:243], v[16:31]
	v_mfma_f32_32x32x16_bf16 v[0:15], v[248:251], v[244:247], v[0:15]
	s_add_i32 m0, s98, 0x6000
	v_lshl_add_u64 v[254:255], v[70:71], 0, s[100:101]
	global_load_lds_dwordx4 v[254:255], off
	v_add_u32_e32 v104, s99, v81
	v_add_u32_e32 v87, s99, v79
	s_waitcnt lgkmcnt(0)
	ds_read_b128 v[236:239], v104 offset:16384
	ds_read_b128 v[240:243], v87
	ds_read_b128 v[244:247], v87 offset:4096
	ds_read_b128 v[248:251], v104 offset:20480
	v_mfma_f32_32x32x16_bf16 v[48:63], v[88:91], v[92:95], v[48:63]
	v_mfma_f32_32x32x16_bf16 v[32:47], v[88:91], v[96:99], v[32:47]
	s_add_i32 m0, s98, 0x8000
	v_lshl_add_u64 v[254:255], v[68:69], 0, s[100:101]
	global_load_lds_dwordx4 v[254:255], off
	v_mfma_f32_32x32x16_bf16 v[16:31], v[100:103], v[92:95], v[16:31]
	v_mfma_f32_32x32x16_bf16 v[0:15], v[100:103], v[96:99], v[0:15]
	s_add_i32 m0, s98, 0xa000
	v_lshl_add_u64 v[254:255], v[66:67], 0, s[100:101]
	global_load_lds_dwordx4 v[254:255], off
	s_cbranch_vccnz .Lfw_737
	s_waitcnt vmcnt(6) lgkmcnt(0)
	s_barrier
.Lfwb_737:
	s_waitcnt lgkmcnt(0)
	s_add_i32 s99, s2, 0
	v_add_u32_e32 v252, s99, v86
	v_add_u32_e32 v87, s99, v84
	ds_read_b128 v[88:91], v252 offset:16384
	ds_read_b128 v[92:95], v87
	ds_read_b128 v[96:99], v87 offset:4096
	ds_read_b128 v[100:103], v252 offset:20480
	v_mfma_f32_32x32x16_bf16 v[48:63], v[236:239], v[240:243], v[48:63]
	v_mfma_f32_32x32x16_bf16 v[32:47], v[236:239], v[244:247], v[32:47]
	v_mfma_f32_32x32x16_bf16 v[16:31], v[248:251], v[240:243], v[16:31]
	v_mfma_f32_32x32x16_bf16 v[0:15], v[248:251], v[244:247], v[0:15]
	s_cmpk_lg_i32 s10, 0x700
	s_cbranch_scc1 .LBB0_737
	s_waitcnt lgkmcnt(0)
	s_add_i32 s3, s2, 0
	v_add_u32_e32 v87, s3, v86
	ds_read_b128 v[66:69], v87 offset:16384
	v_add_u32_e32 v74, s3, v84
	ds_read_b128 v[70:73], v74
	ds_read_b128 v[74:77], v74 offset:4096
	ds_read_b128 v[88:91], v87 offset:20480
	v_add_u32_e32 v87, s3, v85
	s_mov_b64 s[10:11], 0
	s_waitcnt lgkmcnt(0)
	v_mfma_f32_32x32x16_bf16 v[0:15], v[88:91], v[74:77], v[0:15]
	v_mfma_f32_32x32x16_bf16 v[48:63], v[66:69], v[70:73], v[48:63]
	v_mfma_f32_32x32x16_bf16 v[32:47], v[66:69], v[74:77], v[32:47]
	ds_read_b128 v[66:69], v87 offset:16384
	v_add_u32_e32 v74, s3, v82
	v_mfma_f32_32x32x16_bf16 v[16:31], v[88:91], v[70:73], v[16:31]
	ds_read_b128 v[70:73], v74
	ds_read_b128 v[74:77], v74 offset:4096
	ds_read_b128 v[88:91], v87 offset:20480
	v_add_u32_e32 v87, s3, v83
	s_waitcnt lgkmcnt(0)
	v_mfma_f32_32x32x16_bf16 v[48:63], v[66:69], v[70:73], v[48:63]
	v_mfma_f32_32x32x16_bf16 v[32:47], v[66:69], v[74:77], v[32:47]
	ds_read_b128 v[66:69], v87 offset:16384
	v_mfma_f32_32x32x16_bf16 v[0:15], v[88:91], v[74:77], v[0:15]
	v_add_u32_e32 v74, s3, v80
	v_mfma_f32_32x32x16_bf16 v[16:31], v[88:91], v[70:73], v[16:31]
	ds_read_b128 v[70:73], v74
	ds_read_b128 v[74:77], v74 offset:4096
	ds_read_b128 v[88:91], v87 offset:20480
	v_add_u32_e32 v87, s3, v81
	s_waitcnt lgkmcnt(0)
	v_mfma_f32_32x32x16_bf16 v[48:63], v[66:69], v[70:73], v[48:63]
	v_mfma_f32_32x32x16_bf16 v[32:47], v[66:69], v[74:77], v[32:47]
	ds_read_b128 v[66:69], v87 offset:16384
	v_mfma_f32_32x32x16_bf16 v[0:15], v[88:91], v[74:77], v[0:15]
	v_add_u32_e32 v74, s3, v79
	s_add_i32 s3, s2, 0xc000
	s_cmp_lg_u32 s2, 0x18000
	s_cselect_b32 s2, s3, 0
	s_add_i32 s2, s2, 0
	v_add_u32_e32 v86, s2, v86
	v_mfma_f32_32x32x16_bf16 v[16:31], v[88:91], v[70:73], v[16:31]
	ds_read_b128 v[70:73], v74
	ds_read_b128 v[74:77], v74 offset:4096
	ds_read_b128 v[88:91], v87 offset:20480
	s_waitcnt vmcnt(0) lgkmcnt(0)
	s_barrier
; DEV int tid_l() { int t = threadIdx.x; asm volatile("" : "+v"(t)); return t; }
; DEV int stage_next(int s) { return (s == 2 * GS_STAGE) ? 0 : s + GS_STAGE; }
; template <int WAIT0>
; DEV void gk_main(f32x16 (&acc)[2][2], const GTile& t, int s0) {
;   const int tid = tid_l(), lane = tid & 63, wid = __builtin_amdgcn_readfirstlane(tid >> 6), wm = wid & 1, wn = wid >> 1, l32 = lane & 31, hi = lane >> 5;
;   GK_SRC(t)
;   const int sw = (l32 >> 1) & 7;
;   int xk[4], wk[4];
; #pragma unroll
;   for (int ks = 0; ks < 4; ++ks) { const int ko = ((2 * ks + hi) ^ sw) << 4; xk[ks] = GS_A + (64 * wm + l32) * 128 + ko; wk[ks] = GS_B + (64 * wn + l32) * 128 + ko; }
;   const int nk = t.K >> 6;
;     ...
;   vm_wait_bar<WAIT0>();
;   int stc = s0, std_ = stage_next(stage_next(s0));
;     ...
;   GK_COMPUTE(stc);
;   vm_wait_bar<0>();
;   stc = stage_next(stc);
;   GK_COMPUTE(stc);
;   vm_wait_bar<0>();
	s_waitcnt lgkmcnt(0)
	v_mfma_f32_32x32x16_bf16 v[48:63], v[66:69], v[70:73], v[48:63]
	v_mfma_f32_32x32x16_bf16 v[32:47], v[66:69], v[74:77], v[32:47]
	ds_read_b128 v[66:69], v86 offset:16384
	v_mfma_f32_32x32x16_bf16 v[16:31], v[88:91], v[70:73], v[16:31]
	v_mfma_f32_32x32x16_bf16 v[0:15], v[88:91], v[74:77], v[0:15]
	v_add_u32_e32 v74, s2, v84
	ds_read_b128 v[70:73], v74
	ds_read_b128 v[74:77], v74 offset:4096
	ds_read_b128 v[86:89], v86 offset:20480
	v_add_u32_e32 v84, s2, v85
	s_waitcnt lgkmcnt(0)
	v_mfma_f32_32x32x16_bf16 v[48:63], v[66:69], v[70:73], v[48:63]
	v_mfma_f32_32x32x16_bf16 v[32:47], v[66:69], v[74:77], v[32:47]
	ds_read_b128 v[66:69], v84 offset:16384
	v_mfma_f32_32x32x16_bf16 v[16:31], v[86:89], v[70:73], v[16:31]
	v_mfma_f32_32x32x16_bf16 v[0:15], v[86:89], v[74:77], v[0:15]
	v_add_u32_e32 v74, s2, v82
	ds_read_b128 v[70:73], v74
	ds_read_b128 v[74:77], v74 offset:4096
	ds_read_b128 v[84:87], v84 offset:20480
	v_add_u32_e32 v82, s2, v83
	s_waitcnt lgkmcnt(0)
	v_mfma_f32_32x32x16_bf16 v[48:63], v[66:69], v[70:73], v[48:63]
	v_mfma_f32_32x32x16_bf16 v[32:47], v[66:69], v[74:77], v[32:47]
	ds_read_b128 v[66:69], v82 offset:16384
	v_mfma_f32_32x32x16_bf16 v[16:31], v[84:87], v[70:73], v[16:31]
	v_mfma_f32_32x32x16_bf16 v[0:15], v[84:87], v[74:77], v[0:15]
	v_add_u32_e32 v74, s2, v80
	ds_read_b128 v[70:73], v74
	ds_read_b128 v[74:77], v74 offset:4096
	ds_read_b128 v[82:85], v82 offset:20480
	v_add_u32_e32 v80, s2, v81
	s_waitcnt lgkmcnt(0)
	v_mfma_f32_32x32x16_bf16 v[48:63], v[66:69], v[70:73], v[48:63]
	v_mfma_f32_32x32x16_bf16 v[32:47], v[66:69], v[74:77], v[32:47]
	ds_read_b128 v[66:69], v80 offset:16384
	v_mfma_f32_32x32x16_bf16 v[16:31], v[82:85], v[70:73], v[16:31]
	v_mfma_f32_32x32x16_bf16 v[0:15], v[82:85], v[74:77], v[0:15]
	v_add_u32_e32 v74, s2, v79
	ds_read_b128 v[70:73], v74
	ds_read_b128 v[74:77], v74 offset:4096
	ds_read_b128 v[80:83], v80 offset:20480
	s_waitcnt vmcnt(0) lgkmcnt(0)
	s_barrier
	s_waitcnt lgkmcnt(0)
	v_mfma_f32_32x32x16_bf16 v[48:63], v[66:69], v[70:73], v[48:63]
	v_mfma_f32_32x32x16_bf16 v[32:47], v[66:69], v[74:77], v[32:47]
	v_mfma_f32_32x32x16_bf16 v[16:31], v[80:83], v[70:73], v[16:31]
	v_mfma_f32_32x32x16_bf16 v[0:15], v[80:83], v[74:77], v[0:15]
.LBB0_739:
	s_and_b64 vcc, exec, s[10:11]
	s_cbranch_vccz .LBB0_743
	s_nop 9
	v_mov_b32_e32 v1, v176
	s_waitcnt vmcnt(63) lgkmcnt(0)
	s_barrier
	v_readfirstlane_b32 s2, v1
	s_ashr_i32 s3, s2, 6
	v_bfe_u32 v0, v1, 3, 3
	v_and_b32_e32 v2, 31, v1
	v_lshl_or_b32 v0, s3, 3, v0
	v_lshrrev_b32_e32 v3, 1, v0
	v_and_or_b32 v6, s2, 64, v2
	s_lshr_b32 s2, s2, 1
	v_xor_b32_e32 v3, v3, v1
	s_and_b32 s2, s2, 0x1ffffc0
	v_lshlrev_b32_e32 v3, 4, v3
	v_or_b32_e32 v2, s2, v2
	s_lshl_b32 s2, s3, 10
	v_and_b32_e32 v4, 0x70, v3
	v_bfe_u32 v3, v1, 5, 1
	v_lshrrev_b32_e32 v5, 1, v1
	v_bfe_u32 v1, v1, 1, 3
	s_add_i32 s3, s2, 0
	s_add_i32 s2, s16, 0xc000
	v_bitop3_b32 v5, v3, v5, 7 bitop3:0x78
	v_bitop3_b32 v7, v3, v1, 2 bitop3:0x36
	v_bitop3_b32 v8, v3, v1, 4 bitop3:0x36
	v_bitop3_b32 v1, v3, v1, 6 bitop3:0x36
	s_cmp_lg_u32 s16, 0x18000
	v_lshlrev_b32_e32 v2, 7, v2
	v_lshlrev_b32_e32 v5, 4, v5
	v_lshlrev_b32_e32 v7, 4, v7
	v_lshlrev_b32_e32 v8, 4, v8
	v_lshlrev_b32_e32 v1, 4, v1
	s_cselect_b32 s18, s2, 0
	s_add_i32 s2, s18, 0xc000
	v_or_b32_e32 v86, v2, v5
	v_or_b32_e32 v85, v2, v7
	v_or_b32_e32 v83, v2, v8
	v_or_b32_e32 v81, v2, v1
	v_add_u32_e32 v2, 0xc0, v0
	s_cmp_lg_u32 s18, 0x18000
	v_ashrrev_i32_e32 v3, 31, v2
	s_cselect_b32 s19, s2, 0
	s_add_u32 s10, s6, 0x100
	v_lshlrev_b64 v[2:3], 11, v[2:3]
	s_addc_u32 s11, s7, 0
	v_or_b32_e32 v2, v2, v4
	v_lshl_add_u64 v[66:67], s[10:11], 0, v[2:3]
	v_add_u32_e32 v2, 0x80, v0
	v_ashrrev_i32_e32 v3, 31, v2
	v_lshlrev_b64 v[2:3], 11, v[2:3]
	v_lshlrev_b32_e32 v6, 7, v6
	v_or_b32_e32 v2, v2, v4
	v_or_b32_e32 v79, v1, v6
	v_lshl_add_u64 v[68:69], s[10:11], 0, v[2:3]
	v_add_u32_e32 v2, 64, v0
	v_ashrrev_i32_e32 v1, 31, v0
	v_ashrrev_i32_e32 v3, 31, v2
	v_lshlrev_b64 v[0:1], 11, v[0:1]
	v_lshlrev_b64 v[2:3], 11, v[2:3]
	v_or_b32_e32 v0, v0, v4
	v_or_b32_e32 v2, v2, v4
	v_lshl_add_u64 v[72:73], s[10:11], 0, v[0:1]
	v_lshl_add_u64 v[76:77], s[8:9], 0, v[0:1]
	v_mov_b32_e32 v0, 0
	v_or_b32_e32 v84, v5, v6
	v_or_b32_e32 v82, v7, v6
	v_or_b32_e32 v80, v8, v6
	v_lshl_add_u64 v[70:71], s[10:11], 0, v[2:3]
	v_lshl_add_u64 v[74:75], s[8:9], 0, v[2:3]
	s_mov_b64 s[10:11], 0
	s_mov_b32 s2, s16
	v_mov_b32_e32 v1, v0
	v_mov_b32_e32 v2, v0
	v_mov_b32_e32 v3, v0
	v_mov_b32_e32 v4, v0
	v_mov_b32_e32 v5, v0
	v_mov_b32_e32 v6, v0
	v_mov_b32_e32 v7, v0
	v_mov_b32_e32 v8, v0
	v_mov_b32_e32 v9, v0
	v_mov_b32_e32 v10, v0
	v_mov_b32_e32 v11, v0
	v_mov_b32_e32 v12, v0
	v_mov_b32_e32 v13, v0
	v_mov_b32_e32 v14, v0
	v_mov_b32_e32 v15, v0
	v_mov_b32_e32 v16, v0
	v_mov_b32_e32 v17, v0
	v_mov_b32_e32 v18, v0
	v_mov_b32_e32 v19, v0
	v_mov_b32_e32 v20, v0
	v_mov_b32_e32 v21, v0
	v_mov_b32_e32 v22, v0
	v_mov_b32_e32 v23, v0
	v_mov_b32_e32 v24, v0
	v_mov_b32_e32 v25, v0
	v_mov_b32_e32 v26, v0
	v_mov_b32_e32 v27, v0
	v_mov_b32_e32 v28, v0
	v_mov_b32_e32 v29, v0
	v_mov_b32_e32 v30, v0
	v_mov_b32_e32 v31, v0
	v_mov_b32_e32 v32, v0
	v_mov_b32_e32 v33, v0
	v_mov_b32_e32 v34, v0
	v_mov_b32_e32 v35, v0
	v_mov_b32_e32 v36, v0
	v_mov_b32_e32 v37, v0
	v_mov_b32_e32 v38, v0
	v_mov_b32_e32 v39, v0
	v_mov_b32_e32 v40, v0
	v_mov_b32_e32 v41, v0
	v_mov_b32_e32 v42, v0
	v_mov_b32_e32 v43, v0
	v_mov_b32_e32 v44, v0
	v_mov_b32_e32 v45, v0
	v_mov_b32_e32 v46, v0
	v_mov_b32_e32 v47, v0
	v_mov_b32_e32 v48, v0
	v_mov_b32_e32 v49, v0
	v_mov_b32_e32 v50, v0
	v_mov_b32_e32 v51, v0
	v_mov_b32_e32 v52, v0
	v_mov_b32_e32 v53, v0
	v_mov_b32_e32 v54, v0
	v_mov_b32_e32 v55, v0
	v_mov_b32_e32 v56, v0
	v_mov_b32_e32 v57, v0
	v_mov_b32_e32 v58, v0
	v_mov_b32_e32 v59, v0
	v_mov_b32_e32 v60, v0
	v_mov_b32_e32 v61, v0
	v_mov_b32_e32 v62, v0
	v_mov_b32_e32 v63, v0
	s_add_i32 s99, s2, 0
	v_add_u32_e32 v252, s99, v86
	v_add_u32_e32 v87, s99, v84
	ds_read_b128 v[88:91], v252 offset:16384
	ds_read_b128 v[92:95], v87
	ds_read_b128 v[96:99], v87 offset:4096
	ds_read_b128 v[100:103], v252 offset:20480
	s_mov_b64 vcc, -1
	s_branch .Lfws_741

; DEV int stage_next(int s) { return (s == 2 * GS_STAGE) ? 0 : s + GS_STAGE; }
; template <int WAIT0>
; DEV void gk_main(f32x16 (&acc)[2][2], const GTile& t, int s0) {
;     ...
;   for (int kt = 0; kt < nk - 2; ++kt) {
;     GK_DMA(std_, kt + 2);
;     GK_COMPUTE(stc);
;     vm_wait_bar<6>();
;     stc = stage_next(stc); std_ = stage_next(std_);
;   }
;   GK_COMPUTE(stc);
;   vm_wait_bar<0>();
;   stc = stage_next(stc);
;   GK_COMPUTE(stc);
;   vm_wait_bar<0>();
.Lfwb_741:
	s_waitcnt lgkmcnt(0)
	s_add_i32 s99, s2, 0
	v_add_u32_e32 v252, s99, v86
	v_add_u32_e32 v87, s99, v84
	ds_read_b128 v[88:91], v252 offset:16384
	ds_read_b128 v[92:95], v87
	ds_read_b128 v[96:99], v87 offset:4096
	ds_read_b128 v[100:103], v252 offset:20480
	v_mfma_f32_32x32x16_bf16 v[48:63], v[236:239], v[240:243], v[48:63]
	v_mfma_f32_32x32x16_bf16 v[32:47], v[236:239], v[244:247], v[32:47]
	v_mfma_f32_32x32x16_bf16 v[16:31], v[248:251], v[240:243], v[16:31]
	v_mfma_f32_32x32x16_bf16 v[0:15], v[248:251], v[244:247], v[0:15]
	s_cmpk_lg_i32 s10, 0x700
	s_cbranch_scc1 .LBB0_741
	s_waitcnt lgkmcnt(0)
	s_add_i32 s3, s2, 0
	v_add_u32_e32 v87, s3, v86
	ds_read_b128 v[66:69], v87 offset:16384
	v_add_u32_e32 v74, s3, v84
	ds_read_b128 v[70:73], v74
	ds_read_b128 v[74:77], v74 offset:4096
	ds_read_b128 v[88:91], v87 offset:20480
	v_add_u32_e32 v87, s3, v85
	s_waitcnt lgkmcnt(0)
	v_mfma_f32_32x32x16_bf16 v[0:15], v[88:91], v[74:77], v[0:15]
	v_mfma_f32_32x32x16_bf16 v[48:63], v[66:69], v[70:73], v[48:63]
	v_mfma_f32_32x32x16_bf16 v[32:47], v[66:69], v[74:77], v[32:47]
	ds_read_b128 v[66:69], v87 offset:16384
	v_add_u32_e32 v74, s3, v82
	v_mfma_f32_32x32x16_bf16 v[16:31], v[88:91], v[70:73], v[16:31]
	ds_read_b128 v[70:73], v74
	ds_read_b128 v[74:77], v74 offset:4096
	ds_read_b128 v[88:91], v87 offset:20480
	v_add_u32_e32 v87, s3, v83
	s_waitcnt lgkmcnt(0)
	v_mfma_f32_32x32x16_bf16 v[48:63], v[66:69], v[70:73], v[48:63]
	v_mfma_f32_32x32x16_bf16 v[32:47], v[66:69], v[74:77], v[32:47]
	ds_read_b128 v[66:69], v87 offset:16384
	v_mfma_f32_32x32x16_bf16 v[0:15], v[88:91], v[74:77], v[0:15]
	v_add_u32_e32 v74, s3, v80
	v_mfma_f32_32x32x16_bf16 v[16:31], v[88:91], v[70:73], v[16:31]
	ds_read_b128 v[70:73], v74
	ds_read_b128 v[74:77], v74 offset:4096
	ds_read_b128 v[88:91], v87 offset:20480
	v_add_u32_e32 v87, s3, v81
	s_waitcnt lgkmcnt(0)
	v_mfma_f32_32x32x16_bf16 v[48:63], v[66:69], v[70:73], v[48:63]
	v_mfma_f32_32x32x16_bf16 v[32:47], v[66:69], v[74:77], v[32:47]
	ds_read_b128 v[66:69], v87 offset:16384
	v_mfma_f32_32x32x16_bf16 v[0:15], v[88:91], v[74:77], v[0:15]
	v_add_u32_e32 v74, s3, v79
	s_add_i32 s3, s2, 0xc000
	s_cmp_lg_u32 s2, 0x18000
	s_cselect_b32 s2, s3, 0
	s_add_i32 s2, s2, 0
	v_add_u32_e32 v86, s2, v86
	v_mfma_f32_32x32x16_bf16 v[16:31], v[88:91], v[70:73], v[16:31]
	ds_read_b128 v[70:73], v74
	ds_read_b128 v[74:77], v74 offset:4096
	ds_read_b128 v[88:91], v87 offset:20480
	s_waitcnt vmcnt(0) lgkmcnt(0)
	s_barrier
	s_waitcnt lgkmcnt(0)
	v_mfma_f32_32x32x16_bf16 v[48:63], v[66:69], v[70:73], v[48:63]
	v_mfma_f32_32x32x16_bf16 v[32:47], v[66:69], v[74:77], v[32:47]
	ds_read_b128 v[66:69], v86 offset:16384
	v_mfma_f32_32x32x16_bf16 v[16:31], v[88:91], v[70:73], v[16:31]
	v_mfma_f32_32x32x16_bf16 v[0:15], v[88:91], v[74:77], v[0:15]
	v_add_u32_e32 v74, s2, v84
	ds_read_b128 v[70:73], v74
	ds_read_b128 v[74:77], v74 offset:4096
	ds_read_b128 v[86:89], v86 offset:20480
	v_add_u32_e32 v84, s2, v85
	s_waitcnt lgkmcnt(0)
	v_mfma_f32_32x32x16_bf16 v[48:63], v[66:69], v[70:73], v[48:63]
	v_mfma_f32_32x32x16_bf16 v[32:47], v[66:69], v[74:77], v[32:47]
	ds_read_b128 v[66:69], v84 offset:16384
	v_mfma_f32_32x32x16_bf16 v[16:31], v[86:89], v[70:73], v[16:31]
	v_mfma_f32_32x32x16_bf16 v[0:15], v[86:89], v[74:77], v[0:15]
	v_add_u32_e32 v74, s2, v82
	ds_read_b128 v[70:73], v74
	ds_read_b128 v[74:77], v74 offset:4096
	ds_read_b128 v[84:87], v84 offset:20480
	v_add_u32_e32 v82, s2, v83
	s_waitcnt lgkmcnt(0)
	v_mfma_f32_32x32x16_bf16 v[48:63], v[66:69], v[70:73], v[48:63]
	v_mfma_f32_32x32x16_bf16 v[32:47], v[66:69], v[74:77], v[32:47]
	ds_read_b128 v[66:69], v82 offset:16384
	v_mfma_f32_32x32x16_bf16 v[16:31], v[84:87], v[70:73], v[16:31]
	v_mfma_f32_32x32x16_bf16 v[0:15], v[84:87], v[74:77], v[0:15]
	v_add_u32_e32 v74, s2, v80
	ds_read_b128 v[70:73], v74
	ds_read_b128 v[74:77], v74 offset:4096
	ds_read_b128 v[82:85], v82 offset:20480
	v_add_u32_e32 v80, s2, v81
	s_waitcnt lgkmcnt(0)
	v_mfma_f32_32x32x16_bf16 v[48:63], v[66:69], v[70:73], v[48:63]
	v_mfma_f32_32x32x16_bf16 v[32:47], v[66:69], v[74:77], v[32:47]
	ds_read_b128 v[66:69], v80 offset:16384
	v_mfma_f32_32x32x16_bf16 v[16:31], v[82:85], v[70:73], v[16:31]
	v_mfma_f32_32x32x16_bf16 v[0:15], v[82:85], v[74:77], v[0:15]
	v_add_u32_e32 v74, s2, v79
	ds_read_b128 v[70:73], v74
	ds_read_b128 v[74:77], v74 offset:4096
	ds_read_b128 v[80:83], v80 offset:20480
	s_waitcnt vmcnt(0) lgkmcnt(0)
	s_barrier
	s_waitcnt lgkmcnt(0)
	v_mfma_f32_32x32x16_bf16 v[48:63], v[66:69], v[70:73], v[48:63]
	v_mfma_f32_32x32x16_bf16 v[32:47], v[66:69], v[74:77], v[32:47]
	v_mfma_f32_32x32x16_bf16 v[16:31], v[80:83], v[70:73], v[16:31]
	v_mfma_f32_32x32x16_bf16 v[0:15], v[80:83], v[74:77], v[0:15]

; DEV int tid_l() { int t = threadIdx.x; asm volatile("" : "+v"(t)); return t; }
; DEV int stage_next(int s) { return (s == 2 * GS_STAGE) ? 0 : s + GS_STAGE; }
; template <int WAIT0>
; DEV void gk_main(f32x16 (&acc)[2][2], const GTile& t, int s0) {
;   const int tid = tid_l(), lane = tid & 63, wid = __builtin_amdgcn_readfirstlane(tid >> 6), wm = wid & 1, wn = wid >> 1, l32 = lane & 31, hi = lane >> 5;
;   GK_SRC(t)
;   const int sw = (l32 >> 1) & 7;
;   int xk[4], wk[4];
; #pragma unroll
;   for (int ks = 0; ks < 4; ++ks) { const int ko = ((2 * ks + hi) ^ sw) << 4; xk[ks] = GS_A + (64 * wm + l32) * 128 + ko; wk[ks] = GS_B + (64 * wn + l32) * 128 + ko; }
;   const int nk = t.K >> 6;
;     ...
;   vm_wait_bar<WAIT0>();
;   int stc = s0, std_ = stage_next(stage_next(s0));
.LBB0_844:
	s_and_b64 vcc, exec, s[8:9]
	s_cbranch_vccz .LBB0_848
	s_nop 9
	v_mov_b32_e32 v0, v176
	s_lshr_b32 s8, s16, 6
	v_readfirstlane_b32 s2, v0
	v_and_b32_e32 v1, 31, v0
	s_ashr_i32 s3, s2, 6
	v_and_or_b32 v7, s2, 64, v1
	s_lshr_b32 s2, s2, 1
	s_and_b32 s2, s2, 0x1ffffc0
	v_bfe_u32 v2, v0, 3, 3
	v_or_b32_e32 v1, s2, v1
	s_lshl_b32 s2, s3, 10
	v_lshl_or_b32 v4, s3, 3, v2
	s_add_i32 s3, s18, 0xc000
	s_add_i32 s2, s2, 0
	s_cmp_lg_u32 s18, 0x18000
	s_cselect_b32 s17, s3, 0
	s_add_i32 s3, s17, 0xc000
	v_lshrrev_b32_e32 v2, 1, v4
	v_bfe_u32 v3, v0, 5, 1
	v_lshrrev_b32_e32 v5, 1, v0
	v_bfe_u32 v6, v0, 1, 3
	s_cmp_lg_u32 s17, 0x18000
	v_bitop3_b32 v5, v3, v5, 7 bitop3:0x78
	v_bitop3_b32 v8, v3, v6, 2 bitop3:0x36
	v_bitop3_b32 v9, v3, v6, 4 bitop3:0x36
	v_bitop3_b32 v3, v3, v6, 6 bitop3:0x36
	s_cselect_b32 s3, s3, 0
	s_add_i32 s8, s8, -2
	v_bitop3_b32 v0, v2, 7, v0 bitop3:0x48
	v_lshlrev_b32_e32 v1, 7, v1
	v_lshlrev_b32_e32 v5, 4, v5
	v_lshlrev_b32_e32 v8, 4, v8
	v_lshlrev_b32_e32 v9, 4, v9
	v_lshlrev_b32_e32 v3, 4, v3
	v_lshlrev_b32_e32 v120, 4, v0
	s_add_u32 s10, s6, 0x100
	v_add_u32_e32 v0, 0xc0, v4
	v_lshlrev_b32_e32 v7, 7, v7
	v_or_b32_e32 v83, v1, v5
	v_or_b32_e32 v82, v1, v8
	v_or_b32_e32 v80, v1, v9
	v_or_b32_e32 v78, v1, v3
	s_addc_u32 s11, s7, 0
	v_ashrrev_i32_e32 v1, 31, v0
	v_or_b32_e32 v76, v3, v7
	v_alignbit_b32 v3, v1, v0, 31
	v_lshlrev_b32_e32 v2, 1, v0
	v_mov_b64_e32 v[0:1], s[10:11]
	v_mad_u64_u32 v[64:65], s[10:11], v2, s16, v[0:1]
	v_mov_b32_e32 v2, v65
	v_mad_u64_u32 v[2:3], s[10:11], v3, s16, v[2:3]
	v_mov_b32_e32 v65, v2
	v_add_u32_e32 v2, 0x80, v4
	v_ashrrev_i32_e32 v3, 31, v2
	v_alignbit_b32 v3, v3, v2, 31
	v_lshlrev_b32_e32 v2, 1, v2
	v_mad_u64_u32 v[66:67], s[10:11], v2, s16, v[0:1]
	v_mov_b32_e32 v2, v67
	v_mad_u64_u32 v[2:3], s[10:11], v3, s16, v[2:3]
	v_add_u32_e32 v3, 64, v4
	v_lshlrev_b32_e32 v6, 1, v3
	v_or_b32_e32 v81, v5, v7
	v_ashrrev_i32_e32 v5, 31, v3
	v_mad_u64_u32 v[68:69], s[10:11], v6, s16, v[0:1]
	v_mov_b32_e32 v67, v2
	v_mov_b32_e32 v2, v69
	v_alignbit_b32 v5, v5, v3, 31
	v_or_b32_e32 v79, v8, v7
	v_or_b32_e32 v77, v9, v7
	v_mad_u64_u32 v[2:3], s[10:11], v5, s16, v[2:3]
	v_lshlrev_b32_e32 v7, 1, v4
	v_mov_b32_e32 v69, v2
	v_ashrrev_i32_e32 v2, 31, v4
	v_mad_u64_u32 v[70:71], s[10:11], v7, s16, v[0:1]
	v_mov_b32_e32 v0, v71
	v_alignbit_b32 v4, v2, v4, 31
	v_mad_u64_u32 v[0:1], s[10:11], v4, s16, v[0:1]
	s_add_u32 s10, s4, 0x100
	s_addc_u32 s11, s5, 0
	v_mov_b32_e32 v71, v0
	v_mov_b64_e32 v[0:1], s[10:11]
	v_mad_u64_u32 v[74:75], s[10:11], v7, s16, v[0:1]
	v_mad_u64_u32 v[72:73], s[10:11], v6, s16, v[0:1]
	v_mov_b32_e32 v0, v75
	s_waitcnt vmcnt(22) lgkmcnt(0)
	s_barrier
	v_mov_b32_e32 v2, v73
	v_mad_u64_u32 v[0:1], s[10:11], v4, s16, v[0:1]
	v_mad_u64_u32 v[2:3], s[10:11], v5, s16, v[2:3]
	v_mov_b32_e32 v75, v0
	v_mov_b32_e32 v0, 0
	v_mov_b32_e32 v73, v2
	s_mov_b32 s9, s18
	v_mov_b32_e32 v1, v0
	v_mov_b32_e32 v2, v0
	v_mov_b32_e32 v3, v0
	v_mov_b32_e32 v4, v0
	v_mov_b32_e32 v5, v0
	v_mov_b32_e32 v6, v0
	v_mov_b32_e32 v7, v0
	v_mov_b32_e32 v8, v0
	v_mov_b32_e32 v9, v0
	v_mov_b32_e32 v10, v0
	v_mov_b32_e32 v11, v0
	v_mov_b32_e32 v12, v0
	v_mov_b32_e32 v13, v0
	v_mov_b32_e32 v14, v0
	v_mov_b32_e32 v15, v0
	v_mov_b32_e32 v16, v0
	v_mov_b32_e32 v17, v0
	v_mov_b32_e32 v18, v0
	v_mov_b32_e32 v19, v0
	v_mov_b32_e32 v20, v0
	v_mov_b32_e32 v21, v0
	v_mov_b32_e32 v22, v0
	v_mov_b32_e32 v23, v0
	v_mov_b32_e32 v24, v0
	v_mov_b32_e32 v25, v0
	v_mov_b32_e32 v26, v0
	v_mov_b32_e32 v27, v0
	v_mov_b32_e32 v28, v0
	v_mov_b32_e32 v29, v0
	v_mov_b32_e32 v30, v0
	v_mov_b32_e32 v31, v0
	v_mov_b32_e32 v32, v0
	v_mov_b32_e32 v33, v0
	v_mov_b32_e32 v34, v0
	v_mov_b32_e32 v35, v0
	v_mov_b32_e32 v36, v0
	v_mov_b32_e32 v37, v0
	v_mov_b32_e32 v38, v0
	v_mov_b32_e32 v39, v0
	v_mov_b32_e32 v40, v0
	v_mov_b32_e32 v41, v0
	v_mov_b32_e32 v42, v0
	v_mov_b32_e32 v43, v0
	v_mov_b32_e32 v44, v0
	v_mov_b32_e32 v45, v0
	v_mov_b32_e32 v46, v0
	v_mov_b32_e32 v47, v0
	v_mov_b32_e32 v48, v0
	v_mov_b32_e32 v49, v0
	v_mov_b32_e32 v50, v0
	v_mov_b32_e32 v51, v0
	v_mov_b32_e32 v52, v0
	v_mov_b32_e32 v53, v0
	v_mov_b32_e32 v54, v0
	v_mov_b32_e32 v55, v0
	v_mov_b32_e32 v56, v0
	v_mov_b32_e32 v57, v0
	v_mov_b32_e32 v58, v0
	v_mov_b32_e32 v59, v0
	v_mov_b32_e32 v60, v0
	v_mov_b32_e32 v61, v0
	v_mov_b32_e32 v62, v0
	v_mov_b32_e32 v63, v0
	s_add_i32 s99, s9, 0
	v_add_u32_e32 v253, s99, v81
	v_add_u32_e32 v252, s99, v83
	ds_read_b128 v[84:87], v252 offset:16384
	ds_read_b128 v[88:91], v253
	ds_read_b128 v[92:95], v253 offset:4096
	ds_read_b128 v[96:99], v252 offset:20480
	s_mov_b64 vcc, -1
	s_branch .Lfws_846

; DEV int stage_next(int s) { return (s == 2 * GS_STAGE) ? 0 : s + GS_STAGE; }
; template <int WAIT0>
; DEV void gk_main(f32x16 (&acc)[2][2], const GTile& t, int s0) {
;     ...
;   for (int kt = 0; kt < nk - 2; ++kt) {
;     GK_DMA(std_, kt + 2);
;     GK_COMPUTE(stc);
;     vm_wait_bar<6>();
;     stc = stage_next(stc); std_ = stage_next(std_);
;   }
.Lfws_846:
.LBB0_846:
	s_add_i32 s10, s2, s3
	s_mov_b32 s98, s10
	s_waitcnt lgkmcnt(0)
	v_add_u32_e32 v101, s99, v82
	v_add_u32_e32 v100, s99, v79
	s_add_i32 s10, s9, 0xc000
	s_cmp_lg_u32 s9, 0x18000
	s_cselect_b32 s9, s10, 0
	s_add_i32 s10, s3, 0xc000
	s_cmp_lg_u32 s3, 0x18000
	s_cselect_b32 s3, s10, 0
	s_add_i32 s8, s8, -1
	ds_read_b128 v[236:239], v101 offset:16384
	ds_read_b128 v[240:243], v100
	ds_read_b128 v[244:247], v100 offset:4096
	ds_read_b128 v[248:251], v101 offset:20480
	v_mfma_f32_32x32x16_bf16 v[48:63], v[84:87], v[88:91], v[48:63]
	v_mfma_f32_32x32x16_bf16 v[32:47], v[84:87], v[92:95], v[32:47]
	s_mov_b32 m0, s98
	v_lshl_add_u64 v[254:255], v[74:75], 0, v[120:121]
	global_load_lds_dwordx4 v[254:255], off
	v_lshl_add_u64 v[74:75], v[74:75], 0, s[94:95]
	v_mfma_f32_32x32x16_bf16 v[16:31], v[96:99], v[88:91], v[16:31]
	v_mfma_f32_32x32x16_bf16 v[0:15], v[96:99], v[92:95], v[0:15]
	s_add_i32 m0, s98, 0x2000
	v_lshl_add_u64 v[254:255], v[72:73], 0, v[120:121]
	global_load_lds_dwordx4 v[254:255], off
	v_lshl_add_u64 v[72:73], v[72:73], 0, s[94:95]
	v_add_u32_e32 v101, s99, v80
	v_add_u32_e32 v100, s99, v77
	s_waitcnt lgkmcnt(0)
	ds_read_b128 v[84:87], v101 offset:16384
	ds_read_b128 v[88:91], v100
	ds_read_b128 v[92:95], v100 offset:4096
	ds_read_b128 v[96:99], v101 offset:20480
	v_mfma_f32_32x32x16_bf16 v[48:63], v[236:239], v[240:243], v[48:63]
	v_mfma_f32_32x32x16_bf16 v[32:47], v[236:239], v[244:247], v[32:47]
	s_add_i32 m0, s98, 0x4000
	v_lshl_add_u64 v[254:255], v[70:71], 0, v[120:121]
	global_load_lds_dwordx4 v[254:255], off
	v_lshl_add_u64 v[70:71], v[70:71], 0, s[94:95]
	v_mfma_f32_32x32x16_bf16 v[16:31], v[248:251], v[240:243], v[16:31]
	v_mfma_f32_32x32x16_bf16 v[0:15], v[248:251], v[244:247], v[0:15]
	s_add_i32 m0, s98, 0x6000
	v_lshl_add_u64 v[254:255], v[68:69], 0, v[120:121]
	global_load_lds_dwordx4 v[254:255], off
	v_lshl_add_u64 v[68:69], v[68:69], 0, s[94:95]
	v_add_u32_e32 v101, s99, v78
	v_add_u32_e32 v100, s99, v76
	s_waitcnt lgkmcnt(0)
	ds_read_b128 v[236:239], v101 offset:16384
	ds_read_b128 v[240:243], v100
	ds_read_b128 v[244:247], v100 offset:4096
	ds_read_b128 v[248:251], v101 offset:20480
	v_mfma_f32_32x32x16_bf16 v[48:63], v[84:87], v[88:91], v[48:63]
	v_mfma_f32_32x32x16_bf16 v[32:47], v[84:87], v[92:95], v[32:47]
	s_add_i32 m0, s98, 0x8000
	v_lshl_add_u64 v[254:255], v[66:67], 0, v[120:121]
	global_load_lds_dwordx4 v[254:255], off
	v_lshl_add_u64 v[66:67], v[66:67], 0, s[94:95]
	v_mfma_f32_32x32x16_bf16 v[16:31], v[96:99], v[88:91], v[16:31]
	v_mfma_f32_32x32x16_bf16 v[0:15], v[96:99], v[92:95], v[0:15]
	s_add_i32 m0, s98, 0xa000
	v_lshl_add_u64 v[254:255], v[64:65], 0, v[120:121]
	global_load_lds_dwordx4 v[254:255], off
	v_lshl_add_u64 v[64:65], v[64:65], 0, s[94:95]
	s_cbranch_vccnz .Lfw_846
	s_waitcnt vmcnt(6) lgkmcnt(0)
	s_barrier
; DEV int stage_next(int s) { return (s == 2 * GS_STAGE) ? 0 : s + GS_STAGE; }
; template <int WAIT0>
; DEV void gk_main(f32x16 (&acc)[2][2], const GTile& t, int s0) {
;     ...
;   for (int kt = 0; kt < nk - 2; ++kt) {
;     GK_DMA(std_, kt + 2);
;     GK_COMPUTE(stc);
;     vm_wait_bar<6>();
;     stc = stage_next(stc); std_ = stage_next(std_);
;   }
;   GK_COMPUTE(stc);
;   vm_wait_bar<0>();
;   stc = stage_next(stc);
;   GK_COMPUTE(stc);
;   vm_wait_bar<0>();
.Lfwb_846:
	s_waitcnt lgkmcnt(0)
	s_add_i32 s99, s9, 0
	v_add_u32_e32 v253, s99, v81
	v_add_u32_e32 v252, s99, v83
	ds_read_b128 v[84:87], v252 offset:16384
	ds_read_b128 v[88:91], v253
	ds_read_b128 v[92:95], v253 offset:4096
	ds_read_b128 v[96:99], v252 offset:20480
	v_mfma_f32_32x32x16_bf16 v[48:63], v[236:239], v[240:243], v[48:63]
	v_mfma_f32_32x32x16_bf16 v[32:47], v[236:239], v[244:247], v[32:47]
	v_mfma_f32_32x32x16_bf16 v[16:31], v[248:251], v[240:243], v[16:31]
	v_mfma_f32_32x32x16_bf16 v[0:15], v[248:251], v[244:247], v[0:15]
	s_cmp_lg_u32 s8, 0
	s_cbranch_scc1 .LBB0_846
	s_waitcnt lgkmcnt(0)
	s_add_i32 s2, s9, 0
	v_add_u32_e32 v84, s2, v83
	ds_read_b128 v[64:67], v84 offset:16384
	v_add_u32_e32 v72, s2, v81
	ds_read_b128 v[68:71], v72
	ds_read_b128 v[72:75], v72 offset:4096
	ds_read_b128 v[84:87], v84 offset:20480
	s_waitcnt lgkmcnt(0)
	v_mfma_f32_32x32x16_bf16 v[16:31], v[84:87], v[68:71], v[16:31]
	v_mfma_f32_32x32x16_bf16 v[0:15], v[84:87], v[72:75], v[0:15]
	v_add_u32_e32 v84, s2, v82
	v_mfma_f32_32x32x16_bf16 v[48:63], v[64:67], v[68:71], v[48:63]
	v_mfma_f32_32x32x16_bf16 v[32:47], v[64:67], v[72:75], v[32:47]
	ds_read_b128 v[64:67], v84 offset:16384
	v_add_u32_e32 v72, s2, v79
	ds_read_b128 v[68:71], v72
	ds_read_b128 v[72:75], v72 offset:4096
	ds_read_b128 v[84:87], v84 offset:20480
	s_waitcnt lgkmcnt(0)
	v_mfma_f32_32x32x16_bf16 v[16:31], v[84:87], v[68:71], v[16:31]
	v_mfma_f32_32x32x16_bf16 v[0:15], v[84:87], v[72:75], v[0:15]
	v_add_u32_e32 v84, s2, v80
	v_mfma_f32_32x32x16_bf16 v[48:63], v[64:67], v[68:71], v[48:63]
	v_mfma_f32_32x32x16_bf16 v[32:47], v[64:67], v[72:75], v[32:47]
	ds_read_b128 v[64:67], v84 offset:16384
	v_add_u32_e32 v72, s2, v77
	ds_read_b128 v[68:71], v72
	ds_read_b128 v[72:75], v72 offset:4096
	ds_read_b128 v[84:87], v84 offset:20480
	s_waitcnt lgkmcnt(0)
	v_mfma_f32_32x32x16_bf16 v[16:31], v[84:87], v[68:71], v[16:31]
	v_mfma_f32_32x32x16_bf16 v[0:15], v[84:87], v[72:75], v[0:15]
	v_add_u32_e32 v84, s2, v78
	v_mfma_f32_32x32x16_bf16 v[48:63], v[64:67], v[68:71], v[48:63]
	v_mfma_f32_32x32x16_bf16 v[32:47], v[64:67], v[72:75], v[32:47]
	ds_read_b128 v[64:67], v84 offset:16384
	v_add_u32_e32 v72, s2, v76
	s_add_i32 s2, s9, 0xc000
	ds_read_b128 v[68:71], v72
	ds_read_b128 v[72:75], v72 offset:4096
	ds_read_b128 v[84:87], v84 offset:20480
	s_cmp_lg_u32 s9, 0x18000
	s_cselect_b32 s2, s2, 0
	s_add_i32 s2, s2, 0
	s_waitcnt vmcnt(0) lgkmcnt(0)
	s_barrier
	v_add_u32_e32 v83, s2, v83
	s_waitcnt lgkmcnt(0)
	v_mfma_f32_32x32x16_bf16 v[48:63], v[64:67], v[68:71], v[48:63]
	v_mfma_f32_32x32x16_bf16 v[32:47], v[64:67], v[72:75], v[32:47]
	ds_read_b128 v[64:67], v83 offset:16384
	v_mfma_f32_32x32x16_bf16 v[16:31], v[84:87], v[68:71], v[16:31]
	v_mfma_f32_32x32x16_bf16 v[0:15], v[84:87], v[72:75], v[0:15]
	v_add_u32_e32 v72, s2, v81
	ds_read_b128 v[68:71], v72
	ds_read_b128 v[72:75], v72 offset:4096
	ds_read_b128 v[84:87], v83 offset:20480
	v_add_u32_e32 v81, s2, v82
	s_waitcnt lgkmcnt(0)
	v_mfma_f32_32x32x16_bf16 v[48:63], v[64:67], v[68:71], v[48:63]
	v_mfma_f32_32x32x16_bf16 v[32:47], v[64:67], v[72:75], v[32:47]
	ds_read_b128 v[64:67], v81 offset:16384
	v_mfma_f32_32x32x16_bf16 v[16:31], v[84:87], v[68:71], v[16:31]
	v_mfma_f32_32x32x16_bf16 v[0:15], v[84:87], v[72:75], v[0:15]
	v_add_u32_e32 v72, s2, v79
	ds_read_b128 v[68:71], v72
	ds_read_b128 v[72:75], v72 offset:4096
	ds_read_b128 v[82:85], v81 offset:20480
	v_add_u32_e32 v79, s2, v80
	s_waitcnt lgkmcnt(0)
	v_mfma_f32_32x32x16_bf16 v[48:63], v[64:67], v[68:71], v[48:63]
	v_mfma_f32_32x32x16_bf16 v[32:47], v[64:67], v[72:75], v[32:47]
	ds_read_b128 v[64:67], v79 offset:16384
	v_mfma_f32_32x32x16_bf16 v[16:31], v[82:85], v[68:71], v[16:31]
	v_mfma_f32_32x32x16_bf16 v[0:15], v[82:85], v[72:75], v[0:15]
	v_add_u32_e32 v72, s2, v77
	ds_read_b128 v[68:71], v72
	ds_read_b128 v[72:75], v72 offset:4096
	ds_read_b128 v[80:83], v79 offset:20480
	v_add_u32_e32 v77, s2, v78
	s_waitcnt lgkmcnt(0)
	v_mfma_f32_32x32x16_bf16 v[48:63], v[64:67], v[68:71], v[48:63]
	v_mfma_f32_32x32x16_bf16 v[32:47], v[64:67], v[72:75], v[32:47]
	ds_read_b128 v[64:67], v77 offset:16384
	v_mfma_f32_32x32x16_bf16 v[16:31], v[80:83], v[68:71], v[16:31]
	v_mfma_f32_32x32x16_bf16 v[0:15], v[80:83], v[72:75], v[0:15]
	v_add_u32_e32 v72, s2, v76
	ds_read_b128 v[68:71], v72
	ds_read_b128 v[72:75], v72 offset:4096
	ds_read_b128 v[76:79], v77 offset:20480
	s_waitcnt vmcnt(0) lgkmcnt(0)
	s_barrier
	s_waitcnt lgkmcnt(0)
	v_mfma_f32_32x32x16_bf16 v[48:63], v[64:67], v[68:71], v[48:63]
	v_mfma_f32_32x32x16_bf16 v[32:47], v[64:67], v[72:75], v[32:47]
	v_mfma_f32_32x32x16_bf16 v[16:31], v[76:79], v[68:71], v[16:31]
	v_mfma_f32_32x32x16_bf16 v[0:15], v[76:79], v[72:75], v[0:15]
